# GEMM K-loops without per-phase s_setprio flips, placeholder s_nops deleted (80 fewer issue slots per K-pair set)
# speedup vs baseline: 1.0089x; 1.0089x over previous
; #define G8_STAGE(bufoff, gbase) do { _Pragma("unroll") for (int _i = 0; _i < 2; ++_i) \
;     __builtin_amdgcn_global_load_lds((const unsigned*)((const char*)(gbase) + voffA[_i]), (LAS unsigned*)(lds + (bufoff) + ldsw + _i * 8192), 16, 0, 0); } while (0)
; #define G8_LDA(dst, b, h) do { _Pragma("unroll") for (int m = 0; m < 4; ++m) _Pragma("unroll") for (int k = 0; k < 2; ++k) dst[m][k] = *(const LAS h16x8*)(lds + G8_SA(b, h) + aoff + m * 2048 + k * 1024); } while (0)
; #define G8_LDB(dst, b, h) do { _Pragma("unroll") for (int n = 0; n < 2; ++n) _Pragma("unroll") for (int k = 0; k < 2; ++k) dst[n][k] = *(const LAS h16x8*)(lds + G8_SB(b, h) + boff + n * 2048 + k * 1024); } while (0)
; #define G8_MMA(ai, bj, At, Bt_) do { __builtin_amdgcn_s_setprio(1); _Pragma("unroll") for (int m = 0; m < 4; ++m) _Pragma("unroll") for (int n = 0; n < 2; ++n) _Pragma("unroll") for (int k = 0; k < 2; ++k) \
;     acc[ai][bj][m][n] = __builtin_amdgcn_mfma_f32_16x16x32_f16(Bt_[n][k], At[m][k], acc[ai][bj][m][n], 0, 0, 0); __builtin_amdgcn_s_setprio(0); } while (0)
; #define G8_WAIT_V(n) asm volatile("s_waitcnt vmcnt(" #n ")" ::: "memory")
; #define G8_WAIT_L(n) asm volatile("s_waitcnt lgkmcnt(" #n ")" ::: "memory")
; #define G8_BAR __builtin_amdgcn_s_barrier()
; template <class Epi>
; __device__ __forceinline__ void gemm_phase(LAS unsigned char* lds, const h16* A, const h16* Bt, int K, const Order& S, const Epi& E) {
;     ...
;       const bool last = (t == nt - 2);
;       const char* a1 = cA + (size_t)(t + 1) * kstep;
;       const char* a2 = last ? nA : cA + (size_t)(t + 2) * kstep;
;       const char* b2 = last ? nB : cB + (size_t)(t + 2) * kstep;
;       const char* a3 = a2 + kstep;
;       const char* b3 = b2 + kstep;
;       if (Epi::MID_T >= 0 && t == Epi::MID_T) E.mid(acc, ui, wr, fr);
;       G8_LDB(B0, 0, 0); G8_SCHED; G8_LDA(At, 0, 0); G8_STAGE(G8_SA(1, 1), a1 + hstep);
;       G8_WAIT_L(8); G8_BAR; G8_WAIT_L(0); G8_MMA(0, 0, At, B0); G8_BAR; G8_SCHED;
;       G8_LDB(B1, 0, 1); G8_STAGE(G8_SB(0, 0), b2);
;       G8_BAR; G8_WAIT_L(0); G8_MMA(0, 1, At, B1); G8_BAR;
;       G8_LDA(At, 0, 1); G8_STAGE(G8_SA(0, 0), a2);
;       G8_BAR; G8_WAIT_L(0); G8_MMA(1, 0, At, B0); G8_BAR; G8_SCHED;
;       G8_STAGE(G8_SB(0, 1), b2 + hstep);
;       G8_WAIT_V(6); G8_BAR; G8_MMA(1, 1, At, B1); G8_BAR;
;       G8_LDB(B0, 1, 0); G8_SCHED; G8_LDA(At, 1, 0); G8_STAGE(G8_SA(0, 1), a2 + hstep);
.LBB0_195:
	s_add_u32 s12, s10, 0xfffc0080
	s_addc_u32 s13, s11, -1
	s_cmp_eq_u32 s54, 12
	s_cselect_b32 s15, s19, s13
	s_cselect_b32 s14, s25, s12
	s_cselect_b32 s13, s17, s53
	s_cselect_b32 s12, s26, s27
	s_mov_b32 m0, s50
	v_lshl_add_u64 v[140:141], s[10:11], 0, v[136:137]
	ds_read_b128 v[202:205], v159
	ds_read_b128 v[206:209], v159 offset:1024
	ds_read_b128 v[210:213], v159 offset:2048
	ds_read_b128 v[214:217], v159 offset:3072
	ds_read_b128 v[218:221], v159 offset:4096
	ds_read_b128 v[222:225], v159 offset:5120
	ds_read_b128 v[226:229], v159 offset:6144
	ds_read_b128 v[230:233], v159 offset:7168
	global_load_lds_dwordx4 v[140:141], off
	v_lshl_add_u64 v[140:141], s[10:11], 0, v[138:139]
	s_mov_b32 m0, s51
	s_nop 0
	global_load_lds_dwordx4 v[140:141], off
	s_waitcnt lgkmcnt(8)
	s_barrier
	s_waitcnt lgkmcnt(0)
	s_waitcnt lgkmcnt(0)
	v_mfma_f32_16x16x32_f16 v[126:129], v[152:155], v[202:205], v[126:129]
	v_mfma_f32_16x16x32_f16 v[122:125], v[182:185], v[202:205], v[122:125]
	v_mfma_f32_16x16x32_f16 v[110:113], v[152:155], v[210:213], v[110:113]
	v_mfma_f32_16x16x32_f16 v[106:109], v[182:185], v[210:213], v[106:109]
	v_mfma_f32_16x16x32_f16 v[94:97], v[152:155], v[218:221], v[94:97]
	v_mfma_f32_16x16x32_f16 v[90:93], v[182:185], v[218:221], v[90:93]
	v_mfma_f32_16x16x32_f16 v[78:81], v[152:155], v[226:229], v[78:81]
	v_mfma_f32_16x16x32_f16 v[74:77], v[182:185], v[226:229], v[74:77]
	v_mfma_f32_16x16x32_f16 v[126:129], v[178:181], v[206:209], v[126:129]
	v_mfma_f32_16x16x32_f16 v[122:125], v[186:189], v[206:209], v[122:125]
	v_mfma_f32_16x16x32_f16 v[110:113], v[178:181], v[214:217], v[110:113]
	v_mfma_f32_16x16x32_f16 v[106:109], v[186:189], v[214:217], v[106:109]
	v_mfma_f32_16x16x32_f16 v[94:97], v[178:181], v[222:225], v[94:97]
	v_mfma_f32_16x16x32_f16 v[90:93], v[186:189], v[222:225], v[90:93]
	v_mfma_f32_16x16x32_f16 v[78:81], v[178:181], v[230:233], v[78:81]
	v_mfma_f32_16x16x32_f16 v[74:77], v[186:189], v[230:233], v[74:77]
	s_barrier
	s_mov_b32 m0, s36
	v_lshl_add_u64 v[140:141], s[12:13], 0, v[132:133]
	ds_read_b128 v[234:237], v165
	ds_read_b128 v[238:241], v166
	ds_read_b128 v[242:245], v167
	ds_read_b128 v[246:249], v168
	global_load_lds_dwordx4 v[140:141], off
	v_lshl_add_u64 v[156:157], s[12:13], 0, v[130:131]
	s_mov_b32 m0, s37
	s_nop 0
	global_load_lds_dwordx4 v[156:157], off
	s_barrier
	s_waitcnt lgkmcnt(0)
	s_waitcnt lgkmcnt(0)
	v_mfma_f32_16x16x32_f16 v[118:121], v[234:237], v[202:205], v[118:121]
	v_mfma_f32_16x16x32_f16 v[114:117], v[242:245], v[202:205], v[114:117]
	v_mfma_f32_16x16x32_f16 v[102:105], v[234:237], v[210:213], v[102:105]
	v_mfma_f32_16x16x32_f16 v[98:101], v[242:245], v[210:213], v[98:101]
	v_mfma_f32_16x16x32_f16 v[86:89], v[234:237], v[218:221], v[86:89]
	v_mfma_f32_16x16x32_f16 v[82:85], v[242:245], v[218:221], v[82:85]
	v_mfma_f32_16x16x32_f16 v[70:73], v[234:237], v[226:229], v[70:73]
	v_mfma_f32_16x16x32_f16 v[66:69], v[242:245], v[226:229], v[66:69]
	v_mfma_f32_16x16x32_f16 v[118:121], v[238:241], v[206:209], v[118:121]
	v_mfma_f32_16x16x32_f16 v[114:117], v[246:249], v[206:209], v[114:117]
	v_mfma_f32_16x16x32_f16 v[102:105], v[238:241], v[214:217], v[102:105]
	v_mfma_f32_16x16x32_f16 v[98:101], v[246:249], v[214:217], v[98:101]
	v_mfma_f32_16x16x32_f16 v[86:89], v[238:241], v[222:225], v[86:89]
	v_mfma_f32_16x16x32_f16 v[82:85], v[246:249], v[222:225], v[82:85]
	v_mfma_f32_16x16x32_f16 v[70:73], v[238:241], v[230:233], v[70:73]
	v_mfma_f32_16x16x32_f16 v[66:69], v[246:249], v[230:233], v[66:69]
	s_mov_b32 m0, s35
	v_lshl_add_u64 v[250:251], s[14:15], 0, v[132:133]
	s_barrier
	ds_read_b128 v[202:205], v159 offset:16384
	ds_read_b128 v[206:209], v159 offset:17408
	ds_read_b128 v[210:213], v159 offset:18432
	ds_read_b128 v[214:217], v159 offset:19456
	ds_read_b128 v[218:221], v159 offset:20480
	ds_read_b128 v[222:225], v159 offset:21504
	ds_read_b128 v[226:229], v159 offset:22528
	ds_read_b128 v[230:233], v159 offset:23552
	global_load_lds_dwordx4 v[250:251], off
	v_lshl_add_u64 v[252:253], s[14:15], 0, v[130:131]
	s_mov_b32 m0, s38
	s_nop 0
	global_load_lds_dwordx4 v[252:253], off
	s_waitcnt vmcnt(10)
	s_barrier
	s_waitcnt lgkmcnt(0)
	s_waitcnt lgkmcnt(0)
	v_mfma_f32_16x16x32_f16 v[62:65], v[152:155], v[202:205], v[62:65]
	v_mfma_f32_16x16x32_f16 v[58:61], v[182:185], v[202:205], v[58:61]
	v_mfma_f32_16x16x32_f16 v[46:49], v[152:155], v[210:213], v[46:49]
	v_mfma_f32_16x16x32_f16 v[42:45], v[182:185], v[210:213], v[42:45]
	v_mfma_f32_16x16x32_f16 v[30:33], v[152:155], v[218:221], v[30:33]
	v_mfma_f32_16x16x32_f16 v[26:29], v[182:185], v[218:221], v[26:29]
	v_mfma_f32_16x16x32_f16 v[14:17], v[152:155], v[226:229], v[14:17]
	v_mfma_f32_16x16x32_f16 v[10:13], v[182:185], v[226:229], v[10:13]
	v_mfma_f32_16x16x32_f16 v[62:65], v[178:181], v[206:209], v[62:65]
	v_mfma_f32_16x16x32_f16 v[58:61], v[186:189], v[206:209], v[58:61]
	v_mfma_f32_16x16x32_f16 v[46:49], v[178:181], v[214:217], v[46:49]
	v_mfma_f32_16x16x32_f16 v[42:45], v[186:189], v[214:217], v[42:45]
	v_mfma_f32_16x16x32_f16 v[30:33], v[178:181], v[222:225], v[30:33]
	v_mfma_f32_16x16x32_f16 v[26:29], v[186:189], v[222:225], v[26:29]
	v_mfma_f32_16x16x32_f16 v[14:17], v[178:181], v[230:233], v[14:17]
	v_mfma_f32_16x16x32_f16 v[10:13], v[186:189], v[230:233], v[10:13]
	s_barrier
	s_add_u32 s56, s12, 0x40000
	s_addc_u32 s57, s13, 0
	s_mov_b32 m0, s39
	v_lshl_add_u64 v[152:153], s[56:57], 0, v[132:133]
	global_load_lds_dwordx4 v[152:153], off
	v_lshl_add_u64 v[152:153], s[56:57], 0, v[130:131]
	s_mov_b32 m0, s40
	s_nop 0
	global_load_lds_dwordx4 v[152:153], off
	ds_read_b128 v[152:155], v169
	ds_read_b128 v[178:181], v170
	ds_read_b128 v[182:185], v171
	ds_read_b128 v[186:189], v172
	s_waitcnt vmcnt(6)
	s_barrier
; #define G8_STAGE(bufoff, gbase) do { _Pragma("unroll") for (int _i = 0; _i < 2; ++_i) \
;     __builtin_amdgcn_global_load_lds((const unsigned*)((const char*)(gbase) + voffA[_i]), (LAS unsigned*)(lds + (bufoff) + ldsw + _i * 8192), 16, 0, 0); } while (0)
; #define G8_LDA(dst, b, h) do { _Pragma("unroll") for (int m = 0; m < 4; ++m) _Pragma("unroll") for (int k = 0; k < 2; ++k) dst[m][k] = *(const LAS h16x8*)(lds + G8_SA(b, h) + aoff + m * 2048 + k * 1024); } while (0)
; #define G8_LDB(dst, b, h) do { _Pragma("unroll") for (int n = 0; n < 2; ++n) _Pragma("unroll") for (int k = 0; k < 2; ++k) dst[n][k] = *(const LAS h16x8*)(lds + G8_SB(b, h) + boff + n * 2048 + k * 1024); } while (0)
; #define G8_MMA(ai, bj, At, Bt_) do { __builtin_amdgcn_s_setprio(1); _Pragma("unroll") for (int m = 0; m < 4; ++m) _Pragma("unroll") for (int n = 0; n < 2; ++n) _Pragma("unroll") for (int k = 0; k < 2; ++k) \
;     acc[ai][bj][m][n] = __builtin_amdgcn_mfma_f32_16x16x32_f16(Bt_[n][k], At[m][k], acc[ai][bj][m][n], 0, 0, 0); __builtin_amdgcn_s_setprio(0); } while (0)
; #define G8_WAIT_V(n) asm volatile("s_waitcnt vmcnt(" #n ")" ::: "memory")
; #define G8_WAIT_L(n) asm volatile("s_waitcnt lgkmcnt(" #n ")" ::: "memory")
; #define G8_BAR __builtin_amdgcn_s_barrier()
; #define G8_SCHED __builtin_amdgcn_sched_barrier(0)
; template <class Epi>
; __device__ __forceinline__ void gemm_phase(LAS unsigned char* lds, const h16* A, const h16* Bt, int K, const Order& S, const Epi& E) {
;     ...
;       G8_WAIT_V(6); G8_BAR; G8_MMA(1, 1, At, B1); G8_BAR;
;       G8_LDB(B0, 1, 0); G8_SCHED; G8_LDA(At, 1, 0); G8_STAGE(G8_SA(0, 1), a2 + hstep);
;       G8_WAIT_L(8); G8_BAR; G8_WAIT_L(0); G8_MMA(0, 0, At, B0); G8_BAR; G8_SCHED;
;       G8_LDB(B1, 1, 1); G8_STAGE(G8_SB(1, 0), b3);
;       G8_BAR; G8_WAIT_L(0); G8_MMA(0, 1, At, B1); G8_BAR;
	v_mfma_f32_16x16x32_f16 v[54:57], v[234:237], v[202:205], v[54:57]
	v_mfma_f32_16x16x32_f16 v[50:53], v[242:245], v[202:205], v[50:53]
	v_mfma_f32_16x16x32_f16 v[38:41], v[234:237], v[210:213], v[38:41]
	v_mfma_f32_16x16x32_f16 v[34:37], v[242:245], v[210:213], v[34:37]
	v_mfma_f32_16x16x32_f16 v[22:25], v[234:237], v[218:221], v[22:25]
	v_mfma_f32_16x16x32_f16 v[18:21], v[242:245], v[218:221], v[18:21]
	v_mfma_f32_16x16x32_f16 v[6:9], v[234:237], v[226:229], v[6:9]
	v_mfma_f32_16x16x32_f16 v[2:5], v[242:245], v[226:229], v[2:5]
	v_mfma_f32_16x16x32_f16 v[54:57], v[238:241], v[206:209], v[54:57]
	v_mfma_f32_16x16x32_f16 v[50:53], v[246:249], v[206:209], v[50:53]
	v_mfma_f32_16x16x32_f16 v[38:41], v[238:241], v[214:217], v[38:41]
	v_mfma_f32_16x16x32_f16 v[34:37], v[246:249], v[214:217], v[34:37]
	v_mfma_f32_16x16x32_f16 v[22:25], v[238:241], v[222:225], v[22:25]
	v_mfma_f32_16x16x32_f16 v[18:21], v[246:249], v[222:225], v[18:21]
	v_mfma_f32_16x16x32_f16 v[6:9], v[238:241], v[230:233], v[6:9]
	v_mfma_f32_16x16x32_f16 v[2:5], v[246:249], v[230:233], v[2:5]
	s_barrier
	s_add_u32 s14, s14, 0x40000
	s_addc_u32 s15, s15, 0
	s_mov_b32 m0, s41
	v_lshl_add_u64 v[234:235], s[14:15], 0, v[132:133]
	ds_read_b128 v[202:205], v159 offset:32768
	ds_read_b128 v[206:209], v159 offset:33792
	ds_read_b128 v[210:213], v159 offset:34816
	ds_read_b128 v[214:217], v159 offset:35840
	ds_read_b128 v[218:221], v159 offset:36864
	ds_read_b128 v[222:225], v159 offset:37888
	ds_read_b128 v[226:229], v159 offset:38912
	ds_read_b128 v[230:233], v159 offset:39936
	global_load_lds_dwordx4 v[234:235], off
	v_lshl_add_u64 v[234:235], s[14:15], 0, v[130:131]
	s_mov_b32 m0, s42
	s_nop 0
	global_load_lds_dwordx4 v[234:235], off
	s_waitcnt lgkmcnt(8)
	s_barrier
	s_waitcnt lgkmcnt(0)
	s_waitcnt lgkmcnt(0)
	v_mfma_f32_16x16x32_f16 v[126:129], v[152:155], v[202:205], v[126:129]
	v_mfma_f32_16x16x32_f16 v[122:125], v[182:185], v[202:205], v[122:125]
	v_mfma_f32_16x16x32_f16 v[110:113], v[152:155], v[210:213], v[110:113]
	v_mfma_f32_16x16x32_f16 v[106:109], v[182:185], v[210:213], v[106:109]
	v_mfma_f32_16x16x32_f16 v[94:97], v[152:155], v[218:221], v[94:97]
	v_mfma_f32_16x16x32_f16 v[90:93], v[182:185], v[218:221], v[90:93]
	v_mfma_f32_16x16x32_f16 v[78:81], v[152:155], v[226:229], v[78:81]
	v_mfma_f32_16x16x32_f16 v[74:77], v[182:185], v[226:229], v[74:77]
	v_mfma_f32_16x16x32_f16 v[126:129], v[178:181], v[206:209], v[126:129]
	v_mfma_f32_16x16x32_f16 v[122:125], v[186:189], v[206:209], v[122:125]
	v_mfma_f32_16x16x32_f16 v[110:113], v[178:181], v[214:217], v[110:113]
	v_mfma_f32_16x16x32_f16 v[106:109], v[186:189], v[214:217], v[106:109]
	v_mfma_f32_16x16x32_f16 v[94:97], v[178:181], v[222:225], v[94:97]
	v_mfma_f32_16x16x32_f16 v[90:93], v[186:189], v[222:225], v[90:93]
	v_mfma_f32_16x16x32_f16 v[78:81], v[178:181], v[230:233], v[78:81]
	v_mfma_f32_16x16x32_f16 v[74:77], v[186:189], v[230:233], v[74:77]
	s_barrier
	s_mov_b32 m0, s44
	v_lshl_add_u64 v[140:141], v[140:141], 0, s[94:95]
	ds_read_b128 v[234:237], v173
	ds_read_b128 v[238:241], v174
	ds_read_b128 v[242:245], v175
	ds_read_b128 v[246:249], v176
	global_load_lds_dwordx4 v[140:141], off
	v_lshl_add_u64 v[140:141], v[156:157], 0, s[94:95]
	s_mov_b32 m0, s45
	s_nop 0
	global_load_lds_dwordx4 v[140:141], off
	s_barrier
	s_waitcnt lgkmcnt(0)
	s_waitcnt lgkmcnt(0)
	v_mfma_f32_16x16x32_f16 v[118:121], v[234:237], v[202:205], v[118:121]
	v_mfma_f32_16x16x32_f16 v[114:117], v[242:245], v[202:205], v[114:117]
	v_mfma_f32_16x16x32_f16 v[102:105], v[234:237], v[210:213], v[102:105]
	v_mfma_f32_16x16x32_f16 v[98:101], v[242:245], v[210:213], v[98:101]
	v_mfma_f32_16x16x32_f16 v[86:89], v[234:237], v[218:221], v[86:89]
	v_mfma_f32_16x16x32_f16 v[82:85], v[242:245], v[218:221], v[82:85]
	v_mfma_f32_16x16x32_f16 v[70:73], v[234:237], v[226:229], v[70:73]
	v_mfma_f32_16x16x32_f16 v[66:69], v[242:245], v[226:229], v[66:69]
	v_mfma_f32_16x16x32_f16 v[118:121], v[238:241], v[206:209], v[118:121]
	v_mfma_f32_16x16x32_f16 v[114:117], v[246:249], v[206:209], v[114:117]
	v_mfma_f32_16x16x32_f16 v[102:105], v[238:241], v[214:217], v[102:105]
	v_mfma_f32_16x16x32_f16 v[98:101], v[246:249], v[214:217], v[98:101]
	v_mfma_f32_16x16x32_f16 v[86:89], v[238:241], v[222:225], v[86:89]
	v_mfma_f32_16x16x32_f16 v[82:85], v[246:249], v[222:225], v[82:85]
	v_mfma_f32_16x16x32_f16 v[70:73], v[238:241], v[230:233], v[70:73]
	v_mfma_f32_16x16x32_f16 v[66:69], v[246:249], v[230:233], v[66:69]
	s_mov_b32 m0, s46
	v_lshl_add_u64 v[140:141], v[250:251], 0, s[94:95]
	s_barrier
; #define G8_STAGE(bufoff, gbase) do { _Pragma("unroll") for (int _i = 0; _i < 2; ++_i) \
;     __builtin_amdgcn_global_load_lds((const unsigned*)((const char*)(gbase) + voffA[_i]), (LAS unsigned*)(lds + (bufoff) + ldsw + _i * 8192), 16, 0, 0); } while (0)
; #define G8_LDA(dst, b, h) do { _Pragma("unroll") for (int m = 0; m < 4; ++m) _Pragma("unroll") for (int k = 0; k < 2; ++k) dst[m][k] = *(const LAS h16x8*)(lds + G8_SA(b, h) + aoff + m * 2048 + k * 1024); } while (0)
; #define G8_MMA(ai, bj, At, Bt_) do { __builtin_amdgcn_s_setprio(1); _Pragma("unroll") for (int m = 0; m < 4; ++m) _Pragma("unroll") for (int n = 0; n < 2; ++n) _Pragma("unroll") for (int k = 0; k < 2; ++k) \
;     acc[ai][bj][m][n] = __builtin_amdgcn_mfma_f32_16x16x32_f16(Bt_[n][k], At[m][k], acc[ai][bj][m][n], 0, 0, 0); __builtin_amdgcn_s_setprio(0); } while (0)
; #define G8_WAIT_V(n) asm volatile("s_waitcnt vmcnt(" #n ")" ::: "memory")
; #define G8_WAIT_L(n) asm volatile("s_waitcnt lgkmcnt(" #n ")" ::: "memory")
; #define G8_BAR __builtin_amdgcn_s_barrier()
; #define G8_SCHED __builtin_amdgcn_sched_barrier(0)
; template <class Epi>
; __device__ __forceinline__ void gemm_phase(LAS unsigned char* lds, const h16* A, const h16* Bt, int K, const Order& S, const Epi& E) {
;     ...
;       G8_LDA(At, 1, 1); G8_STAGE(G8_SA(1, 0), a3);
;       G8_BAR; G8_WAIT_L(0); G8_MMA(1, 0, At, B0); G8_BAR; G8_SCHED;
;       G8_STAGE(G8_SB(1, 1), b3 + hstep);
;       G8_WAIT_V(6); G8_BAR; G8_MMA(1, 1, At, B1); G8_BAR;
;     }
;   __device__ __forceinline__ void operator()(const f32x4 (&acc)[2][2][4][2], const g8::Unit& u, int ui, int wr, int wc, int fr, int fq) const {
;     const int hs = u.pn * 4 + wc;
;     int gi = -1;
;     if (hs < 4) gi = 0; else if (hs < 6) gi = 1; else if (hs >= 16 && hs < 20) gi = 2; else if (hs == 22) gi = 4; else if (hs == 24) gi = 5;
	ds_read_b128 v[202:205], v159 offset:49152
	ds_read_b128 v[206:209], v159 offset:50176
	ds_read_b128 v[210:213], v159 offset:51200
	ds_read_b128 v[214:217], v159 offset:52224
	ds_read_b128 v[218:221], v159 offset:53248
	ds_read_b128 v[222:225], v159 offset:54272
	ds_read_b128 v[226:229], v159 offset:55296
	ds_read_b128 v[230:233], v159 offset:56320
	global_load_lds_dwordx4 v[140:141], off
	v_lshl_add_u64 v[140:141], v[252:253], 0, s[94:95]
	s_mov_b32 m0, s47
	s_nop 0
	global_load_lds_dwordx4 v[140:141], off
	s_waitcnt vmcnt(10)
	s_barrier
	s_waitcnt lgkmcnt(0)
	s_waitcnt lgkmcnt(0)
	v_mfma_f32_16x16x32_f16 v[62:65], v[152:155], v[202:205], v[62:65]
	v_mfma_f32_16x16x32_f16 v[58:61], v[182:185], v[202:205], v[58:61]
	v_mfma_f32_16x16x32_f16 v[46:49], v[152:155], v[210:213], v[46:49]
	v_mfma_f32_16x16x32_f16 v[42:45], v[182:185], v[210:213], v[42:45]
	v_mfma_f32_16x16x32_f16 v[30:33], v[152:155], v[218:221], v[30:33]
	v_mfma_f32_16x16x32_f16 v[26:29], v[182:185], v[218:221], v[26:29]
	v_mfma_f32_16x16x32_f16 v[14:17], v[152:155], v[226:229], v[14:17]
	v_mfma_f32_16x16x32_f16 v[10:13], v[182:185], v[226:229], v[10:13]
	v_mfma_f32_16x16x32_f16 v[62:65], v[178:181], v[206:209], v[62:65]
	v_mfma_f32_16x16x32_f16 v[58:61], v[186:189], v[206:209], v[58:61]
	v_mfma_f32_16x16x32_f16 v[46:49], v[178:181], v[214:217], v[46:49]
	v_mfma_f32_16x16x32_f16 v[42:45], v[186:189], v[214:217], v[42:45]
	v_mfma_f32_16x16x32_f16 v[30:33], v[178:181], v[222:225], v[30:33]
	v_mfma_f32_16x16x32_f16 v[26:29], v[186:189], v[222:225], v[26:29]
	v_mfma_f32_16x16x32_f16 v[14:17], v[178:181], v[230:233], v[14:17]
	v_mfma_f32_16x16x32_f16 v[10:13], v[186:189], v[230:233], v[10:13]
	s_barrier
	s_add_u32 s12, s12, 0x40080
	s_addc_u32 s13, s13, 0
	s_mov_b32 m0, s48
	v_lshl_add_u64 v[140:141], s[12:13], 0, v[132:133]
	global_load_lds_dwordx4 v[140:141], off
	v_lshl_add_u64 v[140:141], s[12:13], 0, v[130:131]
	s_mov_b32 m0, s49
	s_nop 0
	global_load_lds_dwordx4 v[140:141], off
	ds_read_b128 v[152:155], v161
	ds_read_b128 v[178:181], v162
	ds_read_b128 v[182:185], v163
	ds_read_b128 v[186:189], v164
	s_waitcnt vmcnt(6)
	s_barrier
	v_mfma_f32_16x16x32_f16 v[54:57], v[234:237], v[202:205], v[54:57]
	v_mfma_f32_16x16x32_f16 v[50:53], v[242:245], v[202:205], v[50:53]
	v_mfma_f32_16x16x32_f16 v[38:41], v[234:237], v[210:213], v[38:41]
	v_mfma_f32_16x16x32_f16 v[34:37], v[242:245], v[210:213], v[34:37]
	v_mfma_f32_16x16x32_f16 v[22:25], v[234:237], v[218:221], v[22:25]
	v_mfma_f32_16x16x32_f16 v[18:21], v[242:245], v[218:221], v[18:21]
	v_mfma_f32_16x16x32_f16 v[6:9], v[234:237], v[226:229], v[6:9]
	v_mfma_f32_16x16x32_f16 v[2:5], v[242:245], v[226:229], v[2:5]
	v_mfma_f32_16x16x32_f16 v[54:57], v[238:241], v[206:209], v[54:57]
	v_mfma_f32_16x16x32_f16 v[50:53], v[246:249], v[206:209], v[50:53]
	v_mfma_f32_16x16x32_f16 v[38:41], v[238:241], v[214:217], v[38:41]
	v_mfma_f32_16x16x32_f16 v[34:37], v[246:249], v[214:217], v[34:37]
	v_mfma_f32_16x16x32_f16 v[22:25], v[238:241], v[222:225], v[22:25]
	v_mfma_f32_16x16x32_f16 v[18:21], v[246:249], v[222:225], v[18:21]
	v_mfma_f32_16x16x32_f16 v[6:9], v[238:241], v[230:233], v[6:9]
	v_mfma_f32_16x16x32_f16 v[2:5], v[246:249], v[230:233], v[2:5]
	s_add_i32 s54, s54, 2
	s_add_u32 s10, s10, 0x100
	s_addc_u32 s11, s11, 0
	s_add_u32 s27, s27, 0x100
	s_addc_u32 s53, s53, 0
	s_cmp_gt_u32 s54, 13
	s_barrier
	s_cbranch_scc0 .LBB0_195
	s_waitcnt lgkmcnt(0)
	s_lshl_b32 s10, s24, 2
	s_or_b32 s19, s10, s43
	s_cmp_lt_i32 s19, 4
	s_cbranch_scc1 .LBB0_203
	s_cmp_lt_u32 s19, 6
	s_cbranch_scc1 .LBB0_204
	s_cmp_eq_u32 s24, 4
	s_cbranch_scc1 .LBB0_205
	s_cmp_lt_i32 s19, 24
	s_cbranch_scc1 .LBB0_206
	s_cmp_eq_u32 s19, 24
	s_mov_b64 s[10:11], -1
	s_cbranch_scc0 .LBB0_202
	s_mov_b64 s[10:11], 0

; #define G8_STAGE(bufoff, gbase) do { _Pragma("unroll") for (int _i = 0; _i < 2; ++_i) \
;     __builtin_amdgcn_global_load_lds((const unsigned*)((const char*)(gbase) + voffA[_i]), (LAS unsigned*)(lds + (bufoff) + ldsw + _i * 8192), 16, 0, 0); } while (0)
; #define G8_LDA(dst, b, h) do { _Pragma("unroll") for (int m = 0; m < 4; ++m) _Pragma("unroll") for (int k = 0; k < 2; ++k) dst[m][k] = *(const LAS h16x8*)(lds + G8_SA(b, h) + aoff + m * 2048 + k * 1024); } while (0)
; #define G8_LDB(dst, b, h) do { _Pragma("unroll") for (int n = 0; n < 2; ++n) _Pragma("unroll") for (int k = 0; k < 2; ++k) dst[n][k] = *(const LAS h16x8*)(lds + G8_SB(b, h) + boff + n * 2048 + k * 1024); } while (0)
; #define G8_MMA(ai, bj, At, Bt_) do { __builtin_amdgcn_s_setprio(1); _Pragma("unroll") for (int m = 0; m < 4; ++m) _Pragma("unroll") for (int n = 0; n < 2; ++n) _Pragma("unroll") for (int k = 0; k < 2; ++k) \
;     acc[ai][bj][m][n] = __builtin_amdgcn_mfma_f32_16x16x32_f16(Bt_[n][k], At[m][k], acc[ai][bj][m][n], 0, 0, 0); __builtin_amdgcn_s_setprio(0); } while (0)
; #define G8_WAIT_L(n) asm volatile("s_waitcnt lgkmcnt(" #n ")" ::: "memory")
; #define G8_BAR __builtin_amdgcn_s_barrier()
; #define G8_SCHED __builtin_amdgcn_sched_barrier(0)
; template <class Epi>
; __device__ __forceinline__ void gemm_phase(LAS unsigned char* lds, const h16* A, const h16* Bt, int K, const Order& S, const Epi& E) {
;     ...
;       const bool last = (t == nt - 2);
;       const char* a1 = cA + (size_t)(t + 1) * kstep;
;       const char* a2 = last ? nA : cA + (size_t)(t + 2) * kstep;
;       const char* b2 = last ? nB : cB + (size_t)(t + 2) * kstep;
;       const char* a3 = a2 + kstep;
;       const char* b3 = b2 + kstep;
;       if (Epi::MID_T >= 0 && t == Epi::MID_T) E.mid(acc, ui, wr, fr);
;       G8_LDB(B0, 0, 0); G8_SCHED; G8_LDA(At, 0, 0); G8_STAGE(G8_SA(1, 1), a1 + hstep);
;       G8_WAIT_L(8); G8_BAR; G8_WAIT_L(0); G8_MMA(0, 0, At, B0); G8_BAR; G8_SCHED;
;       G8_LDB(B1, 0, 1); G8_STAGE(G8_SB(0, 0), b2);
;       G8_BAR; G8_WAIT_L(0); G8_MMA(0, 1, At, B1); G8_BAR;
;       G8_LDA(At, 0, 1); G8_STAGE(G8_SA(0, 0), a2);
;       G8_BAR; G8_WAIT_L(0); G8_MMA(1, 0, At, B0); G8_BAR; G8_SCHED;
.LBB0_2284:
	v_or_b32_e32 v34, 0x10000, v171
	v_add_u32_e32 v46, 0x10400, v171
	v_add_u32_e32 v50, 0x10800, v171
	v_add_u32_e32 v160, 0x10c00, v171
	ds_read_b128 v[34:37], v34
	ds_read_b128 v[46:49], v46
	ds_read_b128 v[50:53], v50
	ds_read_b128 v[160:163], v160
	s_add_u32 s26, s24, 0xfffe0080
	s_addc_u32 s27, s25, -1
	s_cmp_eq_u32 s55, 4
	s_cselect_b32 s29, s3, s27
	s_cselect_b32 s28, s17, s26
	s_cselect_b32 s27, s15, s54
	s_cselect_b32 s26, s23, s53
	v_lshl_add_u64 v[168:169], s[24:25], 0, v[156:157]
	s_add_i32 m0, s37, 0xc000
	ds_read_b128 v[164:167], v170
	ds_read_b128 v[174:177], v170 offset:1024
	ds_read_b128 v[178:181], v170 offset:2048
	ds_read_b128 v[182:185], v170 offset:3072
	ds_read_b128 v[186:189], v170 offset:4096
	ds_read_b128 v[202:205], v170 offset:5120
	ds_read_b128 v[206:209], v170 offset:6144
	ds_read_b128 v[210:213], v170 offset:7168
	global_load_lds_dwordx4 v[168:169], off
	v_lshl_add_u64 v[168:169], s[24:25], 0, v[158:159]
	s_add_i32 m0, s37, 0xe000
	s_nop 0
	global_load_lds_dwordx4 v[168:169], off
	s_waitcnt lgkmcnt(8)
	s_barrier
	s_waitcnt lgkmcnt(0)
	s_waitcnt lgkmcnt(0)
	v_mfma_f32_16x16x32_f16 v[62:65], v[34:37], v[164:167], v[62:65]
	v_mfma_f32_16x16x32_f16 v[138:141], v[50:53], v[164:167], v[138:141]
	v_mfma_f32_16x16x32_f16 v[122:125], v[34:37], v[178:181], v[122:125]
	v_mfma_f32_16x16x32_f16 v[126:129], v[50:53], v[178:181], v[126:129]
	v_mfma_f32_16x16x32_f16 v[106:109], v[34:37], v[186:189], v[106:109]
	v_mfma_f32_16x16x32_f16 v[110:113], v[50:53], v[186:189], v[110:113]
	v_mfma_f32_16x16x32_f16 v[90:93], v[34:37], v[206:209], v[90:93]
	v_mfma_f32_16x16x32_f16 v[94:97], v[50:53], v[206:209], v[94:97]
	v_mfma_f32_16x16x32_f16 v[62:65], v[46:49], v[174:177], v[62:65]
	v_mfma_f32_16x16x32_f16 v[138:141], v[160:163], v[174:177], v[138:141]
	v_mfma_f32_16x16x32_f16 v[122:125], v[46:49], v[182:185], v[122:125]
	v_mfma_f32_16x16x32_f16 v[126:129], v[160:163], v[182:185], v[126:129]
	v_mfma_f32_16x16x32_f16 v[106:109], v[46:49], v[202:205], v[106:109]
	v_mfma_f32_16x16x32_f16 v[110:113], v[160:163], v[202:205], v[110:113]
	v_mfma_f32_16x16x32_f16 v[90:93], v[46:49], v[210:213], v[90:93]
	v_mfma_f32_16x16x32_f16 v[94:97], v[160:163], v[210:213], v[94:97]
	s_barrier
	v_or_b32_e32 v168, 0x14000, v171
	v_add_u32_e32 v169, 0x14400, v171
	ds_read_b128 v[214:217], v168
	ds_read_b128 v[218:221], v169
	v_add_u32_e32 v168, 0x14800, v171
	v_add_u32_e32 v169, 0x14c00, v171
	s_mov_b32 m0, s38
	ds_read_b128 v[222:225], v168
	ds_read_b128 v[226:229], v169
	v_lshl_add_u64 v[168:169], s[26:27], 0, v[0:1]
	global_load_lds_dwordx4 v[168:169], off
	v_lshl_add_u64 v[230:231], s[26:27], 0, v[152:153]
	s_mov_b32 m0, s39
	s_nop 0
	global_load_lds_dwordx4 v[230:231], off
	s_barrier
	s_waitcnt lgkmcnt(0)
	s_waitcnt lgkmcnt(0)
	v_mfma_f32_16x16x32_f16 v[130:133], v[214:217], v[164:167], v[130:133]
	v_mfma_f32_16x16x32_f16 v[134:137], v[222:225], v[164:167], v[134:137]
	v_mfma_f32_16x16x32_f16 v[114:117], v[214:217], v[178:181], v[114:117]
	v_mfma_f32_16x16x32_f16 v[118:121], v[222:225], v[178:181], v[118:121]
	v_mfma_f32_16x16x32_f16 v[98:101], v[214:217], v[186:189], v[98:101]
	v_mfma_f32_16x16x32_f16 v[102:105], v[222:225], v[186:189], v[102:105]
	v_mfma_f32_16x16x32_f16 v[82:85], v[214:217], v[206:209], v[82:85]
	v_mfma_f32_16x16x32_f16 v[86:89], v[222:225], v[206:209], v[86:89]
	v_mfma_f32_16x16x32_f16 v[130:133], v[218:221], v[174:177], v[130:133]
	v_mfma_f32_16x16x32_f16 v[134:137], v[226:229], v[174:177], v[134:137]
	v_mfma_f32_16x16x32_f16 v[114:117], v[218:221], v[182:185], v[114:117]
	v_mfma_f32_16x16x32_f16 v[118:121], v[226:229], v[182:185], v[118:121]
	v_mfma_f32_16x16x32_f16 v[98:101], v[218:221], v[202:205], v[98:101]
	v_mfma_f32_16x16x32_f16 v[102:105], v[226:229], v[202:205], v[102:105]
	v_mfma_f32_16x16x32_f16 v[82:85], v[218:221], v[210:213], v[82:85]
	v_mfma_f32_16x16x32_f16 v[86:89], v[226:229], v[210:213], v[86:89]
	s_mov_b32 m0, s37
	v_lshl_add_u64 v[232:233], s[28:29], 0, v[0:1]
	s_barrier
	ds_read_b128 v[164:167], v170 offset:16384
	ds_read_b128 v[174:177], v170 offset:17408
	ds_read_b128 v[178:181], v170 offset:18432
	ds_read_b128 v[182:185], v170 offset:19456
	ds_read_b128 v[186:189], v170 offset:20480
	ds_read_b128 v[202:205], v170 offset:21504
	ds_read_b128 v[206:209], v170 offset:22528
	ds_read_b128 v[210:213], v170 offset:23552
	global_load_lds_dwordx4 v[232:233], off
	v_lshl_add_u64 v[234:235], s[28:29], 0, v[152:153]
	s_mov_b32 m0, s40
	s_nop 0
	global_load_lds_dwordx4 v[234:235], off
	s_barrier
	s_waitcnt lgkmcnt(0)
	s_waitcnt lgkmcnt(0)
	v_mfma_f32_16x16x32_f16 v[74:77], v[34:37], v[164:167], v[74:77]
	v_mfma_f32_16x16x32_f16 v[78:81], v[50:53], v[164:167], v[78:81]
	v_mfma_f32_16x16x32_f16 v[54:57], v[34:37], v[178:181], v[54:57]
	v_mfma_f32_16x16x32_f16 v[58:61], v[50:53], v[178:181], v[58:61]
	v_mfma_f32_16x16x32_f16 v[26:29], v[34:37], v[186:189], v[26:29]
	v_mfma_f32_16x16x32_f16 v[30:33], v[50:53], v[186:189], v[30:33]
	v_mfma_f32_16x16x32_f16 v[10:13], v[34:37], v[206:209], v[10:13]
	v_mfma_f32_16x16x32_f16 v[14:17], v[50:53], v[206:209], v[14:17]
	v_mfma_f32_16x16x32_f16 v[74:77], v[46:49], v[174:177], v[74:77]
	v_mfma_f32_16x16x32_f16 v[78:81], v[160:163], v[174:177], v[78:81]
	v_mfma_f32_16x16x32_f16 v[54:57], v[46:49], v[182:185], v[54:57]
	v_mfma_f32_16x16x32_f16 v[58:61], v[160:163], v[182:185], v[58:61]
	v_mfma_f32_16x16x32_f16 v[26:29], v[46:49], v[202:205], v[26:29]
	v_mfma_f32_16x16x32_f16 v[30:33], v[160:163], v[202:205], v[30:33]
	v_mfma_f32_16x16x32_f16 v[10:13], v[46:49], v[210:213], v[10:13]
	v_mfma_f32_16x16x32_f16 v[14:17], v[160:163], v[210:213], v[14:17]
	s_barrier
; #define G8_STAGE(bufoff, gbase) do { _Pragma("unroll") for (int _i = 0; _i < 2; ++_i) \
;     __builtin_amdgcn_global_load_lds((const unsigned*)((const char*)(gbase) + voffA[_i]), (LAS unsigned*)(lds + (bufoff) + ldsw + _i * 8192), 16, 0, 0); } while (0)
; #define G8_LDA(dst, b, h) do { _Pragma("unroll") for (int m = 0; m < 4; ++m) _Pragma("unroll") for (int k = 0; k < 2; ++k) dst[m][k] = *(const LAS h16x8*)(lds + G8_SA(b, h) + aoff + m * 2048 + k * 1024); } while (0)
; #define G8_LDB(dst, b, h) do { _Pragma("unroll") for (int n = 0; n < 2; ++n) _Pragma("unroll") for (int k = 0; k < 2; ++k) dst[n][k] = *(const LAS h16x8*)(lds + G8_SB(b, h) + boff + n * 2048 + k * 1024); } while (0)
; #define G8_MMA(ai, bj, At, Bt_) do { __builtin_amdgcn_s_setprio(1); _Pragma("unroll") for (int m = 0; m < 4; ++m) _Pragma("unroll") for (int n = 0; n < 2; ++n) _Pragma("unroll") for (int k = 0; k < 2; ++k) \
;     acc[ai][bj][m][n] = __builtin_amdgcn_mfma_f32_16x16x32_f16(Bt_[n][k], At[m][k], acc[ai][bj][m][n], 0, 0, 0); __builtin_amdgcn_s_setprio(0); } while (0)
; #define G8_WAIT_V(n) asm volatile("s_waitcnt vmcnt(" #n ")" ::: "memory")
; #define G8_WAIT_L(n) asm volatile("s_waitcnt lgkmcnt(" #n ")" ::: "memory")
; #define G8_BAR __builtin_amdgcn_s_barrier()
; #define G8_SCHED __builtin_amdgcn_sched_barrier(0)
; template <class Epi>
; __device__ __forceinline__ void gemm_phase(LAS unsigned char* lds, const h16* A, const h16* Bt, int K, const Order& S, const Epi& E) {
;     ...
;       G8_STAGE(G8_SB(0, 1), b2 + hstep);
;       G8_WAIT_V(6); G8_BAR; G8_MMA(1, 1, At, B1); G8_BAR;
;       G8_LDB(B0, 1, 0); G8_SCHED; G8_LDA(At, 1, 0); G8_STAGE(G8_SA(0, 1), a2 + hstep);
;       G8_WAIT_L(8); G8_BAR; G8_WAIT_L(0); G8_MMA(0, 0, At, B0); G8_BAR; G8_SCHED;
;       G8_LDB(B1, 1, 1); G8_STAGE(G8_SB(1, 0), b3);
;       G8_BAR; G8_WAIT_L(0); G8_MMA(0, 1, At, B1); G8_BAR;
;       G8_LDA(At, 1, 1); G8_STAGE(G8_SA(1, 0), a3);
	s_add_u32 s56, s26, 0x20000
	s_addc_u32 s57, s27, 0
	s_mov_b32 m0, s41
	v_lshl_add_u64 v[34:35], s[56:57], 0, v[0:1]
	global_load_lds_dwordx4 v[34:35], off
	v_lshl_add_u64 v[34:35], s[56:57], 0, v[152:153]
	s_mov_b32 m0, s42
	s_nop 0
	global_load_lds_dwordx4 v[34:35], off
	s_waitcnt vmcnt(6)
	s_barrier
	v_mfma_f32_16x16x32_f16 v[38:41], v[214:217], v[178:181], v[38:41]
	v_mfma_f32_16x16x32_f16 v[42:45], v[222:225], v[178:181], v[42:45]
	v_mfma_f32_16x16x32_f16 v[18:21], v[214:217], v[186:189], v[18:21]
	v_mfma_f32_16x16x32_f16 v[22:25], v[222:225], v[186:189], v[22:25]
	v_mfma_f32_16x16x32_f16 v[2:5], v[214:217], v[206:209], v[2:5]
	v_mfma_f32_16x16x32_f16 v[6:9], v[222:225], v[206:209], v[6:9]
	v_mfma_f32_16x16x32_f16 v[34:37], v[214:217], v[164:167], v[66:69]
	v_mfma_f32_16x16x32_f16 v[46:49], v[222:225], v[164:167], v[70:73]
	v_mfma_f32_16x16x32_f16 v[38:41], v[218:221], v[182:185], v[38:41]
	v_mfma_f32_16x16x32_f16 v[42:45], v[226:229], v[182:185], v[42:45]
	v_mfma_f32_16x16x32_f16 v[18:21], v[218:221], v[202:205], v[18:21]
	v_mfma_f32_16x16x32_f16 v[22:25], v[226:229], v[202:205], v[22:25]
	v_mfma_f32_16x16x32_f16 v[2:5], v[218:221], v[210:213], v[2:5]
	v_mfma_f32_16x16x32_f16 v[6:9], v[226:229], v[210:213], v[6:9]
	v_mfma_f32_16x16x32_f16 v[34:37], v[218:221], v[174:177], v[34:37]
	v_mfma_f32_16x16x32_f16 v[46:49], v[226:229], v[174:177], v[46:49]
	v_or_b32_e32 v50, 0x18000, v171
	v_add_u32_e32 v66, 0x18400, v171
	v_add_u32_e32 v70, 0x18800, v171
	v_add_u32_e32 v160, 0x18c00, v171
	s_barrier
	ds_read_b128 v[50:53], v50
	ds_read_b128 v[66:69], v66
	ds_read_b128 v[70:73], v70
	ds_read_b128 v[160:163], v160
	s_add_u32 s28, s28, 0x20000
	s_addc_u32 s29, s29, 0
	s_mov_b32 m0, s43
	v_lshl_add_u64 v[214:215], s[28:29], 0, v[0:1]
	ds_read_b128 v[164:167], v170 offset:32768
	ds_read_b128 v[174:177], v170 offset:33792
	ds_read_b128 v[178:181], v170 offset:34816
	ds_read_b128 v[182:185], v170 offset:35840
	ds_read_b128 v[186:189], v170 offset:36864
	ds_read_b128 v[202:205], v170 offset:37888
	ds_read_b128 v[206:209], v170 offset:38912
	ds_read_b128 v[210:213], v170 offset:39936
	global_load_lds_dwordx4 v[214:215], off
	v_lshl_add_u64 v[214:215], s[28:29], 0, v[152:153]
	s_mov_b32 m0, s44
	s_nop 0
	global_load_lds_dwordx4 v[214:215], off
	s_waitcnt lgkmcnt(8)
	s_barrier
	s_waitcnt lgkmcnt(0)
	s_waitcnt lgkmcnt(0)
	v_mfma_f32_16x16x32_f16 v[62:65], v[50:53], v[164:167], v[62:65]
	v_mfma_f32_16x16x32_f16 v[138:141], v[70:73], v[164:167], v[138:141]
	v_mfma_f32_16x16x32_f16 v[122:125], v[50:53], v[178:181], v[122:125]
	v_mfma_f32_16x16x32_f16 v[126:129], v[70:73], v[178:181], v[126:129]
	v_mfma_f32_16x16x32_f16 v[106:109], v[50:53], v[186:189], v[106:109]
	v_mfma_f32_16x16x32_f16 v[110:113], v[70:73], v[186:189], v[110:113]
	v_mfma_f32_16x16x32_f16 v[90:93], v[50:53], v[206:209], v[90:93]
	v_mfma_f32_16x16x32_f16 v[94:97], v[70:73], v[206:209], v[94:97]
	v_mfma_f32_16x16x32_f16 v[62:65], v[66:69], v[174:177], v[62:65]
	v_mfma_f32_16x16x32_f16 v[138:141], v[160:163], v[174:177], v[138:141]
	v_mfma_f32_16x16x32_f16 v[122:125], v[66:69], v[182:185], v[122:125]
	v_mfma_f32_16x16x32_f16 v[126:129], v[160:163], v[182:185], v[126:129]
	v_mfma_f32_16x16x32_f16 v[106:109], v[66:69], v[202:205], v[106:109]
	v_mfma_f32_16x16x32_f16 v[110:113], v[160:163], v[202:205], v[110:113]
	v_mfma_f32_16x16x32_f16 v[90:93], v[66:69], v[210:213], v[90:93]
	v_mfma_f32_16x16x32_f16 v[94:97], v[160:163], v[210:213], v[94:97]
	s_barrier
	v_or_b32_e32 v173, 0x1c000, v171
	s_mov_b32 m0, s46
	v_add_u32_e32 v195, 0x1c400, v171
	ds_read_b128 v[214:217], v173
	ds_read_b128 v[218:221], v195
	v_add_u32_e32 v173, 0x1c800, v171
	v_lshl_add_u64 v[168:169], v[168:169], 0, s[94:95]
	v_add_u32_e32 v195, 0x1cc00, v171
	ds_read_b128 v[222:225], v173
	ds_read_b128 v[226:229], v195
	global_load_lds_dwordx4 v[168:169], off
	v_lshl_add_u64 v[168:169], v[230:231], 0, s[94:95]
	s_mov_b32 m0, s47
	s_nop 0
	global_load_lds_dwordx4 v[168:169], off
	s_barrier
	s_waitcnt lgkmcnt(0)
	s_waitcnt lgkmcnt(0)
	v_mfma_f32_16x16x32_f16 v[130:133], v[214:217], v[164:167], v[130:133]
	v_mfma_f32_16x16x32_f16 v[134:137], v[222:225], v[164:167], v[134:137]
	v_mfma_f32_16x16x32_f16 v[114:117], v[214:217], v[178:181], v[114:117]
	v_mfma_f32_16x16x32_f16 v[118:121], v[222:225], v[178:181], v[118:121]
	v_mfma_f32_16x16x32_f16 v[98:101], v[214:217], v[186:189], v[98:101]
	v_mfma_f32_16x16x32_f16 v[102:105], v[222:225], v[186:189], v[102:105]
	v_mfma_f32_16x16x32_f16 v[82:85], v[214:217], v[206:209], v[82:85]
	v_mfma_f32_16x16x32_f16 v[86:89], v[222:225], v[206:209], v[86:89]
	v_mfma_f32_16x16x32_f16 v[130:133], v[218:221], v[174:177], v[130:133]
	v_mfma_f32_16x16x32_f16 v[134:137], v[226:229], v[174:177], v[134:137]
	v_mfma_f32_16x16x32_f16 v[114:117], v[218:221], v[182:185], v[114:117]
	v_mfma_f32_16x16x32_f16 v[118:121], v[226:229], v[182:185], v[118:121]
	v_mfma_f32_16x16x32_f16 v[98:101], v[218:221], v[202:205], v[98:101]
	v_mfma_f32_16x16x32_f16 v[102:105], v[226:229], v[202:205], v[102:105]
	v_mfma_f32_16x16x32_f16 v[82:85], v[218:221], v[210:213], v[82:85]
	v_mfma_f32_16x16x32_f16 v[86:89], v[226:229], v[210:213], v[86:89]
	s_mov_b32 m0, s48
	v_lshl_add_u64 v[168:169], v[232:233], 0, s[94:95]
	s_barrier
	ds_read_b128 v[164:167], v170 offset:49152
	ds_read_b128 v[174:177], v170 offset:50176
	ds_read_b128 v[178:181], v170 offset:51200
	ds_read_b128 v[182:185], v170 offset:52224
	ds_read_b128 v[186:189], v170 offset:53248
	ds_read_b128 v[202:205], v170 offset:54272
	ds_read_b128 v[206:209], v170 offset:55296
	ds_read_b128 v[210:213], v170 offset:56320
	global_load_lds_dwordx4 v[168:169], off
	v_lshl_add_u64 v[168:169], v[234:235], 0, s[94:95]
	s_mov_b32 m0, s49
	s_nop 0
	global_load_lds_dwordx4 v[168:169], off
	s_barrier
; #define G8_STAGE(bufoff, gbase) do { _Pragma("unroll") for (int _i = 0; _i < 2; ++_i) \
;     __builtin_amdgcn_global_load_lds((const unsigned*)((const char*)(gbase) + voffA[_i]), (LAS unsigned*)(lds + (bufoff) + ldsw + _i * 8192), 16, 0, 0); } while (0)
; #define G8_MMA(ai, bj, At, Bt_) do { __builtin_amdgcn_s_setprio(1); _Pragma("unroll") for (int m = 0; m < 4; ++m) _Pragma("unroll") for (int n = 0; n < 2; ++n) _Pragma("unroll") for (int k = 0; k < 2; ++k) \
;     acc[ai][bj][m][n] = __builtin_amdgcn_mfma_f32_16x16x32_f16(Bt_[n][k], At[m][k], acc[ai][bj][m][n], 0, 0, 0); __builtin_amdgcn_s_setprio(0); } while (0)
; #define G8_WAIT_V(n) asm volatile("s_waitcnt vmcnt(" #n ")" ::: "memory")
; #define G8_WAIT_L(n) asm volatile("s_waitcnt lgkmcnt(" #n ")" ::: "memory")
; #define G8_BAR __builtin_amdgcn_s_barrier()
; #define G8_SCHED __builtin_amdgcn_sched_barrier(0)
; template <class Epi>
; __device__ __forceinline__ void gemm_phase(LAS unsigned char* lds, const h16* A, const h16* Bt, int K, const Order& S, const Epi& E) {
;     ...
;       G8_BAR; G8_WAIT_L(0); G8_MMA(1, 0, At, B0); G8_BAR; G8_SCHED;
;       G8_STAGE(G8_SB(1, 1), b3 + hstep);
;       G8_WAIT_V(6); G8_BAR; G8_MMA(1, 1, At, B1); G8_BAR;
;     }
	s_waitcnt lgkmcnt(0)
	s_waitcnt lgkmcnt(0)
	v_mfma_f32_16x16x32_f16 v[74:77], v[50:53], v[164:167], v[74:77]
	v_mfma_f32_16x16x32_f16 v[78:81], v[70:73], v[164:167], v[78:81]
	v_mfma_f32_16x16x32_f16 v[54:57], v[50:53], v[178:181], v[54:57]
	v_mfma_f32_16x16x32_f16 v[58:61], v[70:73], v[178:181], v[58:61]
	v_mfma_f32_16x16x32_f16 v[26:29], v[50:53], v[186:189], v[26:29]
	v_mfma_f32_16x16x32_f16 v[30:33], v[70:73], v[186:189], v[30:33]
	v_mfma_f32_16x16x32_f16 v[10:13], v[50:53], v[206:209], v[10:13]
	v_mfma_f32_16x16x32_f16 v[14:17], v[70:73], v[206:209], v[14:17]
	v_mfma_f32_16x16x32_f16 v[74:77], v[66:69], v[174:177], v[74:77]
	v_mfma_f32_16x16x32_f16 v[78:81], v[160:163], v[174:177], v[78:81]
	v_mfma_f32_16x16x32_f16 v[54:57], v[66:69], v[182:185], v[54:57]
	v_mfma_f32_16x16x32_f16 v[58:61], v[160:163], v[182:185], v[58:61]
	v_mfma_f32_16x16x32_f16 v[26:29], v[66:69], v[202:205], v[26:29]
	v_mfma_f32_16x16x32_f16 v[30:33], v[160:163], v[202:205], v[30:33]
	v_mfma_f32_16x16x32_f16 v[10:13], v[66:69], v[210:213], v[10:13]
	v_mfma_f32_16x16x32_f16 v[14:17], v[160:163], v[210:213], v[14:17]
	s_barrier
	s_add_u32 s26, s26, 0x20080
	s_addc_u32 s27, s27, 0
	s_mov_b32 m0, s50
	v_lshl_add_u64 v[50:51], s[26:27], 0, v[0:1]
	global_load_lds_dwordx4 v[50:51], off
	v_lshl_add_u64 v[50:51], s[26:27], 0, v[152:153]
	s_mov_b32 m0, s51
	s_nop 0
	global_load_lds_dwordx4 v[50:51], off
	s_waitcnt vmcnt(6)
	s_barrier
	v_mfma_f32_16x16x32_f16 v[34:37], v[214:217], v[164:167], v[34:37]
	v_mfma_f32_16x16x32_f16 v[66:69], v[218:221], v[174:177], v[34:37]
	v_mfma_f32_16x16x32_f16 v[34:37], v[222:225], v[164:167], v[46:49]
	v_mfma_f32_16x16x32_f16 v[70:73], v[226:229], v[174:177], v[34:37]
	v_mfma_f32_16x16x32_f16 v[34:37], v[214:217], v[178:181], v[38:41]
	v_mfma_f32_16x16x32_f16 v[38:41], v[218:221], v[182:185], v[34:37]
	v_mfma_f32_16x16x32_f16 v[34:37], v[222:225], v[178:181], v[42:45]
	v_mfma_f32_16x16x32_f16 v[18:21], v[214:217], v[186:189], v[18:21]
	v_mfma_f32_16x16x32_f16 v[22:25], v[222:225], v[186:189], v[22:25]
	v_mfma_f32_16x16x32_f16 v[2:5], v[214:217], v[206:209], v[2:5]
	v_mfma_f32_16x16x32_f16 v[6:9], v[222:225], v[206:209], v[6:9]
	v_mfma_f32_16x16x32_f16 v[42:45], v[226:229], v[182:185], v[34:37]
	v_mfma_f32_16x16x32_f16 v[18:21], v[218:221], v[202:205], v[18:21]
	v_mfma_f32_16x16x32_f16 v[22:25], v[226:229], v[202:205], v[22:25]
	v_mfma_f32_16x16x32_f16 v[2:5], v[218:221], v[210:213], v[2:5]
	v_mfma_f32_16x16x32_f16 v[6:9], v[226:229], v[210:213], v[6:9]
	s_add_i32 s55, s55, 2
	s_add_u32 s24, s24, 0x100
	s_addc_u32 s25, s25, 0
	s_add_u32 s53, s53, 0x100
	s_addc_u32 s54, s54, 0
	s_cmp_gt_u32 s55, 5
	s_barrier
	s_cbranch_scc0 .LBB0_2284
; __device__ __forceinline__ float xor16(float v) { return __int_as_float(__builtin_amdgcn_ds_swizzle(__float_as_int(v), 0x401F)); }
; __device__ __forceinline__ float sigmoidf(float x) { return 1.f / (1.f + __expf(-x)); }
;   __device__ __forceinline__ void operator()(const f32x4 (&acc)[2][2][4][2], const g8::Unit& u, int ui, int wr, int wc, int fr, int fq) const {
;     const int ocb = 128 * u.pn + 16 * wc + 4 * fq;
;     float4 ba[2], bb[2];
; #pragma unroll
;     for (int bj = 0; bj < 2; ++bj) { ba[bj] = *(const float4*)(gb + ocb + 64 * bj); bb[bj] = *(const float4*)(gb + 512 + ocb + 64 * bj); }
; #pragma unroll
;     for (int ai = 0; ai < 2; ++ai)
; #pragma unroll
;       for (int m = 0; m < 4; ++m) {
;         const size_t row = (size_t)u.pm * 256 + 128 * ai + 64 * wr + 16 * m + fr;
;         float ss = 0.f;
; #pragma unroll
;         for (int bj = 0; bj < 2; ++bj) {
;           const f32x4 a = acc[ai][bj][m][0], b = acc[ai][bj][m][1];
;           float o0 = (a[0] + ba[bj].x) * sigmoidf(b[0] + bb[bj].x);
;           float o1 = (a[1] + ba[bj].y) * sigmoidf(b[1] + bb[bj].y);
;           float o2 = (a[2] + ba[bj].z) * sigmoidf(b[2] + bb[bj].z);
;           float o3 = (a[3] + ba[bj].w) * sigmoidf(b[3] + bb[bj].w);
;           *(h16x4*)(OB + row * 1024 + ocb + 64 * bj) = pack4(o0, o1, o2, o3);
;           ss += o0 * o0 + o1 * o1 + o2 * o2 + o3 * o3;
;         }
;         ss += xor16(ss);
;         ss += __shfl_xor(ss, 32);
;         if (fq == 0) ssqb[row * 16 + u.pn * 4 + wc] = ss;
	v_lshl_or_b32 v160, s2, 7, v172
	v_ashrrev_i32_e32 v161, 31, v160
	v_lshl_add_u64 v[166:167], v[160:161], 2, s[12:13]
	global_load_dwordx4 v[46:49], v[166:167], off offset:2048
	global_load_dwordx4 v[34:37], v[166:167], off offset:2304
	v_and_b32_e32 v51, 64, v199
	v_xor_b32_e32 v50, 32, v199
	v_add_u32_e32 v51, 64, v51
	v_cmp_lt_i32_e32 vcc, v50, v51
	s_ashr_i32 s23, s22, 31
	s_lshl_b64 s[22:23], s[22:23], 8
	v_cndmask_b32_e32 v50, v199, v50, vcc
	v_lshlrev_b32_e32 v173, 2, v50
	v_lshl_add_u64 v[162:163], s[22:23], 0, v[154:155]
	s_lshl_b32 s22, s2, 2
	v_lshlrev_b64 v[164:165], 11, v[162:163]
	s_ashr_i32 s23, s22, 31
	s_waitcnt vmcnt(0)
	v_add_f32_e32 v50, v138, v46
	v_mul_f32_e32 v50, 0xbfb8aa3b, v50
	v_exp_f32_e32 v138, v50
	global_load_dwordx4 v[50:53], v[166:167], off
	v_add_f32_e32 v139, v139, v47
	v_mul_f32_e32 v139, 0xbfb8aa3b, v139
	v_exp_f32_e32 v139, v139
	v_add_f32_e32 v140, v140, v48
	v_add_f32_e32 v141, v141, v49
	v_mul_f32_e32 v140, 0xbfb8aa3b, v140
	v_pk_add_f32 v[138:139], v[138:139], 1.0 op_sel_hi:[1,0]
	v_mul_f32_e32 v141, 0xbfb8aa3b, v141
	v_div_scale_f32 v168, s[2:3], v139, v139, 1.0
	v_rcp_f32_e32 v169, v168
	v_exp_f32_e32 v140, v140
	v_exp_f32_e32 v141, v141
	v_add_f32_e32 v135, v135, v35
	v_fma_f32 v174, -v168, v169, 1.0
	v_fmac_f32_e32 v169, v174, v169
	v_div_scale_f32 v174, vcc, 1.0, v139, 1.0
	v_mul_f32_e32 v175, v174, v169
	v_fma_f32 v176, -v168, v175, v174
	v_fmac_f32_e32 v175, v176, v169
	v_fma_f32 v168, -v168, v175, v174
	v_div_fmas_f32 v168, v168, v169, v175
	v_div_fixup_f32 v139, v168, v139, 1.0
	v_div_scale_f32 v168, s[2:3], v138, v138, 1.0
	v_rcp_f32_e32 v169, v168
	v_mul_f32_e32 v135, 0xbfb8aa3b, v135
	v_exp_f32_e32 v135, v135
	v_add_f32_e32 v136, v136, v36
	v_fma_f32 v174, -v168, v169, 1.0
	v_fmac_f32_e32 v169, v174, v169
	v_div_scale_f32 v174, vcc, 1.0, v138, 1.0
	v_mul_f32_e32 v175, v174, v169
	v_fma_f32 v176, -v168, v175, v174
	v_fmac_f32_e32 v175, v176, v169
	v_fma_f32 v168, -v168, v175, v174
	v_div_fmas_f32 v168, v168, v169, v175
	v_div_fixup_f32 v138, v168, v138, 1.0
	v_add_f32_e32 v137, v137, v37
	v_mul_f32_e32 v136, 0xbfb8aa3b, v136
	v_mul_f32_e32 v137, 0xbfb8aa3b, v137
	v_exp_f32_e32 v136, v136
	v_exp_f32_e32 v137, v137
	s_waitcnt vmcnt(0)
	v_pk_add_f32 v[62:63], v[62:63], v[50:51]
	s_nop 0
	v_pk_mul_f32 v[62:63], v[62:63], v[138:139]
	v_pk_add_f32 v[138:139], v[140:141], 1.0 op_sel_hi:[1,0]
	v_cvt_pk_f16_f32 v168, v62, v63
	v_div_scale_f32 v140, s[2:3], v139, v139, 1.0
	v_rcp_f32_e32 v141, v140
	v_pk_add_f32 v[64:65], v[64:65], v[52:53]
	v_pk_add_f32 v[136:137], v[136:137], 1.0 op_sel_hi:[1,0]
	v_fma_f32 v169, -v140, v141, 1.0
	v_fmac_f32_e32 v141, v169, v141
	v_div_scale_f32 v169, vcc, 1.0, v139, 1.0
	v_mul_f32_e32 v174, v169, v141
	v_fma_f32 v175, -v140, v174, v169
	v_fmac_f32_e32 v174, v175, v141
	v_fma_f32 v140, -v140, v174, v169
	v_div_fmas_f32 v140, v140, v141, v174
	v_div_fixup_f32 v139, v140, v139, 1.0
	v_div_scale_f32 v140, s[2:3], v138, v138, 1.0
	v_rcp_f32_e32 v141, v140
	s_nop 0
	v_fma_f32 v169, -v140, v141, 1.0
	v_fmac_f32_e32 v141, v169, v141
	v_div_scale_f32 v169, vcc, 1.0, v138, 1.0
	v_mul_f32_e32 v174, v169, v141
	v_fma_f32 v175, -v140, v174, v169
	v_fmac_f32_e32 v174, v175, v141
	v_fma_f32 v140, -v140, v174, v169
	v_div_fmas_f32 v140, v140, v141, v174
	v_div_fixup_f32 v138, v140, v138, 1.0
	v_pk_mul_f32 v[140:141], v[62:63], v[62:63]
	v_add_f32_e32 v62, v134, v34
	v_pk_mul_f32 v[64:65], v[64:65], v[138:139]
	v_lshl_add_u64 v[138:139], s[0:1], 0, v[164:165]
	v_mul_f32_e32 v62, 0xbfb8aa3b, v62
	v_cvt_pk_f16_f32 v169, v64, v65
	v_lshl_add_u64 v[164:165], v[160:161], 1, v[138:139]
	v_pk_mul_f32 v[138:139], v[64:65], v[64:65]
	v_exp_f32_e32 v134, v62
	global_load_dwordx4 v[62:65], v[166:167], off offset:256
	v_pk_add_f32 v[134:135], v[134:135], 1.0 op_sel_hi:[1,0]
	s_nop 0
	v_div_scale_f32 v166, s[2:3], v135, v135, 1.0
	v_rcp_f32_e32 v167, v166
	global_store_dwordx2 v[164:165], v[168:169], off
	v_fma_f32 v168, -v166, v167, 1.0
	v_fmac_f32_e32 v167, v168, v167
	v_div_scale_f32 v168, vcc, 1.0, v135, 1.0
	v_mul_f32_e32 v169, v168, v167
	v_fma_f32 v174, -v166, v169, v168
	v_fmac_f32_e32 v169, v174, v167
	v_fma_f32 v166, -v166, v169, v168
	v_div_fmas_f32 v166, v166, v167, v169
	v_div_fixup_f32 v135, v166, v135, 1.0
	v_div_scale_f32 v166, s[2:3], v134, v134, 1.0
	v_rcp_f32_e32 v167, v166
	s_waitcnt vmcnt(0)
	v_pk_add_f32 v[130:131], v[130:131], v[62:63]
	v_fma_f32 v168, -v166, v167, 1.0
	v_fmac_f32_e32 v167, v168, v167
	v_div_scale_f32 v168, vcc, 1.0, v134, 1.0
	v_mul_f32_e32 v169, v168, v167
	v_fma_f32 v174, -v166, v169, v168
	v_fmac_f32_e32 v169, v174, v167
	v_fma_f32 v166, -v166, v169, v168
	v_div_fmas_f32 v166, v166, v167, v169
	v_div_fixup_f32 v134, v166, v134, 1.0
	v_pk_mul_f32 v[130:131], v[130:131], v[134:135]
	v_div_scale_f32 v135, s[2:3], v137, v137, 1.0
	v_rcp_f32_e32 v166, v135
	v_pk_add_f32 v[132:133], v[132:133], v[64:65]
	v_cvt_pk_f16_f32 v134, v130, v131
	v_pk_mul_f32 v[130:131], v[130:131], v[130:131]
	v_fma_f32 v167, -v135, v166, 1.0
	v_fmac_f32_e32 v166, v167, v166
	v_div_scale_f32 v167, vcc, 1.0, v137, 1.0
	v_mul_f32_e32 v168, v167, v166
	v_fma_f32 v169, -v135, v168, v167
	v_fmac_f32_e32 v168, v169, v166
	v_fma_f32 v135, -v135, v168, v167
	v_div_fmas_f32 v135, v135, v166, v168
	v_div_fixup_f32 v137, v135, v137, 1.0
	v_div_scale_f32 v135, s[2:3], v136, v136, 1.0
	v_rcp_f32_e32 v166, v135
	v_add_f32_e32 v130, v130, v131
	v_add_f32_e32 v131, v140, v141
	v_add_f32_e32 v131, v138, v131
	v_fma_f32 v167, -v135, v166, 1.0
	v_fmac_f32_e32 v166, v167, v166
	v_div_scale_f32 v167, vcc, 1.0, v136, 1.0
	v_mul_f32_e32 v168, v167, v166
	v_fma_f32 v169, -v135, v168, v167
	v_fmac_f32_e32 v168, v169, v166
	v_fma_f32 v135, -v135, v168, v167
	v_div_fmas_f32 v135, v135, v166, v168
	v_div_fixup_f32 v136, v135, v136, 1.0
	v_pk_mul_f32 v[132:133], v[132:133], v[136:137]
	v_add_f32_e32 v131, v139, v131
	v_cvt_pk_f16_f32 v135, v132, v133
	v_pk_mul_f32 v[132:133], v[132:133], v[132:133]
	global_store_dwordx2 v[164:165], v[134:135], off offset:128
	v_add_f32_e32 v130, v132, v130
	v_add_f32_e32 v130, v133, v130
	v_add_f32_e32 v130, v131, v130
	v_mov_b32_e32 v131, v130
	s_nop 1
	v_permlane16_swap_b32_e32 v131, v130
	s_waitcnt lgkmcnt(0)
	v_add_f32_e32 v130, v130, v131
	v_mov_b32_e32 v131, v130
	s_nop 1
	v_permlane32_swap_b32_e32 v131, v130
	s_and_saveexec_b64 s[24:25], s[6:7]
	s_cbranch_execz .LBB0_2287
	s_waitcnt lgkmcnt(0)
	v_add_f32_e32 v132, v130, v131
	v_lshlrev_b64 v[130:131], 6, v[162:163]
	v_lshl_add_u64 v[130:131], s[10:11], 0, v[130:131]
	v_lshl_add_u64 v[130:131], s[22:23], 2, v[130:131]
	s_lshl_b32 s92, s45, 2
	v_lshl_add_u64 v[130:131], v[130:131], 0, s[92:93]
	global_store_dword v[130:131], v132, off

; #define G8_STAGE(bufoff, gbase) do { _Pragma("unroll") for (int _i = 0; _i < 2; ++_i) \
;     __builtin_amdgcn_global_load_lds((const unsigned*)((const char*)(gbase) + voffA[_i]), (LAS unsigned*)(lds + (bufoff) + ldsw + _i * 8192), 16, 0, 0); } while (0)
; #define G8_LDA(dst, b, h) do { _Pragma("unroll") for (int m = 0; m < 4; ++m) _Pragma("unroll") for (int k = 0; k < 2; ++k) dst[m][k] = *(const LAS h16x8*)(lds + G8_SA(b, h) + aoff + m * 2048 + k * 1024); } while (0)
; #define G8_LDB(dst, b, h) do { _Pragma("unroll") for (int n = 0; n < 2; ++n) _Pragma("unroll") for (int k = 0; k < 2; ++k) dst[n][k] = *(const LAS h16x8*)(lds + G8_SB(b, h) + boff + n * 2048 + k * 1024); } while (0)
; #define G8_MMA(ai, bj, At, Bt_) do { __builtin_amdgcn_s_setprio(1); _Pragma("unroll") for (int m = 0; m < 4; ++m) _Pragma("unroll") for (int n = 0; n < 2; ++n) _Pragma("unroll") for (int k = 0; k < 2; ++k) \
;     acc[ai][bj][m][n] = __builtin_amdgcn_mfma_f32_16x16x32_f16(Bt_[n][k], At[m][k], acc[ai][bj][m][n], 0, 0, 0); __builtin_amdgcn_s_setprio(0); } while (0)
; #define G8_WAIT_L(n) asm volatile("s_waitcnt lgkmcnt(" #n ")" ::: "memory")
; #define G8_BAR __builtin_amdgcn_s_barrier()
; #define G8_SCHED __builtin_amdgcn_sched_barrier(0)
; template <class Epi>
; __device__ __forceinline__ void gemm_phase(LAS unsigned char* lds, const h16* A, const h16* Bt, int K, const Order& S, const Epi& E) {
;     ...
;       const bool last = (t == nt - 2);
;       const char* a1 = cA + (size_t)(t + 1) * kstep;
;       const char* a2 = last ? nA : cA + (size_t)(t + 2) * kstep;
;       const char* b2 = last ? nB : cB + (size_t)(t + 2) * kstep;
;       const char* a3 = a2 + kstep;
;       const char* b3 = b2 + kstep;
;       if (Epi::MID_T >= 0 && t == Epi::MID_T) E.mid(acc, ui, wr, fr);
;       G8_LDB(B0, 0, 0); G8_SCHED; G8_LDA(At, 0, 0); G8_STAGE(G8_SA(1, 1), a1 + hstep);
;       G8_WAIT_L(8); G8_BAR; G8_WAIT_L(0); G8_MMA(0, 0, At, B0); G8_BAR; G8_SCHED;
;       G8_LDB(B1, 0, 1); G8_STAGE(G8_SB(0, 0), b2);
;       G8_BAR; G8_WAIT_L(0); G8_MMA(0, 1, At, B1); G8_BAR;
;       G8_LDA(At, 0, 1); G8_STAGE(G8_SA(0, 0), a2);
;       G8_BAR; G8_WAIT_L(0); G8_MMA(1, 0, At, B0); G8_BAR; G8_SCHED;
.LBB0_2378:
	s_add_u32 s26, s20, s24
	v_or_b32_e32 v0, 0x10000, v158
	s_addc_u32 s27, s21, s25
	v_add_u32_e32 v2, 0x10400, v158
	ds_read_b128 v[162:165], v0
	ds_read_b128 v[166:169], v2
	v_add_u32_e32 v0, 0x10800, v158
	s_add_u32 s26, s26, 0x100
	v_add_u32_e32 v2, 0x10c00, v158
	ds_read_b128 v[170:173], v0
	ds_read_b128 v[174:177], v2
	s_addc_u32 s27, s27, 0
	s_add_u32 s56, s53, s24
	s_addc_u32 s57, s54, s25
	s_cmpk_eq_i32 s24, 0x700
	s_cselect_b32 s29, s3, s27
	s_cselect_b32 s28, s15, s26
	s_cselect_b32 s27, s13, s57
	s_cselect_b32 s26, s23, s56
	v_lshl_add_u64 v[2:3], v[154:155], 0, s[24:25]
	s_add_i32 m0, s37, 0xc000
	ds_read_b128 v[178:181], v139
	ds_read_b128 v[182:185], v139 offset:1024
	ds_read_b128 v[186:189], v139 offset:2048
	ds_read_b128 v[202:205], v139 offset:3072
	ds_read_b128 v[206:209], v139 offset:4096
	ds_read_b128 v[210:213], v139 offset:5120
	ds_read_b128 v[214:217], v139 offset:6144
	ds_read_b128 v[218:221], v139 offset:7168
	global_load_lds_dwordx4 v[2:3], off
	v_lshl_add_u64 v[2:3], v[156:157], 0, s[24:25]
	s_add_i32 m0, s37, 0xe000
	s_nop 0
	global_load_lds_dwordx4 v[2:3], off
	s_waitcnt lgkmcnt(8)
	s_barrier
	s_waitcnt lgkmcnt(0)
	s_waitcnt lgkmcnt(0)
	v_mfma_f32_16x16x32_f16 v[128:131], v[162:165], v[178:181], v[128:131]
	v_mfma_f32_16x16x32_f16 v[124:127], v[170:173], v[178:181], v[124:127]
	v_mfma_f32_16x16x32_f16 v[112:115], v[162:165], v[186:189], v[112:115]
	v_mfma_f32_16x16x32_f16 v[108:111], v[170:173], v[186:189], v[108:111]
	v_mfma_f32_16x16x32_f16 v[96:99], v[162:165], v[206:209], v[96:99]
	v_mfma_f32_16x16x32_f16 v[92:95], v[170:173], v[206:209], v[92:95]
	v_mfma_f32_16x16x32_f16 v[80:83], v[162:165], v[214:217], v[80:83]
	v_mfma_f32_16x16x32_f16 v[76:79], v[170:173], v[214:217], v[76:79]
	v_mfma_f32_16x16x32_f16 v[128:131], v[166:169], v[182:185], v[128:131]
	v_mfma_f32_16x16x32_f16 v[124:127], v[174:177], v[182:185], v[124:127]
	v_mfma_f32_16x16x32_f16 v[112:115], v[166:169], v[202:205], v[112:115]
	v_mfma_f32_16x16x32_f16 v[108:111], v[174:177], v[202:205], v[108:111]
	v_mfma_f32_16x16x32_f16 v[96:99], v[166:169], v[210:213], v[96:99]
	v_mfma_f32_16x16x32_f16 v[92:95], v[174:177], v[210:213], v[92:95]
	v_mfma_f32_16x16x32_f16 v[80:83], v[166:169], v[218:221], v[80:83]
	v_mfma_f32_16x16x32_f16 v[76:79], v[174:177], v[218:221], v[76:79]
	s_barrier
	v_or_b32_e32 v0, 0x14000, v158
	s_mov_b32 m0, s38
	v_add_u32_e32 v2, 0x14400, v158
	ds_read_b128 v[222:225], v0
	ds_read_b128 v[226:229], v2
	v_add_u32_e32 v0, 0x14800, v158
	v_lshl_add_u64 v[238:239], s[26:27], 0, v[134:135]
	v_add_u32_e32 v2, 0x14c00, v158
	ds_read_b128 v[230:233], v0
	ds_read_b128 v[234:237], v2
	global_load_lds_dwordx4 v[238:239], off
	v_lshl_add_u64 v[240:241], s[26:27], 0, v[132:133]
	s_mov_b32 m0, s39
	s_nop 0
	global_load_lds_dwordx4 v[240:241], off
	s_barrier
	s_waitcnt lgkmcnt(0)
	s_waitcnt lgkmcnt(0)
	v_mfma_f32_16x16x32_f16 v[120:123], v[222:225], v[178:181], v[120:123]
	v_mfma_f32_16x16x32_f16 v[116:119], v[230:233], v[178:181], v[116:119]
	v_mfma_f32_16x16x32_f16 v[104:107], v[222:225], v[186:189], v[104:107]
	v_mfma_f32_16x16x32_f16 v[100:103], v[230:233], v[186:189], v[100:103]
	v_mfma_f32_16x16x32_f16 v[88:91], v[222:225], v[206:209], v[88:91]
	v_mfma_f32_16x16x32_f16 v[84:87], v[230:233], v[206:209], v[84:87]
	v_mfma_f32_16x16x32_f16 v[72:75], v[222:225], v[214:217], v[72:75]
	v_mfma_f32_16x16x32_f16 v[68:71], v[230:233], v[214:217], v[68:71]
	v_mfma_f32_16x16x32_f16 v[120:123], v[226:229], v[182:185], v[120:123]
	v_mfma_f32_16x16x32_f16 v[116:119], v[234:237], v[182:185], v[116:119]
	v_mfma_f32_16x16x32_f16 v[104:107], v[226:229], v[202:205], v[104:107]
	v_mfma_f32_16x16x32_f16 v[100:103], v[234:237], v[202:205], v[100:103]
	v_mfma_f32_16x16x32_f16 v[88:91], v[226:229], v[210:213], v[88:91]
	v_mfma_f32_16x16x32_f16 v[84:87], v[234:237], v[210:213], v[84:87]
	v_mfma_f32_16x16x32_f16 v[72:75], v[226:229], v[218:221], v[72:75]
	v_mfma_f32_16x16x32_f16 v[68:71], v[234:237], v[218:221], v[68:71]
	s_mov_b32 m0, s37
	v_lshl_add_u64 v[242:243], s[28:29], 0, v[134:135]
	s_barrier
	ds_read_b128 v[178:181], v139 offset:16384
	ds_read_b128 v[182:185], v139 offset:17408
	ds_read_b128 v[186:189], v139 offset:18432
	ds_read_b128 v[202:205], v139 offset:19456
	ds_read_b128 v[206:209], v139 offset:20480
	ds_read_b128 v[210:213], v139 offset:21504
	ds_read_b128 v[214:217], v139 offset:22528
	ds_read_b128 v[218:221], v139 offset:23552
	global_load_lds_dwordx4 v[242:243], off
	v_lshl_add_u64 v[244:245], s[28:29], 0, v[132:133]
	s_mov_b32 m0, s40
	s_nop 0
	global_load_lds_dwordx4 v[244:245], off
	s_barrier
	s_waitcnt lgkmcnt(0)
	s_waitcnt lgkmcnt(0)
	v_mfma_f32_16x16x32_f16 v[64:67], v[162:165], v[178:181], v[64:67]
	v_mfma_f32_16x16x32_f16 v[60:63], v[170:173], v[178:181], v[60:63]
	v_mfma_f32_16x16x32_f16 v[48:51], v[162:165], v[186:189], v[48:51]
	v_mfma_f32_16x16x32_f16 v[44:47], v[170:173], v[186:189], v[44:47]
	v_mfma_f32_16x16x32_f16 v[32:35], v[162:165], v[206:209], v[32:35]
	v_mfma_f32_16x16x32_f16 v[28:31], v[170:173], v[206:209], v[28:31]
	v_mfma_f32_16x16x32_f16 v[16:19], v[162:165], v[214:217], v[16:19]
	v_mfma_f32_16x16x32_f16 v[12:15], v[170:173], v[214:217], v[12:15]
	v_mfma_f32_16x16x32_f16 v[64:67], v[166:169], v[182:185], v[64:67]
	v_mfma_f32_16x16x32_f16 v[60:63], v[174:177], v[182:185], v[60:63]
	v_mfma_f32_16x16x32_f16 v[48:51], v[166:169], v[202:205], v[48:51]
	v_mfma_f32_16x16x32_f16 v[44:47], v[174:177], v[202:205], v[44:47]
	v_mfma_f32_16x16x32_f16 v[32:35], v[166:169], v[210:213], v[32:35]
	v_mfma_f32_16x16x32_f16 v[28:31], v[174:177], v[210:213], v[28:31]
	v_mfma_f32_16x16x32_f16 v[16:19], v[166:169], v[218:221], v[16:19]
	v_mfma_f32_16x16x32_f16 v[12:15], v[174:177], v[218:221], v[12:15]
	s_barrier
; #define G8_STAGE(bufoff, gbase) do { _Pragma("unroll") for (int _i = 0; _i < 2; ++_i) \
;     __builtin_amdgcn_global_load_lds((const unsigned*)((const char*)(gbase) + voffA[_i]), (LAS unsigned*)(lds + (bufoff) + ldsw + _i * 8192), 16, 0, 0); } while (0)
; #define G8_LDA(dst, b, h) do { _Pragma("unroll") for (int m = 0; m < 4; ++m) _Pragma("unroll") for (int k = 0; k < 2; ++k) dst[m][k] = *(const LAS h16x8*)(lds + G8_SA(b, h) + aoff + m * 2048 + k * 1024); } while (0)
; #define G8_LDB(dst, b, h) do { _Pragma("unroll") for (int n = 0; n < 2; ++n) _Pragma("unroll") for (int k = 0; k < 2; ++k) dst[n][k] = *(const LAS h16x8*)(lds + G8_SB(b, h) + boff + n * 2048 + k * 1024); } while (0)
; #define G8_MMA(ai, bj, At, Bt_) do { __builtin_amdgcn_s_setprio(1); _Pragma("unroll") for (int m = 0; m < 4; ++m) _Pragma("unroll") for (int n = 0; n < 2; ++n) _Pragma("unroll") for (int k = 0; k < 2; ++k) \
;     acc[ai][bj][m][n] = __builtin_amdgcn_mfma_f32_16x16x32_f16(Bt_[n][k], At[m][k], acc[ai][bj][m][n], 0, 0, 0); __builtin_amdgcn_s_setprio(0); } while (0)
; #define G8_WAIT_V(n) asm volatile("s_waitcnt vmcnt(" #n ")" ::: "memory")
; #define G8_WAIT_L(n) asm volatile("s_waitcnt lgkmcnt(" #n ")" ::: "memory")
; #define G8_BAR __builtin_amdgcn_s_barrier()
; #define G8_SCHED __builtin_amdgcn_sched_barrier(0)
; template <class Epi>
; __device__ __forceinline__ void gemm_phase(LAS unsigned char* lds, const h16* A, const h16* Bt, int K, const Order& S, const Epi& E) {
;     ...
;       G8_STAGE(G8_SB(0, 1), b2 + hstep);
;       G8_WAIT_V(6); G8_BAR; G8_MMA(1, 1, At, B1); G8_BAR;
;       G8_LDB(B0, 1, 0); G8_SCHED; G8_LDA(At, 1, 0); G8_STAGE(G8_SA(0, 1), a2 + hstep);
;       G8_WAIT_L(8); G8_BAR; G8_WAIT_L(0); G8_MMA(0, 0, At, B0); G8_BAR; G8_SCHED;
;       G8_LDB(B1, 1, 1); G8_STAGE(G8_SB(1, 0), b3);
	s_add_u32 s56, s26, 0x40000
	s_addc_u32 s57, s27, 0
	s_mov_b32 m0, s41
	v_lshl_add_u64 v[2:3], s[56:57], 0, v[134:135]
	global_load_lds_dwordx4 v[2:3], off
	v_lshl_add_u64 v[2:3], s[56:57], 0, v[132:133]
	s_mov_b32 m0, s42
	s_nop 0
	global_load_lds_dwordx4 v[2:3], off
	s_waitcnt vmcnt(6)
	s_barrier
	v_mfma_f32_16x16x32_f16 v[56:59], v[222:225], v[178:181], v[56:59]
	v_mfma_f32_16x16x32_f16 v[52:55], v[230:233], v[178:181], v[52:55]
	v_mfma_f32_16x16x32_f16 v[40:43], v[222:225], v[186:189], v[40:43]
	v_mfma_f32_16x16x32_f16 v[36:39], v[230:233], v[186:189], v[36:39]
	v_mfma_f32_16x16x32_f16 v[24:27], v[222:225], v[206:209], v[24:27]
	v_mfma_f32_16x16x32_f16 v[20:23], v[230:233], v[206:209], v[20:23]
	v_mfma_f32_16x16x32_f16 v[8:11], v[222:225], v[214:217], v[8:11]
	v_mfma_f32_16x16x32_f16 v[2:5], v[230:233], v[214:217], v[4:7]
	v_mfma_f32_16x16x32_f16 v[56:59], v[226:229], v[182:185], v[56:59]
	v_mfma_f32_16x16x32_f16 v[52:55], v[234:237], v[182:185], v[52:55]
	v_mfma_f32_16x16x32_f16 v[40:43], v[226:229], v[202:205], v[40:43]
	v_mfma_f32_16x16x32_f16 v[36:39], v[234:237], v[202:205], v[36:39]
	v_mfma_f32_16x16x32_f16 v[24:27], v[226:229], v[210:213], v[24:27]
	v_mfma_f32_16x16x32_f16 v[20:23], v[234:237], v[210:213], v[20:23]
	v_mfma_f32_16x16x32_f16 v[8:11], v[226:229], v[218:221], v[8:11]
	v_mfma_f32_16x16x32_f16 v[2:5], v[234:237], v[218:221], v[2:5]
	v_or_b32_e32 v0, 0x18000, v158
	s_barrier
	v_add_u32_e32 v6, 0x18400, v158
	ds_read_b128 v[162:165], v0
	ds_read_b128 v[166:169], v6
	v_add_u32_e32 v0, 0x18800, v158
	v_add_u32_e32 v6, 0x18c00, v158
	ds_read_b128 v[170:173], v0
	ds_read_b128 v[174:177], v6
	s_add_u32 s28, s28, 0x40000
	s_addc_u32 s29, s29, 0
	s_mov_b32 m0, s43
	v_lshl_add_u64 v[6:7], s[28:29], 0, v[134:135]
	ds_read_b128 v[178:181], v139 offset:32768
	ds_read_b128 v[182:185], v139 offset:33792
	ds_read_b128 v[186:189], v139 offset:34816
	ds_read_b128 v[202:205], v139 offset:35840
	ds_read_b128 v[206:209], v139 offset:36864
	ds_read_b128 v[210:213], v139 offset:37888
	ds_read_b128 v[214:217], v139 offset:38912
	ds_read_b128 v[218:221], v139 offset:39936
	global_load_lds_dwordx4 v[6:7], off
	v_lshl_add_u64 v[6:7], s[28:29], 0, v[132:133]
	s_mov_b32 m0, s44
	s_nop 0
	global_load_lds_dwordx4 v[6:7], off
	s_waitcnt lgkmcnt(8)
	s_barrier
	s_waitcnt lgkmcnt(0)
	s_waitcnt lgkmcnt(0)
	v_mfma_f32_16x16x32_f16 v[128:131], v[162:165], v[178:181], v[128:131]
	v_mfma_f32_16x16x32_f16 v[124:127], v[170:173], v[178:181], v[124:127]
	v_mfma_f32_16x16x32_f16 v[112:115], v[162:165], v[186:189], v[112:115]
	v_mfma_f32_16x16x32_f16 v[108:111], v[170:173], v[186:189], v[108:111]
	v_mfma_f32_16x16x32_f16 v[96:99], v[162:165], v[206:209], v[96:99]
	v_mfma_f32_16x16x32_f16 v[92:95], v[170:173], v[206:209], v[92:95]
	v_mfma_f32_16x16x32_f16 v[80:83], v[162:165], v[214:217], v[80:83]
	v_mfma_f32_16x16x32_f16 v[76:79], v[170:173], v[214:217], v[76:79]
	v_mfma_f32_16x16x32_f16 v[128:131], v[166:169], v[182:185], v[128:131]
	v_mfma_f32_16x16x32_f16 v[124:127], v[174:177], v[182:185], v[124:127]
	v_mfma_f32_16x16x32_f16 v[112:115], v[166:169], v[202:205], v[112:115]
	v_mfma_f32_16x16x32_f16 v[108:111], v[174:177], v[202:205], v[108:111]
	v_mfma_f32_16x16x32_f16 v[96:99], v[166:169], v[210:213], v[96:99]
	v_mfma_f32_16x16x32_f16 v[92:95], v[174:177], v[210:213], v[92:95]
	v_mfma_f32_16x16x32_f16 v[80:83], v[166:169], v[218:221], v[80:83]
	v_mfma_f32_16x16x32_f16 v[76:79], v[174:177], v[218:221], v[76:79]
	s_barrier
	v_or_b32_e32 v0, 0x1c000, v158
	v_add_u32_e32 v6, 0x1c400, v158
	ds_read_b128 v[222:225], v0
	ds_read_b128 v[226:229], v6
	v_add_u32_e32 v0, 0x1c800, v158
	v_add_u32_e32 v6, 0x1cc00, v158
	s_mov_b32 m0, s46
	ds_read_b128 v[230:233], v0
	ds_read_b128 v[234:237], v6
	v_lshl_add_u64 v[6:7], v[238:239], 0, s[94:95]
	global_load_lds_dwordx4 v[6:7], off
	v_lshl_add_u64 v[6:7], v[240:241], 0, s[94:95]
	s_mov_b32 m0, s47
	s_nop 0
	global_load_lds_dwordx4 v[6:7], off
	s_barrier
; #define G8_STAGE(bufoff, gbase) do { _Pragma("unroll") for (int _i = 0; _i < 2; ++_i) \
;     __builtin_amdgcn_global_load_lds((const unsigned*)((const char*)(gbase) + voffA[_i]), (LAS unsigned*)(lds + (bufoff) + ldsw + _i * 8192), 16, 0, 0); } while (0)
; #define G8_LDA(dst, b, h) do { _Pragma("unroll") for (int m = 0; m < 4; ++m) _Pragma("unroll") for (int k = 0; k < 2; ++k) dst[m][k] = *(const LAS h16x8*)(lds + G8_SA(b, h) + aoff + m * 2048 + k * 1024); } while (0)
; #define G8_MMA(ai, bj, At, Bt_) do { __builtin_amdgcn_s_setprio(1); _Pragma("unroll") for (int m = 0; m < 4; ++m) _Pragma("unroll") for (int n = 0; n < 2; ++n) _Pragma("unroll") for (int k = 0; k < 2; ++k) \
;     acc[ai][bj][m][n] = __builtin_amdgcn_mfma_f32_16x16x32_f16(Bt_[n][k], At[m][k], acc[ai][bj][m][n], 0, 0, 0); __builtin_amdgcn_s_setprio(0); } while (0)
; #define G8_WAIT_V(n) asm volatile("s_waitcnt vmcnt(" #n ")" ::: "memory")
; #define G8_WAIT_L(n) asm volatile("s_waitcnt lgkmcnt(" #n ")" ::: "memory")
; #define G8_BAR __builtin_amdgcn_s_barrier()
; #define G8_SCHED __builtin_amdgcn_sched_barrier(0)
; template <class Epi>
; __device__ __forceinline__ void gemm_phase(LAS unsigned char* lds, const h16* A, const h16* Bt, int K, const Order& S, const Epi& E) {
;     ...
;       G8_BAR; G8_WAIT_L(0); G8_MMA(0, 1, At, B1); G8_BAR;
;       G8_LDA(At, 1, 1); G8_STAGE(G8_SA(1, 0), a3);
;       G8_BAR; G8_WAIT_L(0); G8_MMA(1, 0, At, B0); G8_BAR; G8_SCHED;
;       G8_STAGE(G8_SB(1, 1), b3 + hstep);
;       G8_WAIT_V(6); G8_BAR; G8_MMA(1, 1, At, B1); G8_BAR;
;     }
	s_waitcnt lgkmcnt(0)
	s_waitcnt lgkmcnt(0)
	v_mfma_f32_16x16x32_f16 v[120:123], v[222:225], v[178:181], v[120:123]
	v_mfma_f32_16x16x32_f16 v[116:119], v[230:233], v[178:181], v[116:119]
	v_mfma_f32_16x16x32_f16 v[104:107], v[222:225], v[186:189], v[104:107]
	v_mfma_f32_16x16x32_f16 v[100:103], v[230:233], v[186:189], v[100:103]
	v_mfma_f32_16x16x32_f16 v[88:91], v[222:225], v[206:209], v[88:91]
	v_mfma_f32_16x16x32_f16 v[84:87], v[230:233], v[206:209], v[84:87]
	v_mfma_f32_16x16x32_f16 v[72:75], v[222:225], v[214:217], v[72:75]
	v_mfma_f32_16x16x32_f16 v[68:71], v[230:233], v[214:217], v[68:71]
	v_mfma_f32_16x16x32_f16 v[120:123], v[226:229], v[182:185], v[120:123]
	v_mfma_f32_16x16x32_f16 v[116:119], v[234:237], v[182:185], v[116:119]
	v_mfma_f32_16x16x32_f16 v[104:107], v[226:229], v[202:205], v[104:107]
	v_mfma_f32_16x16x32_f16 v[100:103], v[234:237], v[202:205], v[100:103]
	v_mfma_f32_16x16x32_f16 v[88:91], v[226:229], v[210:213], v[88:91]
	v_mfma_f32_16x16x32_f16 v[84:87], v[234:237], v[210:213], v[84:87]
	v_mfma_f32_16x16x32_f16 v[72:75], v[226:229], v[218:221], v[72:75]
	v_mfma_f32_16x16x32_f16 v[68:71], v[234:237], v[218:221], v[68:71]
	s_mov_b32 m0, s48
	v_lshl_add_u64 v[6:7], v[242:243], 0, s[94:95]
	s_barrier
	ds_read_b128 v[178:181], v139 offset:49152
	ds_read_b128 v[182:185], v139 offset:50176
	ds_read_b128 v[186:189], v139 offset:51200
	ds_read_b128 v[202:205], v139 offset:52224
	ds_read_b128 v[206:209], v139 offset:53248
	ds_read_b128 v[210:213], v139 offset:54272
	ds_read_b128 v[214:217], v139 offset:55296
	ds_read_b128 v[218:221], v139 offset:56320
	global_load_lds_dwordx4 v[6:7], off
	v_lshl_add_u64 v[6:7], v[244:245], 0, s[94:95]
	s_mov_b32 m0, s49
	s_nop 0
	global_load_lds_dwordx4 v[6:7], off
	s_barrier
	s_waitcnt lgkmcnt(0)
	s_waitcnt lgkmcnt(0)
	v_mfma_f32_16x16x32_f16 v[64:67], v[162:165], v[178:181], v[64:67]
	v_mfma_f32_16x16x32_f16 v[60:63], v[170:173], v[178:181], v[60:63]
	v_mfma_f32_16x16x32_f16 v[48:51], v[162:165], v[186:189], v[48:51]
	v_mfma_f32_16x16x32_f16 v[44:47], v[170:173], v[186:189], v[44:47]
	v_mfma_f32_16x16x32_f16 v[32:35], v[162:165], v[206:209], v[32:35]
	v_mfma_f32_16x16x32_f16 v[28:31], v[170:173], v[206:209], v[28:31]
	v_mfma_f32_16x16x32_f16 v[16:19], v[162:165], v[214:217], v[16:19]
	v_mfma_f32_16x16x32_f16 v[12:15], v[170:173], v[214:217], v[12:15]
	v_mfma_f32_16x16x32_f16 v[64:67], v[166:169], v[182:185], v[64:67]
	v_mfma_f32_16x16x32_f16 v[60:63], v[174:177], v[182:185], v[60:63]
	v_mfma_f32_16x16x32_f16 v[48:51], v[166:169], v[202:205], v[48:51]
	v_mfma_f32_16x16x32_f16 v[44:47], v[174:177], v[202:205], v[44:47]
	v_mfma_f32_16x16x32_f16 v[32:35], v[166:169], v[210:213], v[32:35]
	v_mfma_f32_16x16x32_f16 v[28:31], v[174:177], v[210:213], v[28:31]
	v_mfma_f32_16x16x32_f16 v[16:19], v[166:169], v[218:221], v[16:19]
	v_mfma_f32_16x16x32_f16 v[12:15], v[174:177], v[218:221], v[12:15]
	s_barrier
	s_add_u32 s26, s26, 0x40080
	s_addc_u32 s27, s27, 0
	s_mov_b32 m0, s50
	v_lshl_add_u64 v[6:7], s[26:27], 0, v[134:135]
	global_load_lds_dwordx4 v[6:7], off
	v_lshl_add_u64 v[6:7], s[26:27], 0, v[132:133]
	s_mov_b32 m0, s51
	s_nop 0
	global_load_lds_dwordx4 v[6:7], off
	s_waitcnt vmcnt(6)
	s_barrier
	v_mfma_f32_16x16x32_f16 v[56:59], v[222:225], v[178:181], v[56:59]
	v_mfma_f32_16x16x32_f16 v[52:55], v[230:233], v[178:181], v[52:55]
	v_mfma_f32_16x16x32_f16 v[40:43], v[222:225], v[186:189], v[40:43]
	v_mfma_f32_16x16x32_f16 v[36:39], v[230:233], v[186:189], v[36:39]
	v_mfma_f32_16x16x32_f16 v[24:27], v[222:225], v[206:209], v[24:27]
	v_mfma_f32_16x16x32_f16 v[20:23], v[230:233], v[206:209], v[20:23]
	v_mfma_f32_16x16x32_f16 v[6:9], v[222:225], v[214:217], v[8:11]
	v_mfma_f32_16x16x32_f16 v[2:5], v[230:233], v[214:217], v[2:5]
	v_mfma_f32_16x16x32_f16 v[56:59], v[226:229], v[182:185], v[56:59]
	v_mfma_f32_16x16x32_f16 v[52:55], v[234:237], v[182:185], v[52:55]
	v_mfma_f32_16x16x32_f16 v[40:43], v[226:229], v[202:205], v[40:43]
	v_mfma_f32_16x16x32_f16 v[36:39], v[234:237], v[202:205], v[36:39]
	v_mfma_f32_16x16x32_f16 v[24:27], v[226:229], v[210:213], v[24:27]
	v_mfma_f32_16x16x32_f16 v[20:23], v[234:237], v[210:213], v[20:23]
	v_mfma_f32_16x16x32_f16 v[8:11], v[226:229], v[218:221], v[6:9]
	v_mfma_f32_16x16x32_f16 v[4:7], v[234:237], v[218:221], v[2:5]
	s_add_i32 s55, s55, 2
	s_add_u32 s24, s24, 0x100
	s_addc_u32 s25, s25, 0
	s_cmp_gt_u32 s55, 13
	s_barrier
	s_cbranch_scc1 .LBB0_2381

; #define G8_STAGE(bufoff, gbase) do { _Pragma("unroll") for (int _i = 0; _i < 2; ++_i) \
;     __builtin_amdgcn_global_load_lds((const unsigned*)((const char*)(gbase) + voffA[_i]), (LAS unsigned*)(lds + (bufoff) + ldsw + _i * 8192), 16, 0, 0); } while (0)
; #define G8_LDA(dst, b, h) do { _Pragma("unroll") for (int m = 0; m < 4; ++m) _Pragma("unroll") for (int k = 0; k < 2; ++k) dst[m][k] = *(const LAS h16x8*)(lds + G8_SA(b, h) + aoff + m * 2048 + k * 1024); } while (0)
; #define G8_LDB(dst, b, h) do { _Pragma("unroll") for (int n = 0; n < 2; ++n) _Pragma("unroll") for (int k = 0; k < 2; ++k) dst[n][k] = *(const LAS h16x8*)(lds + G8_SB(b, h) + boff + n * 2048 + k * 1024); } while (0)
; #define G8_MMA(ai, bj, At, Bt_) do { __builtin_amdgcn_s_setprio(1); _Pragma("unroll") for (int m = 0; m < 4; ++m) _Pragma("unroll") for (int n = 0; n < 2; ++n) _Pragma("unroll") for (int k = 0; k < 2; ++k) \
;     acc[ai][bj][m][n] = __builtin_amdgcn_mfma_f32_16x16x32_f16(Bt_[n][k], At[m][k], acc[ai][bj][m][n], 0, 0, 0); __builtin_amdgcn_s_setprio(0); } while (0)
; #define G8_WAIT_L(n) asm volatile("s_waitcnt lgkmcnt(" #n ")" ::: "memory")
; #define G8_BAR __builtin_amdgcn_s_barrier()
; #define G8_SCHED __builtin_amdgcn_sched_barrier(0)
; template <class Epi>
; __device__ __forceinline__ void gemm_phase(LAS unsigned char* lds, const h16* A, const h16* Bt, int K, const Order& S, const Epi& E) {
;     ...
;       const bool last = (t == nt - 2);
;       const char* a1 = cA + (size_t)(t + 1) * kstep;
;       const char* a2 = last ? nA : cA + (size_t)(t + 2) * kstep;
;       const char* b2 = last ? nB : cB + (size_t)(t + 2) * kstep;
;       const char* a3 = a2 + kstep;
;       const char* b3 = b2 + kstep;
;       if (Epi::MID_T >= 0 && t == Epi::MID_T) E.mid(acc, ui, wr, fr);
;       G8_LDB(B0, 0, 0); G8_SCHED; G8_LDA(At, 0, 0); G8_STAGE(G8_SA(1, 1), a1 + hstep);
;       G8_WAIT_L(8); G8_BAR; G8_WAIT_L(0); G8_MMA(0, 0, At, B0); G8_BAR; G8_SCHED;
;       G8_LDB(B1, 0, 1); G8_STAGE(G8_SB(0, 0), b2);
;       G8_BAR; G8_WAIT_L(0); G8_MMA(0, 1, At, B1); G8_BAR;
;       G8_LDA(At, 0, 1); G8_STAGE(G8_SA(0, 0), a2);
;       G8_BAR; G8_WAIT_L(0); G8_MMA(1, 0, At, B0); G8_BAR; G8_SCHED;
.LBB0_2473:
	s_add_u32 s20, s18, 0xfffc0080
	s_addc_u32 s21, s19, -1
	s_cmp_eq_u32 s51, 12
	s_cselect_b32 s23, s13, s21
	s_cselect_b32 s22, s47, s20
	s_cselect_b32 s21, s11, s50
	s_cselect_b32 s20, s48, s49
	v_lshl_add_u64 v[188:189], s[18:19], 0, v[134:135]
	s_add_i32 m0, s27, 0xc000
	ds_read_b128 v[176:179], v139
	ds_read_b128 v[180:183], v139 offset:1024
	ds_read_b128 v[184:187], v139 offset:2048
	ds_read_b128 v[202:205], v139 offset:3072
	ds_read_b128 v[206:209], v139 offset:4096
	ds_read_b128 v[210:213], v139 offset:5120
	ds_read_b128 v[214:217], v139 offset:6144
	ds_read_b128 v[218:221], v139 offset:7168
	global_load_lds_dwordx4 v[188:189], off
	v_lshl_add_u64 v[188:189], s[18:19], 0, v[136:137]
	s_add_i32 m0, s27, 0xe000
	s_nop 0
	global_load_lds_dwordx4 v[188:189], off
	s_waitcnt lgkmcnt(8)
	s_barrier
	s_waitcnt lgkmcnt(0)
	s_waitcnt lgkmcnt(0)
	v_mfma_f32_16x16x32_f16 v[126:129], v[160:163], v[176:179], v[126:129]
	v_mfma_f32_16x16x32_f16 v[122:125], v[168:171], v[176:179], v[122:125]
	v_mfma_f32_16x16x32_f16 v[110:113], v[160:163], v[184:187], v[110:113]
	v_mfma_f32_16x16x32_f16 v[106:109], v[168:171], v[184:187], v[106:109]
	v_mfma_f32_16x16x32_f16 v[94:97], v[160:163], v[206:209], v[94:97]
	v_mfma_f32_16x16x32_f16 v[90:93], v[168:171], v[206:209], v[90:93]
	v_mfma_f32_16x16x32_f16 v[78:81], v[160:163], v[214:217], v[78:81]
	v_mfma_f32_16x16x32_f16 v[74:77], v[168:171], v[214:217], v[74:77]
	v_mfma_f32_16x16x32_f16 v[126:129], v[164:167], v[180:183], v[126:129]
	v_mfma_f32_16x16x32_f16 v[122:125], v[172:175], v[180:183], v[122:125]
	v_mfma_f32_16x16x32_f16 v[110:113], v[164:167], v[202:205], v[110:113]
	v_mfma_f32_16x16x32_f16 v[106:109], v[172:175], v[202:205], v[106:109]
	v_mfma_f32_16x16x32_f16 v[94:97], v[164:167], v[210:213], v[94:97]
	v_mfma_f32_16x16x32_f16 v[90:93], v[172:175], v[210:213], v[90:93]
	v_mfma_f32_16x16x32_f16 v[78:81], v[164:167], v[218:221], v[78:81]
	v_mfma_f32_16x16x32_f16 v[74:77], v[172:175], v[218:221], v[74:77]
	s_barrier
	v_or_b32_e32 v159, 0x14000, v140
	v_add_u32_e32 v188, 0x14400, v140
	ds_read_b128 v[222:225], v159
	ds_read_b128 v[226:229], v188
	v_add_u32_e32 v159, 0x14800, v140
	v_add_u32_e32 v188, 0x14c00, v140
	s_mov_b32 m0, s28
	ds_read_b128 v[230:233], v159
	ds_read_b128 v[234:237], v188
	v_lshl_add_u64 v[188:189], s[20:21], 0, v[132:133]
	global_load_lds_dwordx4 v[188:189], off
	v_lshl_add_u64 v[238:239], s[20:21], 0, v[130:131]
	s_mov_b32 m0, s29
	s_nop 0
	global_load_lds_dwordx4 v[238:239], off
	s_barrier
	s_waitcnt lgkmcnt(0)
	s_waitcnt lgkmcnt(0)
	v_mfma_f32_16x16x32_f16 v[118:121], v[222:225], v[176:179], v[118:121]
	v_mfma_f32_16x16x32_f16 v[114:117], v[230:233], v[176:179], v[114:117]
	v_mfma_f32_16x16x32_f16 v[102:105], v[222:225], v[184:187], v[102:105]
	v_mfma_f32_16x16x32_f16 v[98:101], v[230:233], v[184:187], v[98:101]
	v_mfma_f32_16x16x32_f16 v[86:89], v[222:225], v[206:209], v[86:89]
	v_mfma_f32_16x16x32_f16 v[82:85], v[230:233], v[206:209], v[82:85]
	v_mfma_f32_16x16x32_f16 v[70:73], v[222:225], v[214:217], v[70:73]
	v_mfma_f32_16x16x32_f16 v[66:69], v[230:233], v[214:217], v[66:69]
	v_mfma_f32_16x16x32_f16 v[118:121], v[226:229], v[180:183], v[118:121]
	v_mfma_f32_16x16x32_f16 v[114:117], v[234:237], v[180:183], v[114:117]
	v_mfma_f32_16x16x32_f16 v[102:105], v[226:229], v[202:205], v[102:105]
	v_mfma_f32_16x16x32_f16 v[98:101], v[234:237], v[202:205], v[98:101]
	v_mfma_f32_16x16x32_f16 v[86:89], v[226:229], v[210:213], v[86:89]
	v_mfma_f32_16x16x32_f16 v[82:85], v[234:237], v[210:213], v[82:85]
	v_mfma_f32_16x16x32_f16 v[70:73], v[226:229], v[218:221], v[70:73]
	v_mfma_f32_16x16x32_f16 v[66:69], v[234:237], v[218:221], v[66:69]
	s_mov_b32 m0, s27
	v_lshl_add_u64 v[240:241], s[22:23], 0, v[132:133]
	s_barrier
	ds_read_b128 v[176:179], v139 offset:16384
	ds_read_b128 v[180:183], v139 offset:17408
	ds_read_b128 v[184:187], v139 offset:18432
	ds_read_b128 v[202:205], v139 offset:19456
	ds_read_b128 v[206:209], v139 offset:20480
	ds_read_b128 v[210:213], v139 offset:21504
	ds_read_b128 v[214:217], v139 offset:22528
	ds_read_b128 v[218:221], v139 offset:23552
	global_load_lds_dwordx4 v[240:241], off
	v_lshl_add_u64 v[242:243], s[22:23], 0, v[130:131]
	s_mov_b32 m0, s30
	s_nop 0
	global_load_lds_dwordx4 v[242:243], off
	s_waitcnt vmcnt(10)
	s_barrier
	s_waitcnt lgkmcnt(0)
	s_waitcnt lgkmcnt(0)
	v_mfma_f32_16x16x32_f16 v[62:65], v[160:163], v[176:179], v[62:65]
	v_mfma_f32_16x16x32_f16 v[58:61], v[168:171], v[176:179], v[58:61]
	v_mfma_f32_16x16x32_f16 v[46:49], v[160:163], v[184:187], v[46:49]
	v_mfma_f32_16x16x32_f16 v[42:45], v[168:171], v[184:187], v[42:45]
	v_mfma_f32_16x16x32_f16 v[30:33], v[160:163], v[206:209], v[30:33]
	v_mfma_f32_16x16x32_f16 v[26:29], v[168:171], v[206:209], v[26:29]
	v_mfma_f32_16x16x32_f16 v[14:17], v[160:163], v[214:217], v[14:17]
	v_mfma_f32_16x16x32_f16 v[10:13], v[168:171], v[214:217], v[10:13]
	v_mfma_f32_16x16x32_f16 v[62:65], v[164:167], v[180:183], v[62:65]
	v_mfma_f32_16x16x32_f16 v[58:61], v[172:175], v[180:183], v[58:61]
	v_mfma_f32_16x16x32_f16 v[46:49], v[164:167], v[202:205], v[46:49]
	v_mfma_f32_16x16x32_f16 v[42:45], v[172:175], v[202:205], v[42:45]
	v_mfma_f32_16x16x32_f16 v[30:33], v[164:167], v[210:213], v[30:33]
	v_mfma_f32_16x16x32_f16 v[26:29], v[172:175], v[210:213], v[26:29]
	v_mfma_f32_16x16x32_f16 v[14:17], v[164:167], v[218:221], v[14:17]
	v_mfma_f32_16x16x32_f16 v[10:13], v[172:175], v[218:221], v[10:13]
	s_barrier
; #define G8_STAGE(bufoff, gbase) do { _Pragma("unroll") for (int _i = 0; _i < 2; ++_i) \
;     __builtin_amdgcn_global_load_lds((const unsigned*)((const char*)(gbase) + voffA[_i]), (LAS unsigned*)(lds + (bufoff) + ldsw + _i * 8192), 16, 0, 0); } while (0)
; #define G8_LDA(dst, b, h) do { _Pragma("unroll") for (int m = 0; m < 4; ++m) _Pragma("unroll") for (int k = 0; k < 2; ++k) dst[m][k] = *(const LAS h16x8*)(lds + G8_SA(b, h) + aoff + m * 2048 + k * 1024); } while (0)
; #define G8_LDB(dst, b, h) do { _Pragma("unroll") for (int n = 0; n < 2; ++n) _Pragma("unroll") for (int k = 0; k < 2; ++k) dst[n][k] = *(const LAS h16x8*)(lds + G8_SB(b, h) + boff + n * 2048 + k * 1024); } while (0)
; #define G8_MMA(ai, bj, At, Bt_) do { __builtin_amdgcn_s_setprio(1); _Pragma("unroll") for (int m = 0; m < 4; ++m) _Pragma("unroll") for (int n = 0; n < 2; ++n) _Pragma("unroll") for (int k = 0; k < 2; ++k) \
;     acc[ai][bj][m][n] = __builtin_amdgcn_mfma_f32_16x16x32_f16(Bt_[n][k], At[m][k], acc[ai][bj][m][n], 0, 0, 0); __builtin_amdgcn_s_setprio(0); } while (0)
; #define G8_WAIT_V(n) asm volatile("s_waitcnt vmcnt(" #n ")" ::: "memory")
; #define G8_WAIT_L(n) asm volatile("s_waitcnt lgkmcnt(" #n ")" ::: "memory")
; #define G8_BAR __builtin_amdgcn_s_barrier()
; #define G8_SCHED __builtin_amdgcn_sched_barrier(0)
; template <class Epi>
; __device__ __forceinline__ void gemm_phase(LAS unsigned char* lds, const h16* A, const h16* Bt, int K, const Order& S, const Epi& E) {
;     ...
;       G8_STAGE(G8_SB(0, 1), b2 + hstep);
;       G8_WAIT_V(6); G8_BAR; G8_MMA(1, 1, At, B1); G8_BAR;
;       G8_LDB(B0, 1, 0); G8_SCHED; G8_LDA(At, 1, 0); G8_STAGE(G8_SA(0, 1), a2 + hstep);
;       G8_WAIT_L(8); G8_BAR; G8_WAIT_L(0); G8_MMA(0, 0, At, B0); G8_BAR; G8_SCHED;
;       G8_LDB(B1, 1, 1); G8_STAGE(G8_SB(1, 0), b3);
;       G8_BAR; G8_WAIT_L(0); G8_MMA(0, 1, At, B1); G8_BAR;
;       G8_LDA(At, 1, 1); G8_STAGE(G8_SA(1, 0), a3);
	s_add_u32 s52, s20, 0x40000
	s_addc_u32 s53, s21, 0
	s_mov_b32 m0, s31
	v_lshl_add_u64 v[160:161], s[52:53], 0, v[132:133]
	global_load_lds_dwordx4 v[160:161], off
	v_lshl_add_u64 v[160:161], s[52:53], 0, v[130:131]
	s_mov_b32 m0, s34
	s_nop 0
	global_load_lds_dwordx4 v[160:161], off
	v_or_b32_e32 v159, 0x18000, v140
	v_add_u32_e32 v164, 0x18400, v140
	ds_read_b128 v[160:163], v159
	ds_read_b128 v[164:167], v164
	v_add_u32_e32 v159, 0x18800, v140
	v_add_u32_e32 v172, 0x18c00, v140
	ds_read_b128 v[168:171], v159
	ds_read_b128 v[172:175], v172
	s_waitcnt vmcnt(6)
	s_barrier
	v_mfma_f32_16x16x32_f16 v[54:57], v[222:225], v[176:179], v[54:57]
	v_mfma_f32_16x16x32_f16 v[50:53], v[230:233], v[176:179], v[50:53]
	v_mfma_f32_16x16x32_f16 v[38:41], v[222:225], v[184:187], v[38:41]
	v_mfma_f32_16x16x32_f16 v[34:37], v[230:233], v[184:187], v[34:37]
	v_mfma_f32_16x16x32_f16 v[22:25], v[222:225], v[206:209], v[22:25]
	v_mfma_f32_16x16x32_f16 v[18:21], v[230:233], v[206:209], v[18:21]
	v_mfma_f32_16x16x32_f16 v[6:9], v[222:225], v[214:217], v[6:9]
	v_mfma_f32_16x16x32_f16 v[2:5], v[230:233], v[214:217], v[2:5]
	v_mfma_f32_16x16x32_f16 v[54:57], v[226:229], v[180:183], v[54:57]
	v_mfma_f32_16x16x32_f16 v[50:53], v[234:237], v[180:183], v[50:53]
	v_mfma_f32_16x16x32_f16 v[38:41], v[226:229], v[202:205], v[38:41]
	v_mfma_f32_16x16x32_f16 v[34:37], v[234:237], v[202:205], v[34:37]
	v_mfma_f32_16x16x32_f16 v[22:25], v[226:229], v[210:213], v[22:25]
	v_mfma_f32_16x16x32_f16 v[18:21], v[234:237], v[210:213], v[18:21]
	v_mfma_f32_16x16x32_f16 v[6:9], v[226:229], v[218:221], v[6:9]
	v_mfma_f32_16x16x32_f16 v[2:5], v[234:237], v[218:221], v[2:5]
	s_barrier
	s_add_u32 s22, s22, 0x40000
	s_addc_u32 s23, s23, 0
	s_mov_b32 m0, s35
	v_lshl_add_u64 v[222:223], s[22:23], 0, v[132:133]
	ds_read_b128 v[176:179], v139 offset:32768
	ds_read_b128 v[180:183], v139 offset:33792
	ds_read_b128 v[184:187], v139 offset:34816
	ds_read_b128 v[202:205], v139 offset:35840
	ds_read_b128 v[206:209], v139 offset:36864
	ds_read_b128 v[210:213], v139 offset:37888
	ds_read_b128 v[214:217], v139 offset:38912
	ds_read_b128 v[218:221], v139 offset:39936
	global_load_lds_dwordx4 v[222:223], off
	v_lshl_add_u64 v[222:223], s[22:23], 0, v[130:131]
	s_mov_b32 m0, s36
	s_nop 0
	global_load_lds_dwordx4 v[222:223], off
	s_waitcnt lgkmcnt(8)
	s_barrier
	s_waitcnt lgkmcnt(0)
	s_waitcnt lgkmcnt(0)
	v_mfma_f32_16x16x32_f16 v[126:129], v[160:163], v[176:179], v[126:129]
	v_mfma_f32_16x16x32_f16 v[122:125], v[168:171], v[176:179], v[122:125]
	v_mfma_f32_16x16x32_f16 v[110:113], v[160:163], v[184:187], v[110:113]
	v_mfma_f32_16x16x32_f16 v[106:109], v[168:171], v[184:187], v[106:109]
	v_mfma_f32_16x16x32_f16 v[94:97], v[160:163], v[206:209], v[94:97]
	v_mfma_f32_16x16x32_f16 v[90:93], v[168:171], v[206:209], v[90:93]
	v_mfma_f32_16x16x32_f16 v[78:81], v[160:163], v[214:217], v[78:81]
	v_mfma_f32_16x16x32_f16 v[74:77], v[168:171], v[214:217], v[74:77]
	v_mfma_f32_16x16x32_f16 v[126:129], v[164:167], v[180:183], v[126:129]
	v_mfma_f32_16x16x32_f16 v[122:125], v[172:175], v[180:183], v[122:125]
	v_mfma_f32_16x16x32_f16 v[110:113], v[164:167], v[202:205], v[110:113]
	v_mfma_f32_16x16x32_f16 v[106:109], v[172:175], v[202:205], v[106:109]
	v_mfma_f32_16x16x32_f16 v[94:97], v[164:167], v[210:213], v[94:97]
	v_mfma_f32_16x16x32_f16 v[90:93], v[172:175], v[210:213], v[90:93]
	v_mfma_f32_16x16x32_f16 v[78:81], v[164:167], v[218:221], v[78:81]
	v_mfma_f32_16x16x32_f16 v[74:77], v[172:175], v[218:221], v[74:77]
	s_barrier
	v_or_b32_e32 v159, 0x1c000, v140
	s_mov_b32 m0, s37
	v_add_u32_e32 v195, 0x1c400, v140
	ds_read_b128 v[222:225], v159
	ds_read_b128 v[226:229], v195
	v_add_u32_e32 v159, 0x1c800, v140
	v_lshl_add_u64 v[188:189], v[188:189], 0, s[94:95]
	v_add_u32_e32 v195, 0x1cc00, v140
	ds_read_b128 v[230:233], v159
	ds_read_b128 v[234:237], v195
	global_load_lds_dwordx4 v[188:189], off
	v_lshl_add_u64 v[188:189], v[238:239], 0, s[94:95]
	s_mov_b32 m0, s38
	s_nop 0
	global_load_lds_dwordx4 v[188:189], off
	s_barrier
	s_waitcnt lgkmcnt(0)
	s_waitcnt lgkmcnt(0)
	v_mfma_f32_16x16x32_f16 v[118:121], v[222:225], v[176:179], v[118:121]
	v_mfma_f32_16x16x32_f16 v[114:117], v[230:233], v[176:179], v[114:117]
	v_mfma_f32_16x16x32_f16 v[102:105], v[222:225], v[184:187], v[102:105]
	v_mfma_f32_16x16x32_f16 v[98:101], v[230:233], v[184:187], v[98:101]
	v_mfma_f32_16x16x32_f16 v[86:89], v[222:225], v[206:209], v[86:89]
	v_mfma_f32_16x16x32_f16 v[82:85], v[230:233], v[206:209], v[82:85]
	v_mfma_f32_16x16x32_f16 v[70:73], v[222:225], v[214:217], v[70:73]
	v_mfma_f32_16x16x32_f16 v[66:69], v[230:233], v[214:217], v[66:69]
	v_mfma_f32_16x16x32_f16 v[118:121], v[226:229], v[180:183], v[118:121]
	v_mfma_f32_16x16x32_f16 v[114:117], v[234:237], v[180:183], v[114:117]
	v_mfma_f32_16x16x32_f16 v[102:105], v[226:229], v[202:205], v[102:105]
	v_mfma_f32_16x16x32_f16 v[98:101], v[234:237], v[202:205], v[98:101]
	v_mfma_f32_16x16x32_f16 v[86:89], v[226:229], v[210:213], v[86:89]
	v_mfma_f32_16x16x32_f16 v[82:85], v[234:237], v[210:213], v[82:85]
	v_mfma_f32_16x16x32_f16 v[70:73], v[226:229], v[218:221], v[70:73]
	v_mfma_f32_16x16x32_f16 v[66:69], v[234:237], v[218:221], v[66:69]
	s_mov_b32 m0, s39
	v_lshl_add_u64 v[188:189], v[240:241], 0, s[94:95]
	s_barrier
	ds_read_b128 v[176:179], v139 offset:49152
	ds_read_b128 v[180:183], v139 offset:50176
	ds_read_b128 v[184:187], v139 offset:51200
	ds_read_b128 v[202:205], v139 offset:52224
	ds_read_b128 v[206:209], v139 offset:53248
	ds_read_b128 v[210:213], v139 offset:54272
	ds_read_b128 v[214:217], v139 offset:55296
	ds_read_b128 v[218:221], v139 offset:56320
	global_load_lds_dwordx4 v[188:189], off
	v_lshl_add_u64 v[188:189], v[242:243], 0, s[94:95]
	s_mov_b32 m0, s40
	s_nop 0
	global_load_lds_dwordx4 v[188:189], off
	s_waitcnt vmcnt(10)
	s_barrier
; #define G8_STAGE(bufoff, gbase) do { _Pragma("unroll") for (int _i = 0; _i < 2; ++_i) \
;     __builtin_amdgcn_global_load_lds((const unsigned*)((const char*)(gbase) + voffA[_i]), (LAS unsigned*)(lds + (bufoff) + ldsw + _i * 8192), 16, 0, 0); } while (0)
; #define G8_MMA(ai, bj, At, Bt_) do { __builtin_amdgcn_s_setprio(1); _Pragma("unroll") for (int m = 0; m < 4; ++m) _Pragma("unroll") for (int n = 0; n < 2; ++n) _Pragma("unroll") for (int k = 0; k < 2; ++k) \
;     acc[ai][bj][m][n] = __builtin_amdgcn_mfma_f32_16x16x32_f16(Bt_[n][k], At[m][k], acc[ai][bj][m][n], 0, 0, 0); __builtin_amdgcn_s_setprio(0); } while (0)
; #define G8_WAIT_V(n) asm volatile("s_waitcnt vmcnt(" #n ")" ::: "memory")
; #define G8_WAIT_L(n) asm volatile("s_waitcnt lgkmcnt(" #n ")" ::: "memory")
; #define G8_BAR __builtin_amdgcn_s_barrier()
; #define G8_SCHED __builtin_amdgcn_sched_barrier(0)
; template <class Epi>
; __device__ __forceinline__ void gemm_phase(LAS unsigned char* lds, const h16* A, const h16* Bt, int K, const Order& S, const Epi& E) {
;     ...
;       G8_BAR; G8_WAIT_L(0); G8_MMA(1, 0, At, B0); G8_BAR; G8_SCHED;
;       G8_STAGE(G8_SB(1, 1), b3 + hstep);
;       G8_WAIT_V(6); G8_BAR; G8_MMA(1, 1, At, B1); G8_BAR;
;     }
;   __device__ __forceinline__ void operator()(const f32x4 (&acc)[2][2][4][2], const g8::Unit& u, int ui, int wr, int wc, int fr, int fq) const {
; #pragma unroll
;     for (int ai = 0; ai < 2; ++ai)
; #pragma unroll
;       for (int m = 0; m < 4; ++m) {
;         const int rl = 128 * ai + 64 * wr + 16 * m + fr;
;         const float r = rsl[ui * 256 + rl];
;         h16* rowp = hid + (size_t)(u.pm * 256 + rl) * DFF + 256 * u.pn + 32 * wc + 8 * fq;
; #pragma unroll
;         for (int bj = 0; bj < 2; ++bj) {
;           f32x4 v[2];
; #pragma unroll
;           for (int n = 0; n < 2; ++n) {
;             v[n] = acc[ai][bj][m][n] * r;
; #pragma unroll
;             for (int j = 0; j < 4; ++j) { const float t = fmaxf(v[n][j], 0.f); v[n][j] = t * t; }
;           }
;           __builtin_nontemporal_store(pack8(v[0], v[1]), (h16x8*)(rowp + 128 * bj));
	s_waitcnt lgkmcnt(0)
	s_waitcnt lgkmcnt(0)
	v_mfma_f32_16x16x32_f16 v[62:65], v[160:163], v[176:179], v[62:65]
	v_mfma_f32_16x16x32_f16 v[58:61], v[168:171], v[176:179], v[58:61]
	v_mfma_f32_16x16x32_f16 v[46:49], v[160:163], v[184:187], v[46:49]
	v_mfma_f32_16x16x32_f16 v[42:45], v[168:171], v[184:187], v[42:45]
	v_mfma_f32_16x16x32_f16 v[30:33], v[160:163], v[206:209], v[30:33]
	v_mfma_f32_16x16x32_f16 v[26:29], v[168:171], v[206:209], v[26:29]
	v_mfma_f32_16x16x32_f16 v[14:17], v[160:163], v[214:217], v[14:17]
	v_mfma_f32_16x16x32_f16 v[10:13], v[168:171], v[214:217], v[10:13]
	v_mfma_f32_16x16x32_f16 v[62:65], v[164:167], v[180:183], v[62:65]
	v_mfma_f32_16x16x32_f16 v[58:61], v[172:175], v[180:183], v[58:61]
	v_mfma_f32_16x16x32_f16 v[46:49], v[164:167], v[202:205], v[46:49]
	v_mfma_f32_16x16x32_f16 v[42:45], v[172:175], v[202:205], v[42:45]
	v_mfma_f32_16x16x32_f16 v[30:33], v[164:167], v[210:213], v[30:33]
	v_mfma_f32_16x16x32_f16 v[26:29], v[172:175], v[210:213], v[26:29]
	v_mfma_f32_16x16x32_f16 v[14:17], v[164:167], v[218:221], v[14:17]
	v_mfma_f32_16x16x32_f16 v[10:13], v[172:175], v[218:221], v[10:13]
	s_barrier
	s_add_u32 s20, s20, 0x40080
	s_addc_u32 s21, s21, 0
	s_mov_b32 m0, s41
	v_lshl_add_u64 v[160:161], s[20:21], 0, v[132:133]
	global_load_lds_dwordx4 v[160:161], off
	v_lshl_add_u64 v[160:161], s[20:21], 0, v[130:131]
	s_mov_b32 m0, s42
	s_nop 0
	global_load_lds_dwordx4 v[160:161], off
	v_or_b32_e32 v159, 0x10000, v140
	v_add_u32_e32 v164, 0x10400, v140
	ds_read_b128 v[160:163], v159
	ds_read_b128 v[164:167], v164
	v_add_u32_e32 v159, 0x10800, v140
	v_add_u32_e32 v172, 0x10c00, v140
	ds_read_b128 v[168:171], v159
	ds_read_b128 v[172:175], v172
	s_waitcnt vmcnt(6)
	s_barrier
	v_mfma_f32_16x16x32_f16 v[54:57], v[222:225], v[176:179], v[54:57]
	v_mfma_f32_16x16x32_f16 v[50:53], v[230:233], v[176:179], v[50:53]
	v_mfma_f32_16x16x32_f16 v[38:41], v[222:225], v[184:187], v[38:41]
	v_mfma_f32_16x16x32_f16 v[34:37], v[230:233], v[184:187], v[34:37]
	v_mfma_f32_16x16x32_f16 v[22:25], v[222:225], v[206:209], v[22:25]
	v_mfma_f32_16x16x32_f16 v[18:21], v[230:233], v[206:209], v[18:21]
	v_mfma_f32_16x16x32_f16 v[6:9], v[222:225], v[214:217], v[6:9]
	v_mfma_f32_16x16x32_f16 v[2:5], v[230:233], v[214:217], v[2:5]
	v_mfma_f32_16x16x32_f16 v[54:57], v[226:229], v[180:183], v[54:57]
	v_mfma_f32_16x16x32_f16 v[50:53], v[234:237], v[180:183], v[50:53]
	v_mfma_f32_16x16x32_f16 v[38:41], v[226:229], v[202:205], v[38:41]
	v_mfma_f32_16x16x32_f16 v[34:37], v[234:237], v[202:205], v[34:37]
	v_mfma_f32_16x16x32_f16 v[22:25], v[226:229], v[210:213], v[22:25]
	v_mfma_f32_16x16x32_f16 v[18:21], v[234:237], v[210:213], v[18:21]
	v_mfma_f32_16x16x32_f16 v[6:9], v[226:229], v[218:221], v[6:9]
	v_mfma_f32_16x16x32_f16 v[2:5], v[234:237], v[218:221], v[2:5]
	s_add_i32 s51, s51, 2
	s_add_u32 s18, s18, 0x100
	s_addc_u32 s19, s19, 0
	s_add_u32 s49, s49, 0x100
	s_addc_u32 s50, s50, 0
	s_cmp_gt_u32 s51, 13
	s_barrier
	s_cbranch_scc0 .LBB0_2473
	s_waitcnt lgkmcnt(0)
	v_lshl_add_u32 v159, s44, 10, v158
	s_waitcnt vmcnt(0)
	ds_read2_b32 v[160:161], v159 offset1:16
	s_lshl_b32 s11, s46, 8
	v_add_u32_e32 v162, s11, v138
	s_lshl_b32 s18, s45, 8
	v_ashrrev_i32_e32 v163, 31, v162
	s_waitcnt lgkmcnt(0)
	v_pk_mul_f32 v[128:129], v[128:129], v[160:161] op_sel_hi:[1,0]
	v_pk_mul_f32 v[126:127], v[126:127], v[160:161] op_sel_hi:[1,0]
	v_pk_mul_f32 v[122:123], v[122:123], v[160:161] op_sel_hi:[1,0]
	v_max_f32_e32 v166, 0, v126
	v_max_f32_e32 v126, 0, v127
	v_max_f32_e32 v127, 0, v128
	v_max_f32_e32 v128, 0, v129
	v_pk_mul_f32 v[124:125], v[124:125], v[160:161] op_sel_hi:[1,0]
	v_max_f32_e32 v129, 0, v122
	v_max_f32_e32 v164, 0, v123
	v_pk_mul_f32 v[122:123], v[126:127], v[126:127]
	v_max_f32_e32 v165, 0, v124
	v_fma_mixlo_f16 v124, v166, v166, 0
	v_cvt_pk_f16_f32 v123, v122, v123
	s_ashr_i32 s19, s18, 31
	v_lshlrev_b64 v[162:163], 13, v[162:163]
	v_max_f32_e32 v167, 0, v125
	v_pack_b32_f16 v122, v124, v123
	v_pk_mul_f32 v[124:125], v[128:129], v[128:129]
	v_lshl_add_u64 v[162:163], s[0:1], 0, v[162:163]
	s_lshl_b64 s[18:19], s[18:19], 1
	v_cvt_pk_f16_f32 v126, v124, v125
	v_pk_mul_f32 v[124:125], v[164:165], v[164:165]
	v_lshl_add_u64 v[162:163], v[162:163], 0, s[18:19]
	v_cvt_pk_f16_f32 v125, v124, v125
	v_lshl_add_u64 v[162:163], v[162:163], 0, s[92:93]
	v_alignbit_b32 v124, v125, v126, 16
	v_lshrrev_b32_e32 v125, 16, v125
	v_lshl_add_u64 v[162:163], v[162:163], 0, v[0:1]
	v_alignbit_b32 v123, v126, v123, 16
	v_fma_mixhi_f16 v125, v167, v167, 0
	v_pk_mul_f32 v[120:121], v[120:121], v[160:161] op_sel_hi:[1,0]
	v_pk_mul_f32 v[118:119], v[118:119], v[160:161] op_sel_hi:[1,0]
	global_store_dwordx4 v[162:163], v[122:125], off nt
	v_pk_mul_f32 v[114:115], v[114:115], v[160:161] op_sel_hi:[1,0]
	v_pk_mul_f32 v[116:117], v[116:117], v[160:161] op_sel_hi:[1,0]
	v_max_f32_e32 v124, 0, v118
	v_max_f32_e32 v118, 0, v119
	v_max_f32_e32 v119, 0, v120
	v_max_f32_e32 v120, 0, v121
	v_max_f32_e32 v121, 0, v114
	v_max_f32_e32 v122, 0, v115
	v_pk_mul_f32 v[114:115], v[118:119], v[118:119]
	v_max_f32_e32 v123, 0, v116
	v_fma_mixlo_f16 v116, v124, v124, 0
	v_cvt_pk_f16_f32 v115, v114, v115
	v_max_f32_e32 v125, 0, v117
	v_pack_b32_f16 v114, v116, v115
	v_pk_mul_f32 v[116:117], v[120:121], v[120:121]
	s_and_b64 vcc, exec, s[6:7]
	v_cvt_pk_f16_f32 v118, v116, v117
	v_pk_mul_f32 v[116:117], v[122:123], v[122:123]
	v_alignbit_b32 v115, v118, v115, 16
	v_cvt_pk_f16_f32 v117, v116, v117
	v_alignbit_b32 v116, v117, v118, 16
	v_lshrrev_b32_e32 v117, 16, v117
	v_fma_mixhi_f16 v117, v125, v125, 0
	global_store_dwordx4 v[162:163], v[114:117], off offset:256 nt
	s_mov_b32 s45, s10
	s_mov_b32 s46, s12
;   __device__ __forceinline__ void operator()(const f32x4 (&acc)[2][2][4][2], const g8::Unit& u, int ui, int wr, int wc, int fr, int fq) const {
; #pragma unroll
;     for (int ai = 0; ai < 2; ++ai)
; #pragma unroll
;       for (int m = 0; m < 4; ++m) {
;         const int rl = 128 * ai + 64 * wr + 16 * m + fr;
;         const float r = rsl[ui * 256 + rl];
;         h16* rowp = hid + (size_t)(u.pm * 256 + rl) * DFF + 256 * u.pn + 32 * wc + 8 * fq;
; #pragma unroll
;         for (int bj = 0; bj < 2; ++bj) {
;           f32x4 v[2];
; #pragma unroll
;           for (int n = 0; n < 2; ++n) {
;             v[n] = acc[ai][bj][m][n] * r;
; #pragma unroll
;             for (int j = 0; j < 4; ++j) { const float t = fmaxf(v[n][j], 0.f); v[n][j] = t * t; }
;           }
;           __builtin_nontemporal_store(pack8(v[0], v[1]), (h16x8*)(rowp + 128 * bj));
	v_mov_b32_e32 v116, v161
	v_pk_mul_f32 v[110:111], v[110:111], v[116:117] op_sel_hi:[1,0]
	v_pk_mul_f32 v[112:113], v[112:113], v[116:117] op_sel_hi:[1,0]
	v_max_f32_e32 v117, 0, v110
	v_max_f32_e32 v110, 0, v111
	v_max_f32_e32 v111, 0, v112
	v_pk_mul_f32 v[106:107], v[106:107], v[116:117] op_sel_hi:[1,0]
	v_add_u32_e32 v114, s11, v141
	v_max_f32_e32 v112, 0, v113
	v_pk_mul_f32 v[108:109], v[108:109], v[116:117] op_sel_hi:[1,0]
	v_max_f32_e32 v113, 0, v106
	v_max_f32_e32 v118, 0, v107
	v_pk_mul_f32 v[106:107], v[110:111], v[110:111]
	v_ashrrev_i32_e32 v115, 31, v114
	v_max_f32_e32 v119, 0, v108
	v_fma_mixlo_f16 v108, v117, v117, 0
	v_cvt_pk_f16_f32 v107, v106, v107
	v_lshlrev_b64 v[114:115], 13, v[114:115]
	v_max_f32_e32 v120, 0, v109
	v_pack_b32_f16 v106, v108, v107
	v_pk_mul_f32 v[108:109], v[112:113], v[112:113]
	v_lshl_add_u64 v[114:115], s[0:1], 0, v[114:115]
	v_cvt_pk_f16_f32 v110, v108, v109
	v_pk_mul_f32 v[108:109], v[118:119], v[118:119]
	v_lshl_add_u64 v[114:115], v[114:115], 0, s[18:19]
	v_cvt_pk_f16_f32 v109, v108, v109
	v_lshl_add_u64 v[114:115], v[114:115], 0, s[92:93]
	v_alignbit_b32 v108, v109, v110, 16
	v_lshrrev_b32_e32 v109, 16, v109
	v_lshl_add_u64 v[114:115], v[114:115], 0, v[0:1]
	v_alignbit_b32 v107, v110, v107, 16
	v_fma_mixhi_f16 v109, v120, v120, 0
	v_pk_mul_f32 v[104:105], v[104:105], v[116:117] op_sel_hi:[1,0]
	v_pk_mul_f32 v[102:103], v[102:103], v[116:117] op_sel_hi:[1,0]
	global_store_dwordx4 v[114:115], v[106:109], off nt
	v_pk_mul_f32 v[98:99], v[98:99], v[116:117] op_sel_hi:[1,0]
	v_pk_mul_f32 v[100:101], v[100:101], v[116:117] op_sel_hi:[1,0]
	v_max_f32_e32 v108, 0, v102
	v_max_f32_e32 v102, 0, v103
	v_max_f32_e32 v103, 0, v104
	v_max_f32_e32 v104, 0, v105
	v_max_f32_e32 v105, 0, v98
	v_max_f32_e32 v106, 0, v99
	v_pk_mul_f32 v[98:99], v[102:103], v[102:103]
	v_max_f32_e32 v107, 0, v100
	v_fma_mixlo_f16 v100, v108, v108, 0
	v_cvt_pk_f16_f32 v99, v98, v99
	v_max_f32_e32 v109, 0, v101
	v_pack_b32_f16 v98, v100, v99
	v_pk_mul_f32 v[100:101], v[104:105], v[104:105]
	s_mov_b64 s[20:21], s[16:17]
	v_cvt_pk_f16_f32 v102, v100, v101
	v_pk_mul_f32 v[100:101], v[106:107], v[106:107]
	v_alignbit_b32 v99, v102, v99, 16
	v_cvt_pk_f16_f32 v101, v100, v101
	v_alignbit_b32 v100, v101, v102, 16
	v_lshrrev_b32_e32 v101, 16, v101
	v_fma_mixhi_f16 v101, v109, v109, 0
	global_store_dwordx4 v[114:115], v[98:101], off offset:256 nt
	ds_read2_b32 v[98:99], v159 offset0:32 offset1:48
	s_mov_b32 s44, s43
	v_add_u32_e32 v100, s11, v152
	v_ashrrev_i32_e32 v101, 31, v100
	v_lshlrev_b64 v[100:101], 13, v[100:101]
	s_waitcnt lgkmcnt(0)
	v_pk_mul_f32 v[96:97], v[96:97], v[98:99] op_sel_hi:[1,0]
	v_pk_mul_f32 v[94:95], v[94:95], v[98:99] op_sel_hi:[1,0]
	v_pk_mul_f32 v[90:91], v[90:91], v[98:99] op_sel_hi:[1,0]
	v_max_f32_e32 v104, 0, v94
	v_max_f32_e32 v94, 0, v95
	v_max_f32_e32 v95, 0, v96
	v_max_f32_e32 v96, 0, v97
	v_pk_mul_f32 v[92:93], v[92:93], v[98:99] op_sel_hi:[1,0]
	v_max_f32_e32 v97, 0, v90
	v_max_f32_e32 v102, 0, v91
	v_pk_mul_f32 v[90:91], v[94:95], v[94:95]
	v_max_f32_e32 v103, 0, v92
	v_fma_mixlo_f16 v92, v104, v104, 0
	v_cvt_pk_f16_f32 v91, v90, v91
	v_max_f32_e32 v105, 0, v93
	v_pack_b32_f16 v90, v92, v91
	v_pk_mul_f32 v[92:93], v[96:97], v[96:97]
	v_lshl_add_u64 v[100:101], s[0:1], 0, v[100:101]
	v_cvt_pk_f16_f32 v94, v92, v93
	v_pk_mul_f32 v[92:93], v[102:103], v[102:103]
	v_lshl_add_u64 v[100:101], v[100:101], 0, s[18:19]
	v_cvt_pk_f16_f32 v93, v92, v93
	v_lshl_add_u64 v[100:101], v[100:101], 0, s[92:93]
	v_alignbit_b32 v92, v93, v94, 16
	v_lshrrev_b32_e32 v93, 16, v93
	v_lshl_add_u64 v[100:101], v[100:101], 0, v[0:1]
	v_alignbit_b32 v91, v94, v91, 16
	v_fma_mixhi_f16 v93, v105, v105, 0
	v_pk_mul_f32 v[88:89], v[88:89], v[98:99] op_sel_hi:[1,0]
	v_pk_mul_f32 v[86:87], v[86:87], v[98:99] op_sel_hi:[1,0]
	global_store_dwordx4 v[100:101], v[90:93], off nt
	v_pk_mul_f32 v[82:83], v[82:83], v[98:99] op_sel_hi:[1,0]
	v_pk_mul_f32 v[84:85], v[84:85], v[98:99] op_sel_hi:[1,0]
	v_max_f32_e32 v92, 0, v86
	v_max_f32_e32 v86, 0, v87
	v_max_f32_e32 v87, 0, v88
	v_max_f32_e32 v88, 0, v89
	v_max_f32_e32 v89, 0, v82
	v_max_f32_e32 v90, 0, v83
	v_pk_mul_f32 v[82:83], v[86:87], v[86:87]
	v_max_f32_e32 v91, 0, v84
	v_fma_mixlo_f16 v84, v92, v92, 0
	v_cvt_pk_f16_f32 v83, v82, v83
	v_max_f32_e32 v93, 0, v85
	v_pack_b32_f16 v82, v84, v83
	v_pk_mul_f32 v[84:85], v[88:89], v[88:89]
	s_nop 0
	v_cvt_pk_f16_f32 v86, v84, v85
	v_pk_mul_f32 v[84:85], v[90:91], v[90:91]
	v_alignbit_b32 v83, v86, v83, 16
	v_cvt_pk_f16_f32 v85, v84, v85
	v_alignbit_b32 v84, v85, v86, 16
	v_lshrrev_b32_e32 v85, 16, v85
	v_fma_mixhi_f16 v85, v93, v93, 0
	global_store_dwordx4 v[100:101], v[82:85], off offset:256 nt
	s_nop 1
	v_mov_b32_e32 v84, v99
	v_pk_mul_f32 v[78:79], v[78:79], v[84:85] op_sel_hi:[1,0]
	v_pk_mul_f32 v[80:81], v[80:81], v[84:85] op_sel_hi:[1,0]
	v_max_f32_e32 v85, 0, v78
	v_max_f32_e32 v78, 0, v79
	v_max_f32_e32 v79, 0, v80
	v_pk_mul_f32 v[74:75], v[74:75], v[84:85] op_sel_hi:[1,0]
	v_add_u32_e32 v82, s11, v153
	v_max_f32_e32 v80, 0, v81
	v_pk_mul_f32 v[76:77], v[76:77], v[84:85] op_sel_hi:[1,0]
	v_max_f32_e32 v81, 0, v74
	v_max_f32_e32 v86, 0, v75
	v_pk_mul_f32 v[74:75], v[78:79], v[78:79]
	v_ashrrev_i32_e32 v83, 31, v82
	v_max_f32_e32 v87, 0, v76
	v_fma_mixlo_f16 v76, v85, v85, 0
	v_cvt_pk_f16_f32 v75, v74, v75
	v_lshlrev_b64 v[82:83], 13, v[82:83]
	v_max_f32_e32 v88, 0, v77
	v_pack_b32_f16 v74, v76, v75
	v_pk_mul_f32 v[76:77], v[80:81], v[80:81]
	v_lshl_add_u64 v[82:83], s[0:1], 0, v[82:83]
	v_cvt_pk_f16_f32 v78, v76, v77
	v_pk_mul_f32 v[76:77], v[86:87], v[86:87]
	v_lshl_add_u64 v[82:83], v[82:83], 0, s[18:19]
	v_cvt_pk_f16_f32 v77, v76, v77
	v_lshl_add_u64 v[82:83], v[82:83], 0, s[92:93]
	v_alignbit_b32 v76, v77, v78, 16
	v_lshrrev_b32_e32 v77, 16, v77
	v_lshl_add_u64 v[82:83], v[82:83], 0, v[0:1]
	v_alignbit_b32 v75, v78, v75, 16
	v_fma_mixhi_f16 v77, v88, v88, 0
	v_pk_mul_f32 v[72:73], v[72:73], v[84:85] op_sel_hi:[1,0]
	v_pk_mul_f32 v[70:71], v[70:71], v[84:85] op_sel_hi:[1,0]
	global_store_dwordx4 v[82:83], v[74:77], off nt
	v_pk_mul_f32 v[66:67], v[66:67], v[84:85] op_sel_hi:[1,0]
	v_pk_mul_f32 v[68:69], v[68:69], v[84:85] op_sel_hi:[1,0]
	v_max_f32_e32 v76, 0, v70
	v_max_f32_e32 v70, 0, v71
	v_max_f32_e32 v71, 0, v72
	v_max_f32_e32 v72, 0, v73
	v_max_f32_e32 v73, 0, v66
	v_max_f32_e32 v74, 0, v67
	v_pk_mul_f32 v[66:67], v[70:71], v[70:71]
	v_max_f32_e32 v75, 0, v68
	v_fma_mixlo_f16 v68, v76, v76, 0
	v_cvt_pk_f16_f32 v67, v66, v67
	v_max_f32_e32 v77, 0, v69
	v_pack_b32_f16 v66, v68, v67
	v_pk_mul_f32 v[68:69], v[72:73], v[72:73]
	s_nop 0
	v_cvt_pk_f16_f32 v70, v68, v69
	v_pk_mul_f32 v[68:69], v[74:75], v[74:75]
	v_alignbit_b32 v67, v70, v67, 16
	v_cvt_pk_f16_f32 v69, v68, v69
	v_alignbit_b32 v68, v69, v70, 16
	v_lshrrev_b32_e32 v69, 16, v69
	v_fma_mixhi_f16 v69, v77, v77, 0
	global_store_dwordx4 v[82:83], v[66:69], off offset:256 nt
	ds_read2_b32 v[66:67], v159 offset0:128 offset1:144
	s_waitcnt lgkmcnt(0)
;   __device__ __forceinline__ void operator()(const f32x4 (&acc)[2][2][4][2], const g8::Unit& u, int ui, int wr, int wc, int fr, int fq) const {
; #pragma unroll
;     for (int ai = 0; ai < 2; ++ai)
; #pragma unroll
;       for (int m = 0; m < 4; ++m) {
;         const int rl = 128 * ai + 64 * wr + 16 * m + fr;
;         const float r = rsl[ui * 256 + rl];
;         h16* rowp = hid + (size_t)(u.pm * 256 + rl) * DFF + 256 * u.pn + 32 * wc + 8 * fq;
; #pragma unroll
;         for (int bj = 0; bj < 2; ++bj) {
;           f32x4 v[2];
; #pragma unroll
;           for (int n = 0; n < 2; ++n) {
;             v[n] = acc[ai][bj][m][n] * r;
; #pragma unroll
;             for (int j = 0; j < 4; ++j) { const float t = fmaxf(v[n][j], 0.f); v[n][j] = t * t; }
;           }
;           __builtin_nontemporal_store(pack8(v[0], v[1]), (h16x8*)(rowp + 128 * bj));
	v_pk_mul_f32 v[64:65], v[64:65], v[66:67] op_sel_hi:[1,0]
	v_pk_mul_f32 v[62:63], v[62:63], v[66:67] op_sel_hi:[1,0]
	v_pk_mul_f32 v[58:59], v[58:59], v[66:67] op_sel_hi:[1,0]
	v_max_f32_e32 v72, 0, v62
	v_max_f32_e32 v62, 0, v63
	v_max_f32_e32 v63, 0, v64
	v_add_u32_e32 v68, s11, v154
	v_max_f32_e32 v64, 0, v65
	v_pk_mul_f32 v[60:61], v[60:61], v[66:67] op_sel_hi:[1,0]
	v_max_f32_e32 v65, 0, v58
	v_max_f32_e32 v70, 0, v59
	v_pk_mul_f32 v[58:59], v[62:63], v[62:63]
	v_ashrrev_i32_e32 v69, 31, v68
	v_max_f32_e32 v71, 0, v60
	v_fma_mixlo_f16 v60, v72, v72, 0
	v_cvt_pk_f16_f32 v59, v58, v59
	v_lshlrev_b64 v[68:69], 13, v[68:69]
	v_max_f32_e32 v73, 0, v61
	v_pack_b32_f16 v58, v60, v59
	v_pk_mul_f32 v[60:61], v[64:65], v[64:65]
	v_lshl_add_u64 v[68:69], s[0:1], 0, v[68:69]
	v_cvt_pk_f16_f32 v62, v60, v61
	v_pk_mul_f32 v[60:61], v[70:71], v[70:71]
	v_lshl_add_u64 v[68:69], v[68:69], 0, s[18:19]
	v_cvt_pk_f16_f32 v61, v60, v61
	v_lshl_add_u64 v[68:69], v[68:69], 0, s[92:93]
	v_alignbit_b32 v60, v61, v62, 16
	v_lshrrev_b32_e32 v61, 16, v61
	v_lshl_add_u64 v[68:69], v[68:69], 0, v[0:1]
	v_alignbit_b32 v59, v62, v59, 16
	v_fma_mixhi_f16 v61, v73, v73, 0
	v_pk_mul_f32 v[56:57], v[56:57], v[66:67] op_sel_hi:[1,0]
	v_pk_mul_f32 v[54:55], v[54:55], v[66:67] op_sel_hi:[1,0]
	global_store_dwordx4 v[68:69], v[58:61], off nt
	v_pk_mul_f32 v[50:51], v[50:51], v[66:67] op_sel_hi:[1,0]
	v_pk_mul_f32 v[52:53], v[52:53], v[66:67] op_sel_hi:[1,0]
	v_max_f32_e32 v60, 0, v54
	v_max_f32_e32 v54, 0, v55
	v_max_f32_e32 v55, 0, v56
	v_max_f32_e32 v56, 0, v57
	v_max_f32_e32 v57, 0, v50
	v_max_f32_e32 v58, 0, v51
	v_pk_mul_f32 v[50:51], v[54:55], v[54:55]
	v_max_f32_e32 v59, 0, v52
	v_fma_mixlo_f16 v52, v60, v60, 0
	v_cvt_pk_f16_f32 v51, v50, v51
	v_max_f32_e32 v61, 0, v53
	v_pack_b32_f16 v50, v52, v51
	v_pk_mul_f32 v[52:53], v[56:57], v[56:57]
	s_nop 0
	v_cvt_pk_f16_f32 v54, v52, v53
	v_pk_mul_f32 v[52:53], v[58:59], v[58:59]
	v_alignbit_b32 v51, v54, v51, 16
	v_cvt_pk_f16_f32 v53, v52, v53
	v_alignbit_b32 v52, v53, v54, 16
	v_lshrrev_b32_e32 v53, 16, v53
	v_fma_mixhi_f16 v53, v61, v61, 0
	global_store_dwordx4 v[68:69], v[50:53], off offset:256 nt
	s_nop 1
	v_mov_b32_e32 v52, v67
	v_pk_mul_f32 v[46:47], v[46:47], v[52:53] op_sel_hi:[1,0]
	v_pk_mul_f32 v[48:49], v[48:49], v[52:53] op_sel_hi:[1,0]
	v_max_f32_e32 v53, 0, v46
	v_max_f32_e32 v46, 0, v47
	v_max_f32_e32 v47, 0, v48
	v_pk_mul_f32 v[42:43], v[42:43], v[52:53] op_sel_hi:[1,0]
	v_add_u32_e32 v50, s11, v155
	v_max_f32_e32 v48, 0, v49
	v_pk_mul_f32 v[44:45], v[44:45], v[52:53] op_sel_hi:[1,0]
	v_max_f32_e32 v49, 0, v42
	v_max_f32_e32 v54, 0, v43
	v_pk_mul_f32 v[42:43], v[46:47], v[46:47]
	v_ashrrev_i32_e32 v51, 31, v50
	v_max_f32_e32 v55, 0, v44
	v_fma_mixlo_f16 v44, v53, v53, 0
	v_cvt_pk_f16_f32 v43, v42, v43
	v_lshlrev_b64 v[50:51], 13, v[50:51]
	v_max_f32_e32 v56, 0, v45
	v_pack_b32_f16 v42, v44, v43
	v_pk_mul_f32 v[44:45], v[48:49], v[48:49]
	v_lshl_add_u64 v[50:51], s[0:1], 0, v[50:51]
	v_cvt_pk_f16_f32 v46, v44, v45
	v_pk_mul_f32 v[44:45], v[54:55], v[54:55]
	v_lshl_add_u64 v[50:51], v[50:51], 0, s[18:19]
	v_cvt_pk_f16_f32 v45, v44, v45
	v_lshl_add_u64 v[50:51], v[50:51], 0, s[92:93]
	v_alignbit_b32 v44, v45, v46, 16
	v_lshrrev_b32_e32 v45, 16, v45
	v_lshl_add_u64 v[50:51], v[50:51], 0, v[0:1]
	v_alignbit_b32 v43, v46, v43, 16
	v_fma_mixhi_f16 v45, v56, v56, 0
	v_pk_mul_f32 v[40:41], v[40:41], v[52:53] op_sel_hi:[1,0]
	v_pk_mul_f32 v[38:39], v[38:39], v[52:53] op_sel_hi:[1,0]
	global_store_dwordx4 v[50:51], v[42:45], off nt
	v_pk_mul_f32 v[34:35], v[34:35], v[52:53] op_sel_hi:[1,0]
	v_pk_mul_f32 v[36:37], v[36:37], v[52:53] op_sel_hi:[1,0]
	v_max_f32_e32 v44, 0, v38
	v_max_f32_e32 v38, 0, v39
	v_max_f32_e32 v39, 0, v40
	v_max_f32_e32 v40, 0, v41
	v_max_f32_e32 v41, 0, v34
	v_max_f32_e32 v42, 0, v35
	v_pk_mul_f32 v[34:35], v[38:39], v[38:39]
	v_max_f32_e32 v43, 0, v36
	v_fma_mixlo_f16 v36, v44, v44, 0
	v_cvt_pk_f16_f32 v35, v34, v35
	v_max_f32_e32 v45, 0, v37
	v_pack_b32_f16 v34, v36, v35
	v_pk_mul_f32 v[36:37], v[40:41], v[40:41]
	s_nop 0
	v_cvt_pk_f16_f32 v38, v36, v37
	v_pk_mul_f32 v[36:37], v[42:43], v[42:43]
	v_alignbit_b32 v35, v38, v35, 16
	v_cvt_pk_f16_f32 v37, v36, v37
	v_alignbit_b32 v36, v37, v38, 16
	v_lshrrev_b32_e32 v37, 16, v37
	v_fma_mixhi_f16 v37, v45, v45, 0
	global_store_dwordx4 v[50:51], v[34:37], off offset:256 nt
	ds_read2_b32 v[34:35], v159 offset0:160 offset1:176
	s_waitcnt lgkmcnt(0)
; #define G8_WAIT_V(n) asm volatile("s_waitcnt vmcnt(" #n ")" ::: "memory")
; #define G8_BAR __builtin_amdgcn_s_barrier()
; template <class Epi>
; __device__ __forceinline__ void gemm_phase(LAS unsigned char* lds, const h16* A, const h16* Bt, int K, const Order& S, const Epi& E) {
;     ...
;   G8_WAIT_V(0);
;   if (wr == 0) G8_BAR;
;   G8_BAR;
;   __device__ __forceinline__ void operator()(const f32x4 (&acc)[2][2][4][2], const g8::Unit& u, int ui, int wr, int wc, int fr, int fq) const {
; #pragma unroll
;     for (int ai = 0; ai < 2; ++ai)
; #pragma unroll
;       for (int m = 0; m < 4; ++m) {
;         const int rl = 128 * ai + 64 * wr + 16 * m + fr;
;         const float r = rsl[ui * 256 + rl];
;         h16* rowp = hid + (size_t)(u.pm * 256 + rl) * DFF + 256 * u.pn + 32 * wc + 8 * fq;
; #pragma unroll
;         for (int bj = 0; bj < 2; ++bj) {
;           f32x4 v[2];
; #pragma unroll
;           for (int n = 0; n < 2; ++n) {
;             v[n] = acc[ai][bj][m][n] * r;
; #pragma unroll
;             for (int j = 0; j < 4; ++j) { const float t = fmaxf(v[n][j], 0.f); v[n][j] = t * t; }
;           }
;           __builtin_nontemporal_store(pack8(v[0], v[1]), (h16x8*)(rowp + 128 * bj));
	v_pk_mul_f32 v[32:33], v[32:33], v[34:35] op_sel_hi:[1,0]
	v_pk_mul_f32 v[30:31], v[30:31], v[34:35] op_sel_hi:[1,0]
	v_pk_mul_f32 v[26:27], v[26:27], v[34:35] op_sel_hi:[1,0]
	v_max_f32_e32 v40, 0, v30
	v_max_f32_e32 v30, 0, v31
	v_max_f32_e32 v31, 0, v32
	v_add_u32_e32 v36, s11, v156
	v_max_f32_e32 v32, 0, v33
	v_pk_mul_f32 v[28:29], v[28:29], v[34:35] op_sel_hi:[1,0]
	v_max_f32_e32 v33, 0, v26
	v_max_f32_e32 v38, 0, v27
	v_pk_mul_f32 v[26:27], v[30:31], v[30:31]
	v_ashrrev_i32_e32 v37, 31, v36
	v_max_f32_e32 v39, 0, v28
	v_fma_mixlo_f16 v28, v40, v40, 0
	v_cvt_pk_f16_f32 v27, v26, v27
	v_lshlrev_b64 v[36:37], 13, v[36:37]
	v_max_f32_e32 v41, 0, v29
	v_pack_b32_f16 v26, v28, v27
	v_pk_mul_f32 v[28:29], v[32:33], v[32:33]
	v_lshl_add_u64 v[36:37], s[0:1], 0, v[36:37]
	v_cvt_pk_f16_f32 v30, v28, v29
	v_pk_mul_f32 v[28:29], v[38:39], v[38:39]
	v_lshl_add_u64 v[36:37], v[36:37], 0, s[18:19]
	v_cvt_pk_f16_f32 v29, v28, v29
	v_lshl_add_u64 v[36:37], v[36:37], 0, s[92:93]
	v_alignbit_b32 v28, v29, v30, 16
	v_lshrrev_b32_e32 v29, 16, v29
	v_lshl_add_u64 v[36:37], v[36:37], 0, v[0:1]
	v_alignbit_b32 v27, v30, v27, 16
	v_fma_mixhi_f16 v29, v41, v41, 0
	v_pk_mul_f32 v[24:25], v[24:25], v[34:35] op_sel_hi:[1,0]
	v_pk_mul_f32 v[22:23], v[22:23], v[34:35] op_sel_hi:[1,0]
	global_store_dwordx4 v[36:37], v[26:29], off nt
	v_pk_mul_f32 v[18:19], v[18:19], v[34:35] op_sel_hi:[1,0]
	v_pk_mul_f32 v[20:21], v[20:21], v[34:35] op_sel_hi:[1,0]
	v_max_f32_e32 v28, 0, v22
	v_max_f32_e32 v22, 0, v23
	v_max_f32_e32 v23, 0, v24
	v_max_f32_e32 v24, 0, v25
	v_max_f32_e32 v25, 0, v18
	v_max_f32_e32 v26, 0, v19
	v_pk_mul_f32 v[18:19], v[22:23], v[22:23]
	v_max_f32_e32 v27, 0, v20
	v_fma_mixlo_f16 v20, v28, v28, 0
	v_cvt_pk_f16_f32 v19, v18, v19
	v_max_f32_e32 v29, 0, v21
	v_pack_b32_f16 v18, v20, v19
	v_pk_mul_f32 v[20:21], v[24:25], v[24:25]
	s_nop 0
	v_cvt_pk_f16_f32 v22, v20, v21
	v_pk_mul_f32 v[20:21], v[26:27], v[26:27]
	v_alignbit_b32 v19, v22, v19, 16
	v_cvt_pk_f16_f32 v21, v20, v21
	v_alignbit_b32 v20, v21, v22, 16
	v_lshrrev_b32_e32 v21, 16, v21
	v_fma_mixhi_f16 v21, v29, v29, 0
	global_store_dwordx4 v[36:37], v[18:21], off offset:256 nt
	s_nop 1
	v_mov_b32_e32 v20, v35
	v_pk_mul_f32 v[14:15], v[14:15], v[20:21] op_sel_hi:[1,0]
	v_pk_mul_f32 v[16:17], v[16:17], v[20:21] op_sel_hi:[1,0]
	v_max_f32_e32 v21, 0, v14
	v_max_f32_e32 v14, 0, v15
	v_max_f32_e32 v15, 0, v16
	v_pk_mul_f32 v[10:11], v[10:11], v[20:21] op_sel_hi:[1,0]
	v_add_u32_e32 v18, s11, v157
	v_max_f32_e32 v16, 0, v17
	v_pk_mul_f32 v[12:13], v[12:13], v[20:21] op_sel_hi:[1,0]
	v_max_f32_e32 v17, 0, v10
	v_max_f32_e32 v22, 0, v11
	v_pk_mul_f32 v[10:11], v[14:15], v[14:15]
	v_ashrrev_i32_e32 v19, 31, v18
	v_max_f32_e32 v23, 0, v12
	v_fma_mixlo_f16 v12, v21, v21, 0
	v_cvt_pk_f16_f32 v11, v10, v11
	v_lshlrev_b64 v[18:19], 13, v[18:19]
	v_max_f32_e32 v24, 0, v13
	v_pack_b32_f16 v10, v12, v11
	v_pk_mul_f32 v[12:13], v[16:17], v[16:17]
	v_lshl_add_u64 v[18:19], s[0:1], 0, v[18:19]
	v_cvt_pk_f16_f32 v14, v12, v13
	v_pk_mul_f32 v[12:13], v[22:23], v[22:23]
	v_lshl_add_u64 v[18:19], v[18:19], 0, s[18:19]
	v_cvt_pk_f16_f32 v13, v12, v13
	v_lshl_add_u64 v[18:19], v[18:19], 0, s[92:93]
	v_alignbit_b32 v12, v13, v14, 16
	v_lshrrev_b32_e32 v13, 16, v13
	v_lshl_add_u64 v[18:19], v[18:19], 0, v[0:1]
	v_alignbit_b32 v11, v14, v11, 16
	v_fma_mixhi_f16 v13, v24, v24, 0
	v_pk_mul_f32 v[8:9], v[8:9], v[20:21] op_sel_hi:[1,0]
	v_pk_mul_f32 v[6:7], v[6:7], v[20:21] op_sel_hi:[1,0]
	global_store_dwordx4 v[18:19], v[10:13], off nt
	v_pk_mul_f32 v[2:3], v[2:3], v[20:21] op_sel_hi:[1,0]
	v_pk_mul_f32 v[4:5], v[4:5], v[20:21] op_sel_hi:[1,0]
	v_max_f32_e32 v12, 0, v6
	v_max_f32_e32 v6, 0, v7
	v_max_f32_e32 v7, 0, v8
	v_max_f32_e32 v8, 0, v9
	v_max_f32_e32 v9, 0, v2
	v_max_f32_e32 v10, 0, v3
	v_pk_mul_f32 v[2:3], v[6:7], v[6:7]
	v_max_f32_e32 v11, 0, v4
	v_fma_mixlo_f16 v4, v12, v12, 0
	v_cvt_pk_f16_f32 v3, v2, v3
	v_max_f32_e32 v13, 0, v5
	v_pack_b32_f16 v2, v4, v3
	v_pk_mul_f32 v[4:5], v[8:9], v[8:9]
	s_mov_b64 s[18:19], s[14:15]
	v_cvt_pk_f16_f32 v6, v4, v5
	v_pk_mul_f32 v[4:5], v[10:11], v[10:11]
	v_alignbit_b32 v3, v6, v3, 16
	v_cvt_pk_f16_f32 v5, v4, v5
	v_alignbit_b32 v4, v5, v6, 16
	v_lshrrev_b32_e32 v5, 16, v5
	v_fma_mixhi_f16 v5, v13, v13, 0
	global_store_dwordx4 v[18:19], v[2:5], off offset:256 nt
	s_cbranch_vccz .LBB0_2466
	s_waitcnt vmcnt(0)
	s_cmpk_gt_u32 s2, 0xff
	s_cbranch_scc1 .LBB0_2477
	s_barrier

; #define G8_STAGE(bufoff, gbase) do { _Pragma("unroll") for (int _i = 0; _i < 2; ++_i) \
;     __builtin_amdgcn_global_load_lds((const unsigned*)((const char*)(gbase) + voffA[_i]), (LAS unsigned*)(lds + (bufoff) + ldsw + _i * 8192), 16, 0, 0); } while (0)
; #define G8_LDA(dst, b, h) do { _Pragma("unroll") for (int m = 0; m < 4; ++m) _Pragma("unroll") for (int k = 0; k < 2; ++k) dst[m][k] = *(const LAS h16x8*)(lds + G8_SA(b, h) + aoff + m * 2048 + k * 1024); } while (0)
; #define G8_LDB(dst, b, h) do { _Pragma("unroll") for (int n = 0; n < 2; ++n) _Pragma("unroll") for (int k = 0; k < 2; ++k) dst[n][k] = *(const LAS h16x8*)(lds + G8_SB(b, h) + boff + n * 2048 + k * 1024); } while (0)
; #define G8_MMA(ai, bj, At, Bt_) do { __builtin_amdgcn_s_setprio(1); _Pragma("unroll") for (int m = 0; m < 4; ++m) _Pragma("unroll") for (int n = 0; n < 2; ++n) _Pragma("unroll") for (int k = 0; k < 2; ++k) \
;     acc[ai][bj][m][n] = __builtin_amdgcn_mfma_f32_16x16x32_f16(Bt_[n][k], At[m][k], acc[ai][bj][m][n], 0, 0, 0); __builtin_amdgcn_s_setprio(0); } while (0)
; #define G8_WAIT_L(n) asm volatile("s_waitcnt lgkmcnt(" #n ")" ::: "memory")
; #define G8_BAR __builtin_amdgcn_s_barrier()
; #define G8_SCHED __builtin_amdgcn_sched_barrier(0)
; template <class Epi>
; __device__ __forceinline__ void gemm_phase(LAS unsigned char* lds, const h16* A, const h16* Bt, int K, const Order& S, const Epi& E) {
;     ...
;       const bool last = (t == nt - 2);
;       const char* a1 = cA + (size_t)(t + 1) * kstep;
;       const char* a2 = last ? nA : cA + (size_t)(t + 2) * kstep;
;       const char* b2 = last ? nB : cB + (size_t)(t + 2) * kstep;
;       const char* a3 = a2 + kstep;
;       const char* b3 = b2 + kstep;
;       if (Epi::MID_T >= 0 && t == Epi::MID_T) E.mid(acc, ui, wr, fr);
;       G8_LDB(B0, 0, 0); G8_SCHED; G8_LDA(At, 0, 0); G8_STAGE(G8_SA(1, 1), a1 + hstep);
;       G8_WAIT_L(8); G8_BAR; G8_WAIT_L(0); G8_MMA(0, 0, At, B0); G8_BAR; G8_SCHED;
;       G8_LDB(B1, 0, 1); G8_STAGE(G8_SB(0, 0), b2);
;       G8_BAR; G8_WAIT_L(0); G8_MMA(0, 1, At, B1); G8_BAR;
;       G8_LDA(At, 0, 1); G8_STAGE(G8_SA(0, 0), a2);
;       G8_BAR; G8_WAIT_L(0); G8_MMA(1, 0, At, B0); G8_BAR; G8_SCHED;
.LBB0_2542:
	s_add_u32 s24, s22, 0xfff00080
	s_addc_u32 s25, s23, -1
	s_cmp_eq_u32 s53, 60
	s_cselect_b32 s27, s3, s25
	s_cselect_b32 s26, s9, s24
	s_cselect_b32 s25, s15, s52
	s_cselect_b32 s24, s17, s51
	v_lshl_add_u64 v[140:141], s[22:23], 0, v[136:137]
	s_add_i32 m0, s35, 0xc000
	ds_read_b128 v[172:175], v135
	ds_read_b128 v[176:179], v135 offset:1024
	ds_read_b128 v[180:183], v135 offset:2048
	ds_read_b128 v[184:187], v135 offset:3072
	ds_read_b128 v[202:205], v135 offset:4096
	ds_read_b128 v[206:209], v135 offset:5120
	ds_read_b128 v[210:213], v135 offset:6144
	ds_read_b128 v[214:217], v135 offset:7168
	global_load_lds_dwordx4 v[140:141], off
	v_lshl_add_u64 v[140:141], s[22:23], 0, v[138:139]
	s_add_i32 m0, s35, 0xe000
	s_nop 0
	global_load_lds_dwordx4 v[140:141], off
	s_waitcnt lgkmcnt(8)
	s_barrier
	s_waitcnt lgkmcnt(0)
	s_waitcnt lgkmcnt(0)
	v_mfma_f32_16x16x32_f16 v[126:129], v[152:155], v[172:175], v[126:129]
	v_mfma_f32_16x16x32_f16 v[122:125], v[164:167], v[172:175], v[122:125]
	v_mfma_f32_16x16x32_f16 v[110:113], v[152:155], v[180:183], v[110:113]
	v_mfma_f32_16x16x32_f16 v[106:109], v[164:167], v[180:183], v[106:109]
	v_mfma_f32_16x16x32_f16 v[94:97], v[152:155], v[202:205], v[94:97]
	v_mfma_f32_16x16x32_f16 v[90:93], v[164:167], v[202:205], v[90:93]
	v_mfma_f32_16x16x32_f16 v[78:81], v[152:155], v[210:213], v[78:81]
	v_mfma_f32_16x16x32_f16 v[74:77], v[164:167], v[210:213], v[74:77]
	v_mfma_f32_16x16x32_f16 v[126:129], v[160:163], v[176:179], v[126:129]
	v_mfma_f32_16x16x32_f16 v[122:125], v[168:171], v[176:179], v[122:125]
	v_mfma_f32_16x16x32_f16 v[110:113], v[160:163], v[184:187], v[110:113]
	v_mfma_f32_16x16x32_f16 v[106:109], v[168:171], v[184:187], v[106:109]
	v_mfma_f32_16x16x32_f16 v[94:97], v[160:163], v[206:209], v[94:97]
	v_mfma_f32_16x16x32_f16 v[90:93], v[168:171], v[206:209], v[90:93]
	v_mfma_f32_16x16x32_f16 v[78:81], v[160:163], v[214:217], v[78:81]
	v_mfma_f32_16x16x32_f16 v[74:77], v[168:171], v[214:217], v[74:77]
	s_barrier
	v_or_b32_e32 v140, 0x14000, v158
	v_add_u32_e32 v141, 0x14400, v158
	ds_read_b128 v[218:221], v140
	ds_read_b128 v[222:225], v141
	v_add_u32_e32 v140, 0x14800, v158
	v_add_u32_e32 v141, 0x14c00, v158
	s_mov_b32 m0, s36
	ds_read_b128 v[226:229], v140
	ds_read_b128 v[230:233], v141
	v_lshl_add_u64 v[140:141], s[24:25], 0, v[0:1]
	global_load_lds_dwordx4 v[140:141], off
	v_lshl_add_u64 v[156:157], s[24:25], 0, v[130:131]
	s_mov_b32 m0, s37
	s_nop 0
	global_load_lds_dwordx4 v[156:157], off
	s_barrier
	s_waitcnt lgkmcnt(0)
	s_waitcnt lgkmcnt(0)
	v_mfma_f32_16x16x32_f16 v[118:121], v[218:221], v[172:175], v[118:121]
	v_mfma_f32_16x16x32_f16 v[114:117], v[226:229], v[172:175], v[114:117]
	v_mfma_f32_16x16x32_f16 v[102:105], v[218:221], v[180:183], v[102:105]
	v_mfma_f32_16x16x32_f16 v[98:101], v[226:229], v[180:183], v[98:101]
	v_mfma_f32_16x16x32_f16 v[86:89], v[218:221], v[202:205], v[86:89]
	v_mfma_f32_16x16x32_f16 v[82:85], v[226:229], v[202:205], v[82:85]
	v_mfma_f32_16x16x32_f16 v[70:73], v[218:221], v[210:213], v[70:73]
	v_mfma_f32_16x16x32_f16 v[66:69], v[226:229], v[210:213], v[66:69]
	v_mfma_f32_16x16x32_f16 v[118:121], v[222:225], v[176:179], v[118:121]
	v_mfma_f32_16x16x32_f16 v[114:117], v[230:233], v[176:179], v[114:117]
	v_mfma_f32_16x16x32_f16 v[102:105], v[222:225], v[184:187], v[102:105]
	v_mfma_f32_16x16x32_f16 v[98:101], v[230:233], v[184:187], v[98:101]
	v_mfma_f32_16x16x32_f16 v[86:89], v[222:225], v[206:209], v[86:89]
	v_mfma_f32_16x16x32_f16 v[82:85], v[230:233], v[206:209], v[82:85]
	v_mfma_f32_16x16x32_f16 v[70:73], v[222:225], v[214:217], v[70:73]
	v_mfma_f32_16x16x32_f16 v[66:69], v[230:233], v[214:217], v[66:69]
	s_mov_b32 m0, s35
	v_lshl_add_u64 v[188:189], s[26:27], 0, v[0:1]
	s_barrier
	ds_read_b128 v[172:175], v135 offset:16384
	ds_read_b128 v[176:179], v135 offset:17408
	ds_read_b128 v[180:183], v135 offset:18432
	ds_read_b128 v[184:187], v135 offset:19456
	ds_read_b128 v[202:205], v135 offset:20480
	ds_read_b128 v[206:209], v135 offset:21504
	ds_read_b128 v[210:213], v135 offset:22528
	ds_read_b128 v[214:217], v135 offset:23552
	global_load_lds_dwordx4 v[188:189], off
	v_lshl_add_u64 v[234:235], s[26:27], 0, v[130:131]
	s_mov_b32 m0, s38
	s_nop 0
	global_load_lds_dwordx4 v[234:235], off
	s_waitcnt vmcnt(10)
	s_barrier
	s_waitcnt lgkmcnt(0)
	s_waitcnt lgkmcnt(0)
	v_mfma_f32_16x16x32_f16 v[62:65], v[152:155], v[172:175], v[62:65]
	v_mfma_f32_16x16x32_f16 v[58:61], v[164:167], v[172:175], v[58:61]
	v_mfma_f32_16x16x32_f16 v[46:49], v[152:155], v[180:183], v[46:49]
	v_mfma_f32_16x16x32_f16 v[42:45], v[164:167], v[180:183], v[42:45]
	v_mfma_f32_16x16x32_f16 v[30:33], v[152:155], v[202:205], v[30:33]
	v_mfma_f32_16x16x32_f16 v[26:29], v[164:167], v[202:205], v[26:29]
	v_mfma_f32_16x16x32_f16 v[14:17], v[152:155], v[210:213], v[14:17]
	v_mfma_f32_16x16x32_f16 v[10:13], v[164:167], v[210:213], v[10:13]
	v_mfma_f32_16x16x32_f16 v[62:65], v[160:163], v[176:179], v[62:65]
	v_mfma_f32_16x16x32_f16 v[58:61], v[168:171], v[176:179], v[58:61]
	v_mfma_f32_16x16x32_f16 v[46:49], v[160:163], v[184:187], v[46:49]
	v_mfma_f32_16x16x32_f16 v[42:45], v[168:171], v[184:187], v[42:45]
	v_mfma_f32_16x16x32_f16 v[30:33], v[160:163], v[206:209], v[30:33]
	v_mfma_f32_16x16x32_f16 v[26:29], v[168:171], v[206:209], v[26:29]
	v_mfma_f32_16x16x32_f16 v[14:17], v[160:163], v[214:217], v[14:17]
	v_mfma_f32_16x16x32_f16 v[10:13], v[168:171], v[214:217], v[10:13]
	s_barrier
; #define G8_STAGE(bufoff, gbase) do { _Pragma("unroll") for (int _i = 0; _i < 2; ++_i) \
;     __builtin_amdgcn_global_load_lds((const unsigned*)((const char*)(gbase) + voffA[_i]), (LAS unsigned*)(lds + (bufoff) + ldsw + _i * 8192), 16, 0, 0); } while (0)
; #define G8_LDA(dst, b, h) do { _Pragma("unroll") for (int m = 0; m < 4; ++m) _Pragma("unroll") for (int k = 0; k < 2; ++k) dst[m][k] = *(const LAS h16x8*)(lds + G8_SA(b, h) + aoff + m * 2048 + k * 1024); } while (0)
; #define G8_LDB(dst, b, h) do { _Pragma("unroll") for (int n = 0; n < 2; ++n) _Pragma("unroll") for (int k = 0; k < 2; ++k) dst[n][k] = *(const LAS h16x8*)(lds + G8_SB(b, h) + boff + n * 2048 + k * 1024); } while (0)
; #define G8_MMA(ai, bj, At, Bt_) do { __builtin_amdgcn_s_setprio(1); _Pragma("unroll") for (int m = 0; m < 4; ++m) _Pragma("unroll") for (int n = 0; n < 2; ++n) _Pragma("unroll") for (int k = 0; k < 2; ++k) \
;     acc[ai][bj][m][n] = __builtin_amdgcn_mfma_f32_16x16x32_f16(Bt_[n][k], At[m][k], acc[ai][bj][m][n], 0, 0, 0); __builtin_amdgcn_s_setprio(0); } while (0)
; #define G8_WAIT_V(n) asm volatile("s_waitcnt vmcnt(" #n ")" ::: "memory")
; #define G8_WAIT_L(n) asm volatile("s_waitcnt lgkmcnt(" #n ")" ::: "memory")
; #define G8_BAR __builtin_amdgcn_s_barrier()
; #define G8_SCHED __builtin_amdgcn_sched_barrier(0)
; template <class Epi>
; __device__ __forceinline__ void gemm_phase(LAS unsigned char* lds, const h16* A, const h16* Bt, int K, const Order& S, const Epi& E) {
;     ...
;       G8_STAGE(G8_SB(0, 1), b2 + hstep);
;       G8_WAIT_V(6); G8_BAR; G8_MMA(1, 1, At, B1); G8_BAR;
;       G8_LDB(B0, 1, 0); G8_SCHED; G8_LDA(At, 1, 0); G8_STAGE(G8_SA(0, 1), a2 + hstep);
;       G8_WAIT_L(8); G8_BAR; G8_WAIT_L(0); G8_MMA(0, 0, At, B0); G8_BAR; G8_SCHED;
;       G8_LDB(B1, 1, 1); G8_STAGE(G8_SB(1, 0), b3);
;       G8_BAR; G8_WAIT_L(0); G8_MMA(0, 1, At, B1); G8_BAR;
;       G8_LDA(At, 1, 1); G8_STAGE(G8_SA(1, 0), a3);
	s_add_u32 s54, s24, 0x100000
	s_addc_u32 s55, s25, 0
	s_mov_b32 m0, s39
	v_lshl_add_u64 v[152:153], s[54:55], 0, v[0:1]
	global_load_lds_dwordx4 v[152:153], off
	v_lshl_add_u64 v[152:153], s[54:55], 0, v[130:131]
	s_mov_b32 m0, s40
	s_nop 0
	global_load_lds_dwordx4 v[152:153], off
	v_or_b32_e32 v152, 0x18000, v158
	v_add_u32_e32 v159, 0x18400, v158
	ds_read_b128 v[152:155], v152
	ds_read_b128 v[160:163], v159
	v_add_u32_e32 v159, 0x18800, v158
	v_add_u32_e32 v168, 0x18c00, v158
	ds_read_b128 v[164:167], v159
	ds_read_b128 v[168:171], v168
	s_waitcnt vmcnt(6)
	s_barrier
	v_mfma_f32_16x16x32_f16 v[54:57], v[218:221], v[172:175], v[54:57]
	v_mfma_f32_16x16x32_f16 v[50:53], v[226:229], v[172:175], v[50:53]
	v_mfma_f32_16x16x32_f16 v[38:41], v[218:221], v[180:183], v[38:41]
	v_mfma_f32_16x16x32_f16 v[34:37], v[226:229], v[180:183], v[34:37]
	v_mfma_f32_16x16x32_f16 v[22:25], v[218:221], v[202:205], v[22:25]
	v_mfma_f32_16x16x32_f16 v[18:21], v[226:229], v[202:205], v[18:21]
	v_mfma_f32_16x16x32_f16 v[6:9], v[218:221], v[210:213], v[6:9]
	v_mfma_f32_16x16x32_f16 v[2:5], v[226:229], v[210:213], v[2:5]
	v_mfma_f32_16x16x32_f16 v[54:57], v[222:225], v[176:179], v[54:57]
	v_mfma_f32_16x16x32_f16 v[50:53], v[230:233], v[176:179], v[50:53]
	v_mfma_f32_16x16x32_f16 v[38:41], v[222:225], v[184:187], v[38:41]
	v_mfma_f32_16x16x32_f16 v[34:37], v[230:233], v[184:187], v[34:37]
	v_mfma_f32_16x16x32_f16 v[22:25], v[222:225], v[206:209], v[22:25]
	v_mfma_f32_16x16x32_f16 v[18:21], v[230:233], v[206:209], v[18:21]
	v_mfma_f32_16x16x32_f16 v[6:9], v[222:225], v[214:217], v[6:9]
	v_mfma_f32_16x16x32_f16 v[2:5], v[230:233], v[214:217], v[2:5]
	s_barrier
	s_add_u32 s26, s26, 0x100000
	s_addc_u32 s27, s27, 0
	s_mov_b32 m0, s41
	v_lshl_add_u64 v[218:219], s[26:27], 0, v[0:1]
	ds_read_b128 v[172:175], v135 offset:32768
	ds_read_b128 v[176:179], v135 offset:33792
	ds_read_b128 v[180:183], v135 offset:34816
	ds_read_b128 v[184:187], v135 offset:35840
	ds_read_b128 v[202:205], v135 offset:36864
	ds_read_b128 v[206:209], v135 offset:37888
	ds_read_b128 v[210:213], v135 offset:38912
	ds_read_b128 v[214:217], v135 offset:39936
	global_load_lds_dwordx4 v[218:219], off
	v_lshl_add_u64 v[218:219], s[26:27], 0, v[130:131]
	s_mov_b32 m0, s42
	s_nop 0
	global_load_lds_dwordx4 v[218:219], off
	s_waitcnt lgkmcnt(8)
	s_barrier
	s_waitcnt lgkmcnt(0)
	s_waitcnt lgkmcnt(0)
	v_mfma_f32_16x16x32_f16 v[126:129], v[152:155], v[172:175], v[126:129]
	v_mfma_f32_16x16x32_f16 v[122:125], v[164:167], v[172:175], v[122:125]
	v_mfma_f32_16x16x32_f16 v[110:113], v[152:155], v[180:183], v[110:113]
	v_mfma_f32_16x16x32_f16 v[106:109], v[164:167], v[180:183], v[106:109]
	v_mfma_f32_16x16x32_f16 v[94:97], v[152:155], v[202:205], v[94:97]
	v_mfma_f32_16x16x32_f16 v[90:93], v[164:167], v[202:205], v[90:93]
	v_mfma_f32_16x16x32_f16 v[78:81], v[152:155], v[210:213], v[78:81]
	v_mfma_f32_16x16x32_f16 v[74:77], v[164:167], v[210:213], v[74:77]
	v_mfma_f32_16x16x32_f16 v[126:129], v[160:163], v[176:179], v[126:129]
	v_mfma_f32_16x16x32_f16 v[122:125], v[168:171], v[176:179], v[122:125]
	v_mfma_f32_16x16x32_f16 v[110:113], v[160:163], v[184:187], v[110:113]
	v_mfma_f32_16x16x32_f16 v[106:109], v[168:171], v[184:187], v[106:109]
	v_mfma_f32_16x16x32_f16 v[94:97], v[160:163], v[206:209], v[94:97]
	v_mfma_f32_16x16x32_f16 v[90:93], v[168:171], v[206:209], v[90:93]
	v_mfma_f32_16x16x32_f16 v[78:81], v[160:163], v[214:217], v[78:81]
	v_mfma_f32_16x16x32_f16 v[74:77], v[168:171], v[214:217], v[74:77]
	s_barrier
	v_or_b32_e32 v159, 0x1c000, v158
	s_mov_b32 m0, s44
	v_add_u32_e32 v195, 0x1c400, v158
	ds_read_b128 v[218:221], v159
	ds_read_b128 v[222:225], v195
	v_add_u32_e32 v159, 0x1c800, v158
	v_lshl_add_u64 v[140:141], v[140:141], 0, s[94:95]
	v_add_u32_e32 v195, 0x1cc00, v158
	ds_read_b128 v[226:229], v159
	ds_read_b128 v[230:233], v195
	global_load_lds_dwordx4 v[140:141], off
	v_lshl_add_u64 v[140:141], v[156:157], 0, s[94:95]
	s_mov_b32 m0, s45
	s_nop 0
	global_load_lds_dwordx4 v[140:141], off
	s_barrier
	s_waitcnt lgkmcnt(0)
	s_waitcnt lgkmcnt(0)
	v_mfma_f32_16x16x32_f16 v[118:121], v[218:221], v[172:175], v[118:121]
	v_mfma_f32_16x16x32_f16 v[114:117], v[226:229], v[172:175], v[114:117]
	v_mfma_f32_16x16x32_f16 v[102:105], v[218:221], v[180:183], v[102:105]
	v_mfma_f32_16x16x32_f16 v[98:101], v[226:229], v[180:183], v[98:101]
	v_mfma_f32_16x16x32_f16 v[86:89], v[218:221], v[202:205], v[86:89]
	v_mfma_f32_16x16x32_f16 v[82:85], v[226:229], v[202:205], v[82:85]
	v_mfma_f32_16x16x32_f16 v[70:73], v[218:221], v[210:213], v[70:73]
	v_mfma_f32_16x16x32_f16 v[66:69], v[226:229], v[210:213], v[66:69]
	v_mfma_f32_16x16x32_f16 v[118:121], v[222:225], v[176:179], v[118:121]
	v_mfma_f32_16x16x32_f16 v[114:117], v[230:233], v[176:179], v[114:117]
	v_mfma_f32_16x16x32_f16 v[102:105], v[222:225], v[184:187], v[102:105]
	v_mfma_f32_16x16x32_f16 v[98:101], v[230:233], v[184:187], v[98:101]
	v_mfma_f32_16x16x32_f16 v[86:89], v[222:225], v[206:209], v[86:89]
	v_mfma_f32_16x16x32_f16 v[82:85], v[230:233], v[206:209], v[82:85]
	v_mfma_f32_16x16x32_f16 v[70:73], v[222:225], v[214:217], v[70:73]
	v_mfma_f32_16x16x32_f16 v[66:69], v[230:233], v[214:217], v[66:69]
	s_mov_b32 m0, s46
	v_lshl_add_u64 v[140:141], v[188:189], 0, s[94:95]
	s_barrier
	ds_read_b128 v[172:175], v135 offset:49152
	ds_read_b128 v[176:179], v135 offset:50176
	ds_read_b128 v[180:183], v135 offset:51200
	ds_read_b128 v[184:187], v135 offset:52224
	ds_read_b128 v[202:205], v135 offset:53248
	ds_read_b128 v[206:209], v135 offset:54272
	ds_read_b128 v[210:213], v135 offset:55296
	ds_read_b128 v[214:217], v135 offset:56320
	global_load_lds_dwordx4 v[140:141], off
	v_lshl_add_u64 v[140:141], v[234:235], 0, s[94:95]
	s_mov_b32 m0, s47
	s_nop 0
	global_load_lds_dwordx4 v[140:141], off
	s_waitcnt vmcnt(10)
	s_barrier
; #define G8_STAGE(bufoff, gbase) do { _Pragma("unroll") for (int _i = 0; _i < 2; ++_i) \
;     __builtin_amdgcn_global_load_lds((const unsigned*)((const char*)(gbase) + voffA[_i]), (LAS unsigned*)(lds + (bufoff) + ldsw + _i * 8192), 16, 0, 0); } while (0)
; #define G8_MMA(ai, bj, At, Bt_) do { __builtin_amdgcn_s_setprio(1); _Pragma("unroll") for (int m = 0; m < 4; ++m) _Pragma("unroll") for (int n = 0; n < 2; ++n) _Pragma("unroll") for (int k = 0; k < 2; ++k) \
;     acc[ai][bj][m][n] = __builtin_amdgcn_mfma_f32_16x16x32_f16(Bt_[n][k], At[m][k], acc[ai][bj][m][n], 0, 0, 0); __builtin_amdgcn_s_setprio(0); } while (0)
; #define G8_WAIT_V(n) asm volatile("s_waitcnt vmcnt(" #n ")" ::: "memory")
; #define G8_WAIT_L(n) asm volatile("s_waitcnt lgkmcnt(" #n ")" ::: "memory")
; #define G8_BAR __builtin_amdgcn_s_barrier()
; #define G8_SCHED __builtin_amdgcn_sched_barrier(0)
; template <class Epi>
; __device__ __forceinline__ void gemm_phase(LAS unsigned char* lds, const h16* A, const h16* Bt, int K, const Order& S, const Epi& E) {
;     ...
;       G8_BAR; G8_WAIT_L(0); G8_MMA(1, 0, At, B0); G8_BAR; G8_SCHED;
;       G8_STAGE(G8_SB(1, 1), b3 + hstep);
;       G8_WAIT_V(6); G8_BAR; G8_MMA(1, 1, At, B1); G8_BAR;
;     }
;   __device__ __forceinline__ void operator()(const f32x4 (&acc)[2][2][4][2], const g8::Unit& u, int ui, int wr, int wc, int fr, int fq) const {
; #pragma unroll
;     for (int ai = 0; ai < 2; ++ai)
; #pragma unroll
;       for (int m = 0; m < 4; ++m) {
;         const size_t row = (size_t)u.pm * 256 + 128 * ai + 64 * wr + 16 * m + fr;
;         const size_t base = row * DM + 256 * u.pn + 32 * wc + 8 * fq;
;         float ss = 0.f;
; #pragma unroll
;         for (int bj = 0; bj < 2; ++bj) {
;           const size_t idx = base + 128 * bj;
;           const h16x8 xv = *(const h16x8*)(xb + idx);
;           f32x4 x0 = acc[ai][bj][m][0], x1 = acc[ai][bj][m][1];
; #pragma unroll
;           for (int j = 0; j < 4; ++j) { x0[j] += (float)xv[j]; x1[j] += (float)xv[4 + j]; ss += x0[j] * x0[j] + x1[j] * x1[j]; }
;           if (final_out) {
;             __builtin_nontemporal_store(x0, (f32x4*)(xo + idx));
;             __builtin_nontemporal_store(x1, (f32x4*)(xo + idx + 4));
;           } else {
;             *(h16x8*)(xb + idx) = pack8(x0, x1);
	s_waitcnt lgkmcnt(0)
	s_waitcnt lgkmcnt(0)
	v_mfma_f32_16x16x32_f16 v[62:65], v[152:155], v[172:175], v[62:65]
	v_mfma_f32_16x16x32_f16 v[58:61], v[164:167], v[172:175], v[58:61]
	v_mfma_f32_16x16x32_f16 v[46:49], v[152:155], v[180:183], v[46:49]
	v_mfma_f32_16x16x32_f16 v[42:45], v[164:167], v[180:183], v[42:45]
	v_mfma_f32_16x16x32_f16 v[30:33], v[152:155], v[202:205], v[30:33]
	v_mfma_f32_16x16x32_f16 v[26:29], v[164:167], v[202:205], v[26:29]
	v_mfma_f32_16x16x32_f16 v[14:17], v[152:155], v[210:213], v[14:17]
	v_mfma_f32_16x16x32_f16 v[10:13], v[164:167], v[210:213], v[10:13]
	v_mfma_f32_16x16x32_f16 v[62:65], v[160:163], v[176:179], v[62:65]
	v_mfma_f32_16x16x32_f16 v[58:61], v[168:171], v[176:179], v[58:61]
	v_mfma_f32_16x16x32_f16 v[46:49], v[160:163], v[184:187], v[46:49]
	v_mfma_f32_16x16x32_f16 v[42:45], v[168:171], v[184:187], v[42:45]
	v_mfma_f32_16x16x32_f16 v[30:33], v[160:163], v[206:209], v[30:33]
	v_mfma_f32_16x16x32_f16 v[26:29], v[168:171], v[206:209], v[26:29]
	v_mfma_f32_16x16x32_f16 v[14:17], v[160:163], v[214:217], v[14:17]
	v_mfma_f32_16x16x32_f16 v[10:13], v[168:171], v[214:217], v[10:13]
	s_barrier
	s_add_u32 s24, s24, 0x100080
	s_addc_u32 s25, s25, 0
	s_mov_b32 m0, s48
	v_lshl_add_u64 v[140:141], s[24:25], 0, v[0:1]
	global_load_lds_dwordx4 v[140:141], off
	v_lshl_add_u64 v[140:141], s[24:25], 0, v[130:131]
	s_mov_b32 m0, s49
	s_nop 0
	global_load_lds_dwordx4 v[140:141], off
	v_or_b32_e32 v140, 0x10000, v158
	v_add_u32_e32 v141, 0x10400, v158
	ds_read_b128 v[152:155], v140
	ds_read_b128 v[160:163], v141
	v_add_u32_e32 v140, 0x10800, v158
	v_add_u32_e32 v141, 0x10c00, v158
	ds_read_b128 v[164:167], v140
	ds_read_b128 v[168:171], v141
	s_waitcnt vmcnt(6)
	s_barrier
	v_mfma_f32_16x16x32_f16 v[54:57], v[218:221], v[172:175], v[54:57]
	v_mfma_f32_16x16x32_f16 v[50:53], v[226:229], v[172:175], v[50:53]
	v_mfma_f32_16x16x32_f16 v[38:41], v[218:221], v[180:183], v[38:41]
	v_mfma_f32_16x16x32_f16 v[34:37], v[226:229], v[180:183], v[34:37]
	v_mfma_f32_16x16x32_f16 v[22:25], v[218:221], v[202:205], v[22:25]
	v_mfma_f32_16x16x32_f16 v[18:21], v[226:229], v[202:205], v[18:21]
	v_mfma_f32_16x16x32_f16 v[6:9], v[218:221], v[210:213], v[6:9]
	v_mfma_f32_16x16x32_f16 v[2:5], v[226:229], v[210:213], v[2:5]
	v_mfma_f32_16x16x32_f16 v[54:57], v[222:225], v[176:179], v[54:57]
	v_mfma_f32_16x16x32_f16 v[50:53], v[230:233], v[176:179], v[50:53]
	v_mfma_f32_16x16x32_f16 v[38:41], v[222:225], v[184:187], v[38:41]
	v_mfma_f32_16x16x32_f16 v[34:37], v[230:233], v[184:187], v[34:37]
	v_mfma_f32_16x16x32_f16 v[22:25], v[222:225], v[206:209], v[22:25]
	v_mfma_f32_16x16x32_f16 v[18:21], v[230:233], v[206:209], v[18:21]
	v_mfma_f32_16x16x32_f16 v[6:9], v[222:225], v[214:217], v[6:9]
	v_mfma_f32_16x16x32_f16 v[2:5], v[230:233], v[214:217], v[2:5]
	s_add_i32 s53, s53, 2
	s_add_u32 s22, s22, 0x100
	s_addc_u32 s23, s23, 0
	s_add_u32 s51, s51, 0x100
	s_addc_u32 s52, s52, 0
	s_cmp_gt_u32 s53, 61
	s_barrier
	s_cbranch_scc0 .LBB0_2542
	s_waitcnt lgkmcnt(0)
	s_ashr_i32 s9, s8, 31
	s_lshl_b64 s[8:9], s[8:9], 8
	s_lshl_b32 s3, s2, 8
	v_lshl_add_u64 v[140:141], s[8:9], 0, v[132:133]
	s_ashr_i32 s8, s3, 31
	v_mov_b32_e32 v153, s8
	v_or_b32_e32 v152, s3, v134
	v_lshlrev_b64 v[154:155], 10, v[140:141]
	v_lshl_add_u64 v[156:157], v[154:155], 0, v[152:153]
	v_lshl_add_u64 v[154:155], v[156:157], 1, s[10:11]
	global_load_dwordx4 v[166:169], v[154:155], off
	global_load_dwordx4 v[170:173], v[154:155], off offset:256
	s_mov_b32 s9, 0
	s_mov_b32 s8, 0x8000
	v_lshl_add_u64 v[234:235], v[154:155], 0, s[8:9]
	global_load_dwordx4 v[174:177], v[234:235], off
	global_load_dwordx4 v[178:181], v[234:235], off offset:256
	s_mov_b32 s8, 0x10000
	v_lshl_add_u64 v[234:235], v[154:155], 0, s[8:9]
	global_load_dwordx4 v[182:185], v[234:235], off
	global_load_dwordx4 v[186:189], v[234:235], off offset:256
	s_mov_b32 s8, 0x18000
	v_lshl_add_u64 v[234:235], v[154:155], 0, s[8:9]
	global_load_dwordx4 v[202:205], v[234:235], off
	global_load_dwordx4 v[206:209], v[234:235], off offset:256
	s_mov_b32 s8, 0x40000
	v_lshl_add_u64 v[234:235], v[154:155], 0, s[8:9]
	global_load_dwordx4 v[210:213], v[234:235], off
	global_load_dwordx4 v[214:217], v[234:235], off offset:256
	s_mov_b32 s8, 0x48000
	v_lshl_add_u64 v[234:235], v[154:155], 0, s[8:9]
	global_load_dwordx4 v[218:221], v[234:235], off
	global_load_dwordx4 v[222:225], v[234:235], off offset:256
	s_mov_b32 s8, 0x50000
	v_lshl_add_u64 v[234:235], v[154:155], 0, s[8:9]
	global_load_dwordx4 v[226:229], v[234:235], off
	global_load_dwordx4 v[230:233], v[234:235], off offset:256
	s_mov_b64 s[8:9], -1
	s_and_b64 vcc, exec, s[0:1]
	s_waitcnt vmcnt(13)
	v_cvt_f32_f16_e32 v164, v166
	v_cvt_f32_f16_sdwa v165, v166 dst_sel:DWORD dst_unused:UNUSED_PAD src0_sel:WORD_1
	v_cvt_f32_f16_e32 v160, v167
	v_cvt_f32_f16_sdwa v161, v167 dst_sel:DWORD dst_unused:UNUSED_PAD src0_sel:WORD_1
	v_pk_add_f32 v[126:127], v[126:127], v[164:165]
	v_cvt_f32_f16_e32 v164, v168
	v_cvt_f32_f16_sdwa v165, v168 dst_sel:DWORD dst_unused:UNUSED_PAD src0_sel:WORD_1
	v_pk_add_f32 v[128:129], v[128:129], v[160:161]
	v_cvt_f32_f16_e32 v160, v169
	v_cvt_f32_f16_sdwa v161, v169 dst_sel:DWORD dst_unused:UNUSED_PAD src0_sel:WORD_1
	v_pk_add_f32 v[122:123], v[122:123], v[164:165]
	v_pk_add_f32 v[124:125], v[124:125], v[160:161]
	s_cbranch_vccz .LBB0_2545
	v_cvt_pk_f16_f32 v163, v124, v125
	v_cvt_pk_f16_f32 v162, v122, v123
	v_cvt_pk_f16_f32 v161, v128, v129
	v_cvt_pk_f16_f32 v160, v126, v127
	global_store_dwordx4 v[154:155], v[160:163], off
	s_mov_b64 s[8:9], 0
